# scan waves store 16 un-reduced y partials per row (one DPP add less per step), staging waves sum them with a conflict-free row-rotated read; static LDS 16 KiB added for the larger partial buffers
# speedup vs baseline: 1.0049x; 1.0049x over previous
.Lsc_item:
	v_lshlrev_b32_e32 v164, 2, v0
	v_add_u32_e32 v164, 139776, v164
	v_xor_b32_e32 v164, 16, v164
	ds_write_b32 v164, v169
	s_waitcnt lgkmcnt(0)
	s_barrier
	s_cmp_ge_u32 s7, 4
	s_cbranch_scc1 .Lsc_G
	v_lshlrev_b32_e32 v27, 2, v173
	v_and_b32_e32 v27, 60, v27
	v_lshlrev_b32_e32 v7, 2, v0
	v_bfe_u32 v1, v173, 4, 2
	v_or_b32_e32 v37, v7, v1
	v_lshlrev_b32_e32 v37, 6, v37
	v_and_b32_e32 v36, 15, v173
	v_lshl_add_u32 v37, v36, 2, v37
	v_add_u32_e32 v37, 74240, v37
	v_and_b32_e32 v34, 15, v173
	v_lshlrev_b32_e32 v34, 4, v34
	v_or_b32_e32 v35, v7, v1
	v_mul_u32_u24_e32 v35, 144, v35
	v_add_u32_e32 v35, 69632, v35
	v_mov_b32_e32 v8, 0
	v_mov_b32_e32 v9, 0
	v_mov_b32_e32 v10, 0
	v_mov_b32_e32 v11, 0
	v_add_u32_e32 v48, 34816, v34
	v_add_u32_e32 v49, 2304, v35
	v_add_u32_e32 v50, 32768, v37
	v_mov_b32_e32 v51, 0
	v_mov_b32_e32 v52, 139776
	v_mov_b32_e32 v53, v164
	s_mov_b32 s6, 0
	s_mov_b32 s55, 0x100000

.Lsc_S_loop:
	s_waitcnt lgkmcnt(3)
	v_pk_fma_f32 v[10:11], v[80:81], v[30:31], v[16:17] op_sel_hi:[1,0,1] neg_lo:[0,1,0] neg_hi:[0,1,0]
	v_pk_fma_f32 v[8:9], v[82:83], v[30:31], v[18:19] op_sel_hi:[1,0,1] neg_lo:[0,1,0] neg_hi:[0,1,0]
	v_pk_mul_f32 v[24:25], v[10:11], v[84:85] op_sel:[0,0] op_sel_hi:[0,1]
	v_pk_fma_f32 v[24:25], v[10:11], v[86:87], v[24:25] op_sel:[1,0,0] op_sel_hi:[1,1,1]
	v_pk_fma_f32 v[24:25], v[8:9], v[88:89], v[24:25] op_sel:[0,0,0] op_sel_hi:[0,1,1]
	v_pk_fma_f32 v[24:25], v[8:9], v[90:91], v[24:25] op_sel:[1,0,0] op_sel_hi:[1,1,1]
	v_pk_fma_f32 v[16:17], v[92:93], v[156:157], v[10:11] op_sel:[0,1,0] op_sel_hi:[1,1,1]
	v_pk_fma_f32 v[18:19], v[94:95], v[156:157], v[8:9] op_sel:[0,1,0] op_sel_hi:[1,1,1]
	v_add_f32_dpp v15, v24, v24 row_ror:8 row_mask:0xf bank_mask:0xf bound_ctrl:1
	ds_read_b128 v[124:127], v34 offset:3072
	s_nop 0
	v_add_f32_dpp v15, v15, v15 row_ror:4 row_mask:0xf bank_mask:0xf bound_ctrl:1
	ds_read_b128 v[128:131], v34 offset:3328
	ds_read_b128 v[132:135], v34 offset:3584
	v_add_f32_dpp v15, v15, v15 row_ror:2 row_mask:0xf bank_mask:0xf bound_ctrl:1
	ds_read_b128 v[136:139], v34 offset:3840
	ds_read_b128 v[160:163], v35 offset:16
	v_add_f32_dpp v30, v15, v15 row_ror:1 row_mask:0xf bank_mask:0xf bound_ctrl:1
	v_pk_fma_f32 v[10:11], v[96:97], v[30:31], v[16:17] op_sel_hi:[1,0,1] neg_lo:[0,1,0] neg_hi:[0,1,0]
	v_pk_fma_f32 v[8:9], v[98:99], v[30:31], v[18:19] op_sel_hi:[1,0,1] neg_lo:[0,1,0] neg_hi:[0,1,0]
	v_pk_mul_f32 v[26:27], v[10:11], v[100:101] op_sel:[0,0] op_sel_hi:[0,1]
	v_pk_fma_f32 v[26:27], v[10:11], v[102:103], v[26:27] op_sel:[1,0,0] op_sel_hi:[1,1,1]
	v_pk_fma_f32 v[26:27], v[8:9], v[104:105], v[26:27] op_sel:[0,0,0] op_sel_hi:[0,1,1]
	v_pk_fma_f32 v[26:27], v[8:9], v[106:107], v[26:27] op_sel:[1,0,0] op_sel_hi:[1,1,1]
	v_pk_fma_f32 v[16:17], v[108:109], v[158:159], v[10:11] op_sel_hi:[1,0,1]
	v_pk_fma_f32 v[18:19], v[110:111], v[158:159], v[8:9] op_sel_hi:[1,0,1]
	v_add_f32_dpp v15, v26, v26 row_ror:8 row_mask:0xf bank_mask:0xf bound_ctrl:1
	ds_read_b128 v[76:79], v34 offset:4096
	s_nop 0
	v_add_f32_dpp v15, v15, v15 row_ror:4 row_mask:0xf bank_mask:0xf bound_ctrl:1
	ds_read_b128 v[80:83], v34 offset:4352
	ds_read_b128 v[84:87], v34 offset:4608
	v_add_f32_dpp v15, v15, v15 row_ror:2 row_mask:0xf bank_mask:0xf bound_ctrl:1
	ds_read_b128 v[88:91], v34 offset:4864
	ds_write2st64_b32 v37, v25, v27 offset0:0 offset1:4
	v_add_f32_dpp v30, v15, v15 row_ror:1 row_mask:0xf bank_mask:0xf bound_ctrl:1
	s_waitcnt lgkmcnt(4)
	v_pk_fma_f32 v[10:11], v[112:113], v[30:31], v[16:17] op_sel_hi:[1,0,1] neg_lo:[0,1,0] neg_hi:[0,1,0]
	v_pk_fma_f32 v[8:9], v[114:115], v[30:31], v[18:19] op_sel_hi:[1,0,1] neg_lo:[0,1,0] neg_hi:[0,1,0]
	v_pk_mul_f32 v[24:25], v[10:11], v[116:117] op_sel:[0,0] op_sel_hi:[0,1]
	v_pk_fma_f32 v[24:25], v[10:11], v[118:119], v[24:25] op_sel:[1,0,0] op_sel_hi:[1,1,1]
	v_pk_fma_f32 v[24:25], v[8:9], v[120:121], v[24:25] op_sel:[0,0,0] op_sel_hi:[0,1,1]
	v_pk_fma_f32 v[24:25], v[8:9], v[122:123], v[24:25] op_sel:[1,0,0] op_sel_hi:[1,1,1]
	v_pk_fma_f32 v[16:17], v[124:125], v[158:159], v[10:11] op_sel:[0,1,0] op_sel_hi:[1,1,1]
	v_pk_fma_f32 v[18:19], v[126:127], v[158:159], v[8:9] op_sel:[0,1,0] op_sel_hi:[1,1,1]
	v_add_f32_dpp v15, v24, v24 row_ror:8 row_mask:0xf bank_mask:0xf bound_ctrl:1
	ds_read_b128 v[92:95], v34 offset:5120
	s_nop 0
	v_add_f32_dpp v15, v15, v15 row_ror:4 row_mask:0xf bank_mask:0xf bound_ctrl:1
	ds_read_b128 v[96:99], v34 offset:5376
	ds_read_b128 v[100:103], v34 offset:5632
	v_add_f32_dpp v15, v15, v15 row_ror:2 row_mask:0xf bank_mask:0xf bound_ctrl:1
	ds_read_b128 v[104:107], v34 offset:5888
	s_nop 0
	v_add_f32_dpp v30, v15, v15 row_ror:1 row_mask:0xf bank_mask:0xf bound_ctrl:1
	v_pk_fma_f32 v[10:11], v[128:129], v[30:31], v[16:17] op_sel_hi:[1,0,1] neg_lo:[0,1,0] neg_hi:[0,1,0]
	v_pk_fma_f32 v[8:9], v[130:131], v[30:31], v[18:19] op_sel_hi:[1,0,1] neg_lo:[0,1,0] neg_hi:[0,1,0]
	v_pk_mul_f32 v[26:27], v[10:11], v[132:133] op_sel:[0,0] op_sel_hi:[0,1]
	v_pk_fma_f32 v[26:27], v[10:11], v[134:135], v[26:27] op_sel:[1,0,0] op_sel_hi:[1,1,1]
	v_pk_fma_f32 v[26:27], v[8:9], v[136:137], v[26:27] op_sel:[0,0,0] op_sel_hi:[0,1,1]
	v_pk_fma_f32 v[26:27], v[8:9], v[138:139], v[26:27] op_sel:[1,0,0] op_sel_hi:[1,1,1]
	v_pk_fma_f32 v[16:17], v[76:77], v[160:161], v[10:11] op_sel_hi:[1,0,1]
	v_pk_fma_f32 v[18:19], v[78:79], v[160:161], v[8:9] op_sel_hi:[1,0,1]
	v_add_f32_dpp v15, v26, v26 row_ror:8 row_mask:0xf bank_mask:0xf bound_ctrl:1
	ds_read_b128 v[108:111], v34 offset:6144
	s_nop 0
	v_add_f32_dpp v15, v15, v15 row_ror:4 row_mask:0xf bank_mask:0xf bound_ctrl:1
	ds_read_b128 v[112:115], v34 offset:6400
	ds_read_b128 v[116:119], v34 offset:6656
	v_add_f32_dpp v15, v15, v15 row_ror:2 row_mask:0xf bank_mask:0xf bound_ctrl:1
	ds_read_b128 v[120:123], v34 offset:6912
	ds_read_b128 v[140:143], v34 offset:33792
	ds_write2st64_b32 v37, v25, v27 offset0:8 offset1:12
	v_add_f32_dpp v30, v15, v15 row_ror:1 row_mask:0xf bank_mask:0xf bound_ctrl:1
	s_waitcnt lgkmcnt(5)
	v_pk_fma_f32 v[10:11], v[80:81], v[30:31], v[16:17] op_sel_hi:[1,0,1] neg_lo:[0,1,0] neg_hi:[0,1,0]
	v_pk_fma_f32 v[8:9], v[82:83], v[30:31], v[18:19] op_sel_hi:[1,0,1] neg_lo:[0,1,0] neg_hi:[0,1,0]
	v_pk_mul_f32 v[24:25], v[10:11], v[84:85] op_sel:[0,0] op_sel_hi:[0,1]
	v_pk_fma_f32 v[24:25], v[10:11], v[86:87], v[24:25] op_sel:[1,0,0] op_sel_hi:[1,1,1]
	v_pk_fma_f32 v[24:25], v[8:9], v[88:89], v[24:25] op_sel:[0,0,0] op_sel_hi:[0,1,1]
	v_pk_fma_f32 v[24:25], v[8:9], v[90:91], v[24:25] op_sel:[1,0,0] op_sel_hi:[1,1,1]
	v_pk_fma_f32 v[16:17], v[92:93], v[160:161], v[10:11] op_sel:[0,1,0] op_sel_hi:[1,1,1]
	v_pk_fma_f32 v[18:19], v[94:95], v[160:161], v[8:9] op_sel:[0,1,0] op_sel_hi:[1,1,1]
	v_add_f32_dpp v15, v24, v24 row_ror:8 row_mask:0xf bank_mask:0xf bound_ctrl:1
	ds_read_b128 v[124:127], v34 offset:7168
	s_nop 0
	v_add_f32_dpp v15, v15, v15 row_ror:4 row_mask:0xf bank_mask:0xf bound_ctrl:1
	ds_read_b128 v[128:131], v34 offset:7424
	ds_read_b128 v[132:135], v34 offset:7680
	v_add_f32_dpp v15, v15, v15 row_ror:2 row_mask:0xf bank_mask:0xf bound_ctrl:1
	ds_read_b128 v[136:139], v34 offset:7936
	ds_read_b128 v[156:159], v35 offset:32
	v_add_f32_dpp v30, v15, v15 row_ror:1 row_mask:0xf bank_mask:0xf bound_ctrl:1
	v_pk_fma_f32 v[10:11], v[96:97], v[30:31], v[16:17] op_sel_hi:[1,0,1] neg_lo:[0,1,0] neg_hi:[0,1,0]
	v_pk_fma_f32 v[8:9], v[98:99], v[30:31], v[18:19] op_sel_hi:[1,0,1] neg_lo:[0,1,0] neg_hi:[0,1,0]
	v_pk_mul_f32 v[26:27], v[10:11], v[100:101] op_sel:[0,0] op_sel_hi:[0,1]
	v_pk_fma_f32 v[26:27], v[10:11], v[102:103], v[26:27] op_sel:[1,0,0] op_sel_hi:[1,1,1]
	v_pk_fma_f32 v[26:27], v[8:9], v[104:105], v[26:27] op_sel:[0,0,0] op_sel_hi:[0,1,1]
	v_pk_fma_f32 v[26:27], v[8:9], v[106:107], v[26:27] op_sel:[1,0,0] op_sel_hi:[1,1,1]
	v_pk_fma_f32 v[16:17], v[108:109], v[162:163], v[10:11] op_sel_hi:[1,0,1]
	v_pk_fma_f32 v[18:19], v[110:111], v[162:163], v[8:9] op_sel_hi:[1,0,1]
	v_add_f32_dpp v15, v26, v26 row_ror:8 row_mask:0xf bank_mask:0xf bound_ctrl:1
	ds_read_b128 v[76:79], v34 offset:8192
	s_nop 0
	v_add_f32_dpp v15, v15, v15 row_ror:4 row_mask:0xf bank_mask:0xf bound_ctrl:1
	ds_read_b128 v[80:83], v34 offset:8448
	ds_read_b128 v[84:87], v34 offset:8704
	v_add_f32_dpp v15, v15, v15 row_ror:2 row_mask:0xf bank_mask:0xf bound_ctrl:1
	ds_read_b128 v[88:91], v34 offset:8960
	ds_read_b128 v[144:147], v34 offset:33024
	ds_write2st64_b32 v37, v25, v27 offset0:16 offset1:20
	v_add_f32_dpp v30, v15, v15 row_ror:1 row_mask:0xf bank_mask:0xf bound_ctrl:1
	s_waitcnt lgkmcnt(5)
	v_pk_fma_f32 v[10:11], v[112:113], v[30:31], v[16:17] op_sel_hi:[1,0,1] neg_lo:[0,1,0] neg_hi:[0,1,0]
	v_pk_fma_f32 v[8:9], v[114:115], v[30:31], v[18:19] op_sel_hi:[1,0,1] neg_lo:[0,1,0] neg_hi:[0,1,0]
	v_pk_mul_f32 v[24:25], v[10:11], v[116:117] op_sel:[0,0] op_sel_hi:[0,1]
	v_pk_fma_f32 v[24:25], v[10:11], v[118:119], v[24:25] op_sel:[1,0,0] op_sel_hi:[1,1,1]
	v_pk_fma_f32 v[24:25], v[8:9], v[120:121], v[24:25] op_sel:[0,0,0] op_sel_hi:[0,1,1]
	v_pk_fma_f32 v[24:25], v[8:9], v[122:123], v[24:25] op_sel:[1,0,0] op_sel_hi:[1,1,1]
	v_pk_fma_f32 v[16:17], v[124:125], v[162:163], v[10:11] op_sel:[0,1,0] op_sel_hi:[1,1,1]
	v_pk_fma_f32 v[18:19], v[126:127], v[162:163], v[8:9] op_sel:[0,1,0] op_sel_hi:[1,1,1]
	v_add_f32_dpp v15, v24, v24 row_ror:8 row_mask:0xf bank_mask:0xf bound_ctrl:1
	ds_read_b128 v[92:95], v34 offset:9216
	s_nop 0
	v_add_f32_dpp v15, v15, v15 row_ror:4 row_mask:0xf bank_mask:0xf bound_ctrl:1
	ds_read_b128 v[96:99], v34 offset:9472
	ds_read_b128 v[100:103], v34 offset:9728
	v_add_f32_dpp v15, v15, v15 row_ror:2 row_mask:0xf bank_mask:0xf bound_ctrl:1
	ds_read_b128 v[104:107], v34 offset:9984
	s_nop 0
	v_add_f32_dpp v30, v15, v15 row_ror:1 row_mask:0xf bank_mask:0xf bound_ctrl:1
	v_pk_fma_f32 v[10:11], v[128:129], v[30:31], v[16:17] op_sel_hi:[1,0,1] neg_lo:[0,1,0] neg_hi:[0,1,0]
	v_pk_fma_f32 v[8:9], v[130:131], v[30:31], v[18:19] op_sel_hi:[1,0,1] neg_lo:[0,1,0] neg_hi:[0,1,0]
	v_pk_mul_f32 v[26:27], v[10:11], v[132:133] op_sel:[0,0] op_sel_hi:[0,1]
	v_pk_fma_f32 v[26:27], v[10:11], v[134:135], v[26:27] op_sel:[1,0,0] op_sel_hi:[1,1,1]
	v_pk_fma_f32 v[26:27], v[8:9], v[136:137], v[26:27] op_sel:[0,0,0] op_sel_hi:[0,1,1]
	v_pk_fma_f32 v[26:27], v[8:9], v[138:139], v[26:27] op_sel:[1,0,0] op_sel_hi:[1,1,1]
	ds_write2st64_b32 v37, v25, v27 offset0:24 offset1:28
	v_pk_mul_f32 v[10:11], v[10:11], v[140:141]
	v_pk_mul_f32 v[8:9], v[8:9], v[142:143]
	s_waitcnt lgkmcnt(6)
	v_pk_mul_f32 v[24:25], v[10:11], v[144:145]
	v_pk_fma_f32 v[24:25], v[8:9], v[146:147], v[24:25]
	v_add_f32_e32 v24, v24, v25
	v_pk_fma_f32 v[16:17], v[76:77], v[156:157], v[10:11] op_sel_hi:[1,0,1]
	v_pk_fma_f32 v[18:19], v[78:79], v[156:157], v[8:9] op_sel_hi:[1,0,1]
	v_add_f32_dpp v15, v24, v24 row_ror:8 row_mask:0xf bank_mask:0xf bound_ctrl:1
	ds_read_b128 v[108:111], v34 offset:10240
	ds_read_b128 v[112:115], v34 offset:10496
	v_add_f32_dpp v15, v15, v15 row_ror:4 row_mask:0xf bank_mask:0xf bound_ctrl:1
	ds_read_b128 v[116:119], v34 offset:10752
	ds_read_b128 v[120:123], v34 offset:11008
	v_add_f32_dpp v15, v15, v15 row_ror:2 row_mask:0xf bank_mask:0xf bound_ctrl:1
	s_nop 1
	v_add_f32_dpp v30, v15, v15 row_ror:1 row_mask:0xf bank_mask:0xf bound_ctrl:1
	s_waitcnt lgkmcnt(3)
	v_pk_fma_f32 v[10:11], v[80:81], v[30:31], v[16:17] op_sel_hi:[1,0,1] neg_lo:[0,1,0] neg_hi:[0,1,0]
	v_pk_fma_f32 v[8:9], v[82:83], v[30:31], v[18:19] op_sel_hi:[1,0,1] neg_lo:[0,1,0] neg_hi:[0,1,0]
	v_pk_mul_f32 v[24:25], v[10:11], v[84:85] op_sel:[0,0] op_sel_hi:[0,1]
	v_pk_fma_f32 v[24:25], v[10:11], v[86:87], v[24:25] op_sel:[1,0,0] op_sel_hi:[1,1,1]
	v_pk_fma_f32 v[24:25], v[8:9], v[88:89], v[24:25] op_sel:[0,0,0] op_sel_hi:[0,1,1]
	v_pk_fma_f32 v[24:25], v[8:9], v[90:91], v[24:25] op_sel:[1,0,0] op_sel_hi:[1,1,1]
	v_pk_fma_f32 v[16:17], v[92:93], v[156:157], v[10:11] op_sel:[0,1,0] op_sel_hi:[1,1,1]
	v_pk_fma_f32 v[18:19], v[94:95], v[156:157], v[8:9] op_sel:[0,1,0] op_sel_hi:[1,1,1]
	v_add_f32_dpp v15, v24, v24 row_ror:8 row_mask:0xf bank_mask:0xf bound_ctrl:1
	ds_read_b128 v[124:127], v34 offset:11264
	s_nop 0
	v_add_f32_dpp v15, v15, v15 row_ror:4 row_mask:0xf bank_mask:0xf bound_ctrl:1
	ds_read_b128 v[128:131], v34 offset:11520
	ds_read_b128 v[132:135], v34 offset:11776
	v_add_f32_dpp v15, v15, v15 row_ror:2 row_mask:0xf bank_mask:0xf bound_ctrl:1
	ds_read_b128 v[136:139], v34 offset:12032
	ds_read_b128 v[160:163], v35 offset:48
	v_add_f32_dpp v30, v15, v15 row_ror:1 row_mask:0xf bank_mask:0xf bound_ctrl:1
	v_pk_fma_f32 v[10:11], v[96:97], v[30:31], v[16:17] op_sel_hi:[1,0,1] neg_lo:[0,1,0] neg_hi:[0,1,0]
	v_pk_fma_f32 v[8:9], v[98:99], v[30:31], v[18:19] op_sel_hi:[1,0,1] neg_lo:[0,1,0] neg_hi:[0,1,0]
	v_pk_mul_f32 v[26:27], v[10:11], v[100:101] op_sel:[0,0] op_sel_hi:[0,1]
	v_pk_fma_f32 v[26:27], v[10:11], v[102:103], v[26:27] op_sel:[1,0,0] op_sel_hi:[1,1,1]
	v_pk_fma_f32 v[26:27], v[8:9], v[104:105], v[26:27] op_sel:[0,0,0] op_sel_hi:[0,1,1]
	v_pk_fma_f32 v[26:27], v[8:9], v[106:107], v[26:27] op_sel:[1,0,0] op_sel_hi:[1,1,1]
	v_pk_fma_f32 v[16:17], v[108:109], v[158:159], v[10:11] op_sel_hi:[1,0,1]
	v_pk_fma_f32 v[18:19], v[110:111], v[158:159], v[8:9] op_sel_hi:[1,0,1]
	v_add_f32_dpp v15, v26, v26 row_ror:8 row_mask:0xf bank_mask:0xf bound_ctrl:1
	ds_read_b128 v[76:79], v34 offset:12288
	s_nop 0
	v_add_f32_dpp v15, v15, v15 row_ror:4 row_mask:0xf bank_mask:0xf bound_ctrl:1
	ds_read_b128 v[80:83], v34 offset:12544
	ds_read_b128 v[84:87], v34 offset:12800
	v_add_f32_dpp v15, v15, v15 row_ror:2 row_mask:0xf bank_mask:0xf bound_ctrl:1
	ds_read_b128 v[88:91], v34 offset:13056
	ds_write2st64_b32 v37, v25, v27 offset0:32 offset1:36
	v_add_f32_dpp v30, v15, v15 row_ror:1 row_mask:0xf bank_mask:0xf bound_ctrl:1
	s_waitcnt lgkmcnt(4)
	v_pk_fma_f32 v[10:11], v[112:113], v[30:31], v[16:17] op_sel_hi:[1,0,1] neg_lo:[0,1,0] neg_hi:[0,1,0]
	v_pk_fma_f32 v[8:9], v[114:115], v[30:31], v[18:19] op_sel_hi:[1,0,1] neg_lo:[0,1,0] neg_hi:[0,1,0]
	v_pk_mul_f32 v[24:25], v[10:11], v[116:117] op_sel:[0,0] op_sel_hi:[0,1]
	v_pk_fma_f32 v[24:25], v[10:11], v[118:119], v[24:25] op_sel:[1,0,0] op_sel_hi:[1,1,1]
	v_pk_fma_f32 v[24:25], v[8:9], v[120:121], v[24:25] op_sel:[0,0,0] op_sel_hi:[0,1,1]
	v_pk_fma_f32 v[24:25], v[8:9], v[122:123], v[24:25] op_sel:[1,0,0] op_sel_hi:[1,1,1]
	v_pk_fma_f32 v[16:17], v[124:125], v[158:159], v[10:11] op_sel:[0,1,0] op_sel_hi:[1,1,1]
	v_pk_fma_f32 v[18:19], v[126:127], v[158:159], v[8:9] op_sel:[0,1,0] op_sel_hi:[1,1,1]
	v_add_f32_dpp v15, v24, v24 row_ror:8 row_mask:0xf bank_mask:0xf bound_ctrl:1
	ds_read_b128 v[92:95], v34 offset:13312
	s_nop 0
	v_add_f32_dpp v15, v15, v15 row_ror:4 row_mask:0xf bank_mask:0xf bound_ctrl:1
	ds_read_b128 v[96:99], v34 offset:13568
	ds_read_b128 v[100:103], v34 offset:13824
	v_add_f32_dpp v15, v15, v15 row_ror:2 row_mask:0xf bank_mask:0xf bound_ctrl:1
	ds_read_b128 v[104:107], v34 offset:14080
	s_nop 0
	v_add_f32_dpp v30, v15, v15 row_ror:1 row_mask:0xf bank_mask:0xf bound_ctrl:1
	v_pk_fma_f32 v[10:11], v[128:129], v[30:31], v[16:17] op_sel_hi:[1,0,1] neg_lo:[0,1,0] neg_hi:[0,1,0]
	v_pk_fma_f32 v[8:9], v[130:131], v[30:31], v[18:19] op_sel_hi:[1,0,1] neg_lo:[0,1,0] neg_hi:[0,1,0]
	v_pk_mul_f32 v[26:27], v[10:11], v[132:133] op_sel:[0,0] op_sel_hi:[0,1]
	v_pk_fma_f32 v[26:27], v[10:11], v[134:135], v[26:27] op_sel:[1,0,0] op_sel_hi:[1,1,1]
	v_pk_fma_f32 v[26:27], v[8:9], v[136:137], v[26:27] op_sel:[0,0,0] op_sel_hi:[0,1,1]
	v_pk_fma_f32 v[26:27], v[8:9], v[138:139], v[26:27] op_sel:[1,0,0] op_sel_hi:[1,1,1]
	v_pk_fma_f32 v[16:17], v[76:77], v[160:161], v[10:11] op_sel_hi:[1,0,1]
	v_pk_fma_f32 v[18:19], v[78:79], v[160:161], v[8:9] op_sel_hi:[1,0,1]
	v_add_f32_dpp v15, v26, v26 row_ror:8 row_mask:0xf bank_mask:0xf bound_ctrl:1
	ds_read_b128 v[108:111], v34 offset:14336
	s_nop 0
	v_add_f32_dpp v15, v15, v15 row_ror:4 row_mask:0xf bank_mask:0xf bound_ctrl:1
	ds_read_b128 v[112:115], v34 offset:14592
	ds_read_b128 v[116:119], v34 offset:14848
	v_add_f32_dpp v15, v15, v15 row_ror:2 row_mask:0xf bank_mask:0xf bound_ctrl:1
	ds_read_b128 v[120:123], v34 offset:15104
	ds_read_b128 v[140:143], v34 offset:34048
	ds_write2st64_b32 v37, v25, v27 offset0:40 offset1:44
	v_add_f32_dpp v30, v15, v15 row_ror:1 row_mask:0xf bank_mask:0xf bound_ctrl:1
	s_waitcnt lgkmcnt(5)
	v_pk_fma_f32 v[10:11], v[80:81], v[30:31], v[16:17] op_sel_hi:[1,0,1] neg_lo:[0,1,0] neg_hi:[0,1,0]
	v_pk_fma_f32 v[8:9], v[82:83], v[30:31], v[18:19] op_sel_hi:[1,0,1] neg_lo:[0,1,0] neg_hi:[0,1,0]
	v_pk_mul_f32 v[24:25], v[10:11], v[84:85] op_sel:[0,0] op_sel_hi:[0,1]
	v_pk_fma_f32 v[24:25], v[10:11], v[86:87], v[24:25] op_sel:[1,0,0] op_sel_hi:[1,1,1]
	v_pk_fma_f32 v[24:25], v[8:9], v[88:89], v[24:25] op_sel:[0,0,0] op_sel_hi:[0,1,1]
	v_pk_fma_f32 v[24:25], v[8:9], v[90:91], v[24:25] op_sel:[1,0,0] op_sel_hi:[1,1,1]
	v_pk_fma_f32 v[16:17], v[92:93], v[160:161], v[10:11] op_sel:[0,1,0] op_sel_hi:[1,1,1]
	v_pk_fma_f32 v[18:19], v[94:95], v[160:161], v[8:9] op_sel:[0,1,0] op_sel_hi:[1,1,1]
	v_add_f32_dpp v15, v24, v24 row_ror:8 row_mask:0xf bank_mask:0xf bound_ctrl:1
	ds_read_b128 v[124:127], v34 offset:15360
	s_nop 0
	v_add_f32_dpp v15, v15, v15 row_ror:4 row_mask:0xf bank_mask:0xf bound_ctrl:1
	ds_read_b128 v[128:131], v34 offset:15616
	ds_read_b128 v[132:135], v34 offset:15872
	v_add_f32_dpp v15, v15, v15 row_ror:2 row_mask:0xf bank_mask:0xf bound_ctrl:1
	ds_read_b128 v[136:139], v34 offset:16128
	ds_read_b128 v[156:159], v35 offset:64
	v_add_f32_dpp v30, v15, v15 row_ror:1 row_mask:0xf bank_mask:0xf bound_ctrl:1
	v_pk_fma_f32 v[10:11], v[96:97], v[30:31], v[16:17] op_sel_hi:[1,0,1] neg_lo:[0,1,0] neg_hi:[0,1,0]
	v_pk_fma_f32 v[8:9], v[98:99], v[30:31], v[18:19] op_sel_hi:[1,0,1] neg_lo:[0,1,0] neg_hi:[0,1,0]
	v_pk_mul_f32 v[26:27], v[10:11], v[100:101] op_sel:[0,0] op_sel_hi:[0,1]
	v_pk_fma_f32 v[26:27], v[10:11], v[102:103], v[26:27] op_sel:[1,0,0] op_sel_hi:[1,1,1]
	v_pk_fma_f32 v[26:27], v[8:9], v[104:105], v[26:27] op_sel:[0,0,0] op_sel_hi:[0,1,1]
	v_pk_fma_f32 v[26:27], v[8:9], v[106:107], v[26:27] op_sel:[1,0,0] op_sel_hi:[1,1,1]
	v_pk_fma_f32 v[16:17], v[108:109], v[162:163], v[10:11] op_sel_hi:[1,0,1]
	v_pk_fma_f32 v[18:19], v[110:111], v[162:163], v[8:9] op_sel_hi:[1,0,1]
	v_add_f32_dpp v15, v26, v26 row_ror:8 row_mask:0xf bank_mask:0xf bound_ctrl:1
	ds_read_b128 v[76:79], v34 offset:16384
	s_nop 0
	v_add_f32_dpp v15, v15, v15 row_ror:4 row_mask:0xf bank_mask:0xf bound_ctrl:1
	ds_read_b128 v[80:83], v34 offset:16640
	ds_read_b128 v[84:87], v34 offset:16896
	v_add_f32_dpp v15, v15, v15 row_ror:2 row_mask:0xf bank_mask:0xf bound_ctrl:1
	ds_read_b128 v[88:91], v34 offset:17152
	ds_read_b128 v[144:147], v34 offset:33280
	ds_write2st64_b32 v37, v25, v27 offset0:48 offset1:52
	v_add_f32_dpp v30, v15, v15 row_ror:1 row_mask:0xf bank_mask:0xf bound_ctrl:1
	s_waitcnt lgkmcnt(5)
	v_pk_fma_f32 v[10:11], v[112:113], v[30:31], v[16:17] op_sel_hi:[1,0,1] neg_lo:[0,1,0] neg_hi:[0,1,0]
	v_pk_fma_f32 v[8:9], v[114:115], v[30:31], v[18:19] op_sel_hi:[1,0,1] neg_lo:[0,1,0] neg_hi:[0,1,0]
	v_pk_mul_f32 v[24:25], v[10:11], v[116:117] op_sel:[0,0] op_sel_hi:[0,1]
	v_pk_fma_f32 v[24:25], v[10:11], v[118:119], v[24:25] op_sel:[1,0,0] op_sel_hi:[1,1,1]
	v_pk_fma_f32 v[24:25], v[8:9], v[120:121], v[24:25] op_sel:[0,0,0] op_sel_hi:[0,1,1]
	v_pk_fma_f32 v[24:25], v[8:9], v[122:123], v[24:25] op_sel:[1,0,0] op_sel_hi:[1,1,1]
	v_pk_fma_f32 v[16:17], v[124:125], v[162:163], v[10:11] op_sel:[0,1,0] op_sel_hi:[1,1,1]
	v_pk_fma_f32 v[18:19], v[126:127], v[162:163], v[8:9] op_sel:[0,1,0] op_sel_hi:[1,1,1]
	v_add_f32_dpp v15, v24, v24 row_ror:8 row_mask:0xf bank_mask:0xf bound_ctrl:1
	ds_read_b128 v[92:95], v34 offset:17408
	s_nop 0
	v_add_f32_dpp v15, v15, v15 row_ror:4 row_mask:0xf bank_mask:0xf bound_ctrl:1
	ds_read_b128 v[96:99], v34 offset:17664
	ds_read_b128 v[100:103], v34 offset:17920
	v_add_f32_dpp v15, v15, v15 row_ror:2 row_mask:0xf bank_mask:0xf bound_ctrl:1
	ds_read_b128 v[104:107], v34 offset:18176
	s_nop 0
	v_add_f32_dpp v30, v15, v15 row_ror:1 row_mask:0xf bank_mask:0xf bound_ctrl:1
	v_pk_fma_f32 v[10:11], v[128:129], v[30:31], v[16:17] op_sel_hi:[1,0,1] neg_lo:[0,1,0] neg_hi:[0,1,0]
	v_pk_fma_f32 v[8:9], v[130:131], v[30:31], v[18:19] op_sel_hi:[1,0,1] neg_lo:[0,1,0] neg_hi:[0,1,0]
	v_pk_mul_f32 v[26:27], v[10:11], v[132:133] op_sel:[0,0] op_sel_hi:[0,1]
	v_pk_fma_f32 v[26:27], v[10:11], v[134:135], v[26:27] op_sel:[1,0,0] op_sel_hi:[1,1,1]
	v_pk_fma_f32 v[26:27], v[8:9], v[136:137], v[26:27] op_sel:[0,0,0] op_sel_hi:[0,1,1]
	v_pk_fma_f32 v[26:27], v[8:9], v[138:139], v[26:27] op_sel:[1,0,0] op_sel_hi:[1,1,1]
	ds_write2st64_b32 v37, v25, v27 offset0:56 offset1:60
	v_pk_mul_f32 v[10:11], v[10:11], v[140:141]
	v_pk_mul_f32 v[8:9], v[8:9], v[142:143]
	s_waitcnt lgkmcnt(6)
	v_pk_mul_f32 v[24:25], v[10:11], v[144:145]
	v_pk_fma_f32 v[24:25], v[8:9], v[146:147], v[24:25]
	v_add_f32_e32 v24, v24, v25
	v_pk_fma_f32 v[16:17], v[76:77], v[156:157], v[10:11] op_sel_hi:[1,0,1]
	v_pk_fma_f32 v[18:19], v[78:79], v[156:157], v[8:9] op_sel_hi:[1,0,1]
	v_add_f32_dpp v15, v24, v24 row_ror:8 row_mask:0xf bank_mask:0xf bound_ctrl:1
	ds_read_b128 v[108:111], v34 offset:18432
	ds_read_b128 v[112:115], v34 offset:18688
	v_add_f32_dpp v15, v15, v15 row_ror:4 row_mask:0xf bank_mask:0xf bound_ctrl:1
	ds_read_b128 v[116:119], v34 offset:18944
	ds_read_b128 v[120:123], v34 offset:19200
	v_add_f32_dpp v15, v15, v15 row_ror:2 row_mask:0xf bank_mask:0xf bound_ctrl:1
	s_nop 1
	v_add_f32_dpp v30, v15, v15 row_ror:1 row_mask:0xf bank_mask:0xf bound_ctrl:1
	s_waitcnt lgkmcnt(3)
	v_pk_fma_f32 v[10:11], v[80:81], v[30:31], v[16:17] op_sel_hi:[1,0,1] neg_lo:[0,1,0] neg_hi:[0,1,0]
	v_pk_fma_f32 v[8:9], v[82:83], v[30:31], v[18:19] op_sel_hi:[1,0,1] neg_lo:[0,1,0] neg_hi:[0,1,0]
	v_pk_mul_f32 v[24:25], v[10:11], v[84:85] op_sel:[0,0] op_sel_hi:[0,1]
	v_pk_fma_f32 v[24:25], v[10:11], v[86:87], v[24:25] op_sel:[1,0,0] op_sel_hi:[1,1,1]
	v_pk_fma_f32 v[24:25], v[8:9], v[88:89], v[24:25] op_sel:[0,0,0] op_sel_hi:[0,1,1]
	v_pk_fma_f32 v[24:25], v[8:9], v[90:91], v[24:25] op_sel:[1,0,0] op_sel_hi:[1,1,1]
	v_pk_fma_f32 v[16:17], v[92:93], v[156:157], v[10:11] op_sel:[0,1,0] op_sel_hi:[1,1,1]
	v_pk_fma_f32 v[18:19], v[94:95], v[156:157], v[8:9] op_sel:[0,1,0] op_sel_hi:[1,1,1]
	v_add_f32_dpp v15, v24, v24 row_ror:8 row_mask:0xf bank_mask:0xf bound_ctrl:1
	ds_read_b128 v[124:127], v34 offset:19456
	s_nop 0
	v_add_f32_dpp v15, v15, v15 row_ror:4 row_mask:0xf bank_mask:0xf bound_ctrl:1
	ds_read_b128 v[128:131], v34 offset:19712
	ds_read_b128 v[132:135], v34 offset:19968
	v_add_f32_dpp v15, v15, v15 row_ror:2 row_mask:0xf bank_mask:0xf bound_ctrl:1
	ds_read_b128 v[136:139], v34 offset:20224
	ds_read_b128 v[160:163], v35 offset:80
	v_add_f32_dpp v30, v15, v15 row_ror:1 row_mask:0xf bank_mask:0xf bound_ctrl:1
	v_pk_fma_f32 v[10:11], v[96:97], v[30:31], v[16:17] op_sel_hi:[1,0,1] neg_lo:[0,1,0] neg_hi:[0,1,0]
	v_pk_fma_f32 v[8:9], v[98:99], v[30:31], v[18:19] op_sel_hi:[1,0,1] neg_lo:[0,1,0] neg_hi:[0,1,0]
	v_pk_mul_f32 v[26:27], v[10:11], v[100:101] op_sel:[0,0] op_sel_hi:[0,1]
	v_pk_fma_f32 v[26:27], v[10:11], v[102:103], v[26:27] op_sel:[1,0,0] op_sel_hi:[1,1,1]
	v_pk_fma_f32 v[26:27], v[8:9], v[104:105], v[26:27] op_sel:[0,0,0] op_sel_hi:[0,1,1]
	v_pk_fma_f32 v[26:27], v[8:9], v[106:107], v[26:27] op_sel:[1,0,0] op_sel_hi:[1,1,1]
	v_pk_fma_f32 v[16:17], v[108:109], v[158:159], v[10:11] op_sel_hi:[1,0,1]
	v_pk_fma_f32 v[18:19], v[110:111], v[158:159], v[8:9] op_sel_hi:[1,0,1]
	v_add_f32_dpp v15, v26, v26 row_ror:8 row_mask:0xf bank_mask:0xf bound_ctrl:1
	ds_read_b128 v[76:79], v34 offset:20480
	s_nop 0
	v_add_f32_dpp v15, v15, v15 row_ror:4 row_mask:0xf bank_mask:0xf bound_ctrl:1
	ds_read_b128 v[80:83], v34 offset:20736
	ds_read_b128 v[84:87], v34 offset:20992
	v_add_f32_dpp v15, v15, v15 row_ror:2 row_mask:0xf bank_mask:0xf bound_ctrl:1
	ds_read_b128 v[88:91], v34 offset:21248
	ds_write2st64_b32 v37, v25, v27 offset0:64 offset1:68
	v_add_f32_dpp v30, v15, v15 row_ror:1 row_mask:0xf bank_mask:0xf bound_ctrl:1
	s_waitcnt lgkmcnt(4)
	v_pk_fma_f32 v[10:11], v[112:113], v[30:31], v[16:17] op_sel_hi:[1,0,1] neg_lo:[0,1,0] neg_hi:[0,1,0]
	v_pk_fma_f32 v[8:9], v[114:115], v[30:31], v[18:19] op_sel_hi:[1,0,1] neg_lo:[0,1,0] neg_hi:[0,1,0]
	v_pk_mul_f32 v[24:25], v[10:11], v[116:117] op_sel:[0,0] op_sel_hi:[0,1]
	v_pk_fma_f32 v[24:25], v[10:11], v[118:119], v[24:25] op_sel:[1,0,0] op_sel_hi:[1,1,1]
	v_pk_fma_f32 v[24:25], v[8:9], v[120:121], v[24:25] op_sel:[0,0,0] op_sel_hi:[0,1,1]
	v_pk_fma_f32 v[24:25], v[8:9], v[122:123], v[24:25] op_sel:[1,0,0] op_sel_hi:[1,1,1]
	v_pk_fma_f32 v[16:17], v[124:125], v[158:159], v[10:11] op_sel:[0,1,0] op_sel_hi:[1,1,1]
	v_pk_fma_f32 v[18:19], v[126:127], v[158:159], v[8:9] op_sel:[0,1,0] op_sel_hi:[1,1,1]
	v_add_f32_dpp v15, v24, v24 row_ror:8 row_mask:0xf bank_mask:0xf bound_ctrl:1
	ds_read_b128 v[92:95], v34 offset:21504
	s_nop 0
	v_add_f32_dpp v15, v15, v15 row_ror:4 row_mask:0xf bank_mask:0xf bound_ctrl:1
	ds_read_b128 v[96:99], v34 offset:21760
	ds_read_b128 v[100:103], v34 offset:22016
	v_add_f32_dpp v15, v15, v15 row_ror:2 row_mask:0xf bank_mask:0xf bound_ctrl:1
	ds_read_b128 v[104:107], v34 offset:22272
	s_nop 0
	v_add_f32_dpp v30, v15, v15 row_ror:1 row_mask:0xf bank_mask:0xf bound_ctrl:1
	v_pk_fma_f32 v[10:11], v[128:129], v[30:31], v[16:17] op_sel_hi:[1,0,1] neg_lo:[0,1,0] neg_hi:[0,1,0]
	v_pk_fma_f32 v[8:9], v[130:131], v[30:31], v[18:19] op_sel_hi:[1,0,1] neg_lo:[0,1,0] neg_hi:[0,1,0]
	v_pk_mul_f32 v[26:27], v[10:11], v[132:133] op_sel:[0,0] op_sel_hi:[0,1]
	v_pk_fma_f32 v[26:27], v[10:11], v[134:135], v[26:27] op_sel:[1,0,0] op_sel_hi:[1,1,1]
	v_pk_fma_f32 v[26:27], v[8:9], v[136:137], v[26:27] op_sel:[0,0,0] op_sel_hi:[0,1,1]
	v_pk_fma_f32 v[26:27], v[8:9], v[138:139], v[26:27] op_sel:[1,0,0] op_sel_hi:[1,1,1]
	v_pk_fma_f32 v[16:17], v[76:77], v[160:161], v[10:11] op_sel_hi:[1,0,1]
	v_pk_fma_f32 v[18:19], v[78:79], v[160:161], v[8:9] op_sel_hi:[1,0,1]
	v_add_f32_dpp v15, v26, v26 row_ror:8 row_mask:0xf bank_mask:0xf bound_ctrl:1
	ds_read_b128 v[108:111], v34 offset:22528
	s_nop 0
	v_add_f32_dpp v15, v15, v15 row_ror:4 row_mask:0xf bank_mask:0xf bound_ctrl:1
	ds_read_b128 v[112:115], v34 offset:22784
	ds_read_b128 v[116:119], v34 offset:23040
	v_add_f32_dpp v15, v15, v15 row_ror:2 row_mask:0xf bank_mask:0xf bound_ctrl:1
	ds_read_b128 v[120:123], v34 offset:23296
	ds_read_b128 v[140:143], v34 offset:34304
	ds_write2st64_b32 v37, v25, v27 offset0:72 offset1:76
	v_add_f32_dpp v30, v15, v15 row_ror:1 row_mask:0xf bank_mask:0xf bound_ctrl:1
	s_waitcnt lgkmcnt(5)
	v_pk_fma_f32 v[10:11], v[80:81], v[30:31], v[16:17] op_sel_hi:[1,0,1] neg_lo:[0,1,0] neg_hi:[0,1,0]
	v_pk_fma_f32 v[8:9], v[82:83], v[30:31], v[18:19] op_sel_hi:[1,0,1] neg_lo:[0,1,0] neg_hi:[0,1,0]
	v_pk_mul_f32 v[24:25], v[10:11], v[84:85] op_sel:[0,0] op_sel_hi:[0,1]
	v_pk_fma_f32 v[24:25], v[10:11], v[86:87], v[24:25] op_sel:[1,0,0] op_sel_hi:[1,1,1]
	v_pk_fma_f32 v[24:25], v[8:9], v[88:89], v[24:25] op_sel:[0,0,0] op_sel_hi:[0,1,1]
	v_pk_fma_f32 v[24:25], v[8:9], v[90:91], v[24:25] op_sel:[1,0,0] op_sel_hi:[1,1,1]
	v_pk_fma_f32 v[16:17], v[92:93], v[160:161], v[10:11] op_sel:[0,1,0] op_sel_hi:[1,1,1]
	v_pk_fma_f32 v[18:19], v[94:95], v[160:161], v[8:9] op_sel:[0,1,0] op_sel_hi:[1,1,1]
	v_add_f32_dpp v15, v24, v24 row_ror:8 row_mask:0xf bank_mask:0xf bound_ctrl:1
	ds_read_b128 v[124:127], v34 offset:23552
	s_nop 0
	v_add_f32_dpp v15, v15, v15 row_ror:4 row_mask:0xf bank_mask:0xf bound_ctrl:1
	ds_read_b128 v[128:131], v34 offset:23808
	ds_read_b128 v[132:135], v34 offset:24064
	v_add_f32_dpp v15, v15, v15 row_ror:2 row_mask:0xf bank_mask:0xf bound_ctrl:1
	ds_read_b128 v[136:139], v34 offset:24320
	ds_read_b128 v[156:159], v35 offset:96
	v_add_f32_dpp v30, v15, v15 row_ror:1 row_mask:0xf bank_mask:0xf bound_ctrl:1
	v_pk_fma_f32 v[10:11], v[96:97], v[30:31], v[16:17] op_sel_hi:[1,0,1] neg_lo:[0,1,0] neg_hi:[0,1,0]
	v_pk_fma_f32 v[8:9], v[98:99], v[30:31], v[18:19] op_sel_hi:[1,0,1] neg_lo:[0,1,0] neg_hi:[0,1,0]
	v_pk_mul_f32 v[26:27], v[10:11], v[100:101] op_sel:[0,0] op_sel_hi:[0,1]
	v_pk_fma_f32 v[26:27], v[10:11], v[102:103], v[26:27] op_sel:[1,0,0] op_sel_hi:[1,1,1]
	v_pk_fma_f32 v[26:27], v[8:9], v[104:105], v[26:27] op_sel:[0,0,0] op_sel_hi:[0,1,1]
	v_pk_fma_f32 v[26:27], v[8:9], v[106:107], v[26:27] op_sel:[1,0,0] op_sel_hi:[1,1,1]
	v_pk_fma_f32 v[16:17], v[108:109], v[162:163], v[10:11] op_sel_hi:[1,0,1]
	v_pk_fma_f32 v[18:19], v[110:111], v[162:163], v[8:9] op_sel_hi:[1,0,1]
	v_add_f32_dpp v15, v26, v26 row_ror:8 row_mask:0xf bank_mask:0xf bound_ctrl:1
	ds_read_b128 v[76:79], v34 offset:24576
	s_nop 0
	v_add_f32_dpp v15, v15, v15 row_ror:4 row_mask:0xf bank_mask:0xf bound_ctrl:1
	ds_read_b128 v[80:83], v34 offset:24832
	ds_read_b128 v[84:87], v34 offset:25088
	v_add_f32_dpp v15, v15, v15 row_ror:2 row_mask:0xf bank_mask:0xf bound_ctrl:1
	ds_read_b128 v[88:91], v34 offset:25344
	ds_read_b128 v[144:147], v34 offset:33536
	ds_write2st64_b32 v37, v25, v27 offset0:80 offset1:84
	v_add_f32_dpp v30, v15, v15 row_ror:1 row_mask:0xf bank_mask:0xf bound_ctrl:1
	s_waitcnt lgkmcnt(5)
	v_pk_fma_f32 v[10:11], v[112:113], v[30:31], v[16:17] op_sel_hi:[1,0,1] neg_lo:[0,1,0] neg_hi:[0,1,0]
	v_pk_fma_f32 v[8:9], v[114:115], v[30:31], v[18:19] op_sel_hi:[1,0,1] neg_lo:[0,1,0] neg_hi:[0,1,0]
	v_pk_mul_f32 v[24:25], v[10:11], v[116:117] op_sel:[0,0] op_sel_hi:[0,1]
	v_pk_fma_f32 v[24:25], v[10:11], v[118:119], v[24:25] op_sel:[1,0,0] op_sel_hi:[1,1,1]
	v_pk_fma_f32 v[24:25], v[8:9], v[120:121], v[24:25] op_sel:[0,0,0] op_sel_hi:[0,1,1]
	v_pk_fma_f32 v[24:25], v[8:9], v[122:123], v[24:25] op_sel:[1,0,0] op_sel_hi:[1,1,1]
	v_pk_fma_f32 v[16:17], v[124:125], v[162:163], v[10:11] op_sel:[0,1,0] op_sel_hi:[1,1,1]
	v_pk_fma_f32 v[18:19], v[126:127], v[162:163], v[8:9] op_sel:[0,1,0] op_sel_hi:[1,1,1]
	v_add_f32_dpp v15, v24, v24 row_ror:8 row_mask:0xf bank_mask:0xf bound_ctrl:1
	ds_read_b128 v[92:95], v34 offset:25600
	s_nop 0
	v_add_f32_dpp v15, v15, v15 row_ror:4 row_mask:0xf bank_mask:0xf bound_ctrl:1
	ds_read_b128 v[96:99], v34 offset:25856
	ds_read_b128 v[100:103], v34 offset:26112
	v_add_f32_dpp v15, v15, v15 row_ror:2 row_mask:0xf bank_mask:0xf bound_ctrl:1
	ds_read_b128 v[104:107], v34 offset:26368
	s_nop 0
	v_add_f32_dpp v30, v15, v15 row_ror:1 row_mask:0xf bank_mask:0xf bound_ctrl:1
	v_pk_fma_f32 v[10:11], v[128:129], v[30:31], v[16:17] op_sel_hi:[1,0,1] neg_lo:[0,1,0] neg_hi:[0,1,0]
	v_pk_fma_f32 v[8:9], v[130:131], v[30:31], v[18:19] op_sel_hi:[1,0,1] neg_lo:[0,1,0] neg_hi:[0,1,0]
	v_pk_mul_f32 v[26:27], v[10:11], v[132:133] op_sel:[0,0] op_sel_hi:[0,1]
	v_pk_fma_f32 v[26:27], v[10:11], v[134:135], v[26:27] op_sel:[1,0,0] op_sel_hi:[1,1,1]
	v_pk_fma_f32 v[26:27], v[8:9], v[136:137], v[26:27] op_sel:[0,0,0] op_sel_hi:[0,1,1]
	v_pk_fma_f32 v[26:27], v[8:9], v[138:139], v[26:27] op_sel:[1,0,0] op_sel_hi:[1,1,1]
	ds_write2st64_b32 v37, v25, v27 offset0:88 offset1:92
	v_pk_mul_f32 v[10:11], v[10:11], v[140:141]
	v_pk_mul_f32 v[8:9], v[8:9], v[142:143]
	s_waitcnt lgkmcnt(6)
	v_pk_mul_f32 v[24:25], v[10:11], v[144:145]
	v_pk_fma_f32 v[24:25], v[8:9], v[146:147], v[24:25]
	v_add_f32_e32 v24, v24, v25
	v_pk_fma_f32 v[16:17], v[76:77], v[156:157], v[10:11] op_sel_hi:[1,0,1]
	v_pk_fma_f32 v[18:19], v[78:79], v[156:157], v[8:9] op_sel_hi:[1,0,1]
	v_add_f32_dpp v15, v24, v24 row_ror:8 row_mask:0xf bank_mask:0xf bound_ctrl:1
	ds_read_b128 v[108:111], v34 offset:26624
	ds_read_b128 v[112:115], v34 offset:26880
	v_add_f32_dpp v15, v15, v15 row_ror:4 row_mask:0xf bank_mask:0xf bound_ctrl:1
	ds_read_b128 v[116:119], v34 offset:27136
	ds_read_b128 v[120:123], v34 offset:27392
	v_add_f32_dpp v15, v15, v15 row_ror:2 row_mask:0xf bank_mask:0xf bound_ctrl:1
	s_nop 1
	v_add_f32_dpp v30, v15, v15 row_ror:1 row_mask:0xf bank_mask:0xf bound_ctrl:1
	s_waitcnt lgkmcnt(3)
	v_pk_fma_f32 v[10:11], v[80:81], v[30:31], v[16:17] op_sel_hi:[1,0,1] neg_lo:[0,1,0] neg_hi:[0,1,0]
	v_pk_fma_f32 v[8:9], v[82:83], v[30:31], v[18:19] op_sel_hi:[1,0,1] neg_lo:[0,1,0] neg_hi:[0,1,0]
	v_pk_mul_f32 v[24:25], v[10:11], v[84:85] op_sel:[0,0] op_sel_hi:[0,1]
	v_pk_fma_f32 v[24:25], v[10:11], v[86:87], v[24:25] op_sel:[1,0,0] op_sel_hi:[1,1,1]
	v_pk_fma_f32 v[24:25], v[8:9], v[88:89], v[24:25] op_sel:[0,0,0] op_sel_hi:[0,1,1]
	v_pk_fma_f32 v[24:25], v[8:9], v[90:91], v[24:25] op_sel:[1,0,0] op_sel_hi:[1,1,1]
	v_pk_fma_f32 v[16:17], v[92:93], v[156:157], v[10:11] op_sel:[0,1,0] op_sel_hi:[1,1,1]
	v_pk_fma_f32 v[18:19], v[94:95], v[156:157], v[8:9] op_sel:[0,1,0] op_sel_hi:[1,1,1]
	v_add_f32_dpp v15, v24, v24 row_ror:8 row_mask:0xf bank_mask:0xf bound_ctrl:1
	ds_read_b128 v[124:127], v34 offset:27648
	s_nop 0
	v_add_f32_dpp v15, v15, v15 row_ror:4 row_mask:0xf bank_mask:0xf bound_ctrl:1
	ds_read_b128 v[128:131], v34 offset:27904
	ds_read_b128 v[132:135], v34 offset:28160
	v_add_f32_dpp v15, v15, v15 row_ror:2 row_mask:0xf bank_mask:0xf bound_ctrl:1
	ds_read_b128 v[136:139], v34 offset:28416
	ds_read_b128 v[160:163], v35 offset:112
	v_add_f32_dpp v30, v15, v15 row_ror:1 row_mask:0xf bank_mask:0xf bound_ctrl:1
	v_pk_fma_f32 v[10:11], v[96:97], v[30:31], v[16:17] op_sel_hi:[1,0,1] neg_lo:[0,1,0] neg_hi:[0,1,0]
	v_pk_fma_f32 v[8:9], v[98:99], v[30:31], v[18:19] op_sel_hi:[1,0,1] neg_lo:[0,1,0] neg_hi:[0,1,0]
	v_pk_mul_f32 v[26:27], v[10:11], v[100:101] op_sel:[0,0] op_sel_hi:[0,1]
	v_pk_fma_f32 v[26:27], v[10:11], v[102:103], v[26:27] op_sel:[1,0,0] op_sel_hi:[1,1,1]
	v_pk_fma_f32 v[26:27], v[8:9], v[104:105], v[26:27] op_sel:[0,0,0] op_sel_hi:[0,1,1]
	v_pk_fma_f32 v[26:27], v[8:9], v[106:107], v[26:27] op_sel:[1,0,0] op_sel_hi:[1,1,1]
	v_pk_fma_f32 v[16:17], v[108:109], v[158:159], v[10:11] op_sel_hi:[1,0,1]
	v_pk_fma_f32 v[18:19], v[110:111], v[158:159], v[8:9] op_sel_hi:[1,0,1]
	v_add_f32_dpp v15, v26, v26 row_ror:8 row_mask:0xf bank_mask:0xf bound_ctrl:1
	ds_read_b128 v[76:79], v34 offset:28672
	s_nop 0
	v_add_f32_dpp v15, v15, v15 row_ror:4 row_mask:0xf bank_mask:0xf bound_ctrl:1
	ds_read_b128 v[80:83], v34 offset:28928
	ds_read_b128 v[84:87], v34 offset:29184
	v_add_f32_dpp v15, v15, v15 row_ror:2 row_mask:0xf bank_mask:0xf bound_ctrl:1
	ds_read_b128 v[88:91], v34 offset:29440
	ds_write2st64_b32 v37, v25, v27 offset0:96 offset1:100
	v_add_f32_dpp v30, v15, v15 row_ror:1 row_mask:0xf bank_mask:0xf bound_ctrl:1
	ds_read_b128 v[56:59], v52
	s_waitcnt lgkmcnt(5)
	v_pk_fma_f32 v[10:11], v[112:113], v[30:31], v[16:17] op_sel_hi:[1,0,1] neg_lo:[0,1,0] neg_hi:[0,1,0]
	v_pk_fma_f32 v[8:9], v[114:115], v[30:31], v[18:19] op_sel_hi:[1,0,1] neg_lo:[0,1,0] neg_hi:[0,1,0]
	v_pk_mul_f32 v[24:25], v[10:11], v[116:117] op_sel:[0,0] op_sel_hi:[0,1]
	v_pk_fma_f32 v[24:25], v[10:11], v[118:119], v[24:25] op_sel:[1,0,0] op_sel_hi:[1,1,1]
	v_pk_fma_f32 v[24:25], v[8:9], v[120:121], v[24:25] op_sel:[0,0,0] op_sel_hi:[0,1,1]
	v_pk_fma_f32 v[24:25], v[8:9], v[122:123], v[24:25] op_sel:[1,0,0] op_sel_hi:[1,1,1]
	v_pk_fma_f32 v[16:17], v[124:125], v[158:159], v[10:11] op_sel:[0,1,0] op_sel_hi:[1,1,1]
	v_pk_fma_f32 v[18:19], v[126:127], v[158:159], v[8:9] op_sel:[0,1,0] op_sel_hi:[1,1,1]
	v_add_f32_dpp v15, v24, v24 row_ror:8 row_mask:0xf bank_mask:0xf bound_ctrl:1
	ds_read_b128 v[92:95], v34 offset:29696
	s_nop 0
	v_add_f32_dpp v15, v15, v15 row_ror:4 row_mask:0xf bank_mask:0xf bound_ctrl:1
	ds_read_b128 v[96:99], v34 offset:29952
	ds_read_b128 v[100:103], v34 offset:30208
	v_add_f32_dpp v15, v15, v15 row_ror:2 row_mask:0xf bank_mask:0xf bound_ctrl:1
	ds_read_b128 v[104:107], v34 offset:30464
	s_nop 0
	v_add_f32_dpp v30, v15, v15 row_ror:1 row_mask:0xf bank_mask:0xf bound_ctrl:1
	s_waitcnt lgkmcnt(4)
	v_min_u32_e32 v56, v56, v57
	v_min3_u32 v56, v56, v58, v59
	v_pk_fma_f32 v[10:11], v[128:129], v[30:31], v[16:17] op_sel_hi:[1,0,1] neg_lo:[0,1,0] neg_hi:[0,1,0]
	v_pk_fma_f32 v[8:9], v[130:131], v[30:31], v[18:19] op_sel_hi:[1,0,1] neg_lo:[0,1,0] neg_hi:[0,1,0]
	v_pk_mul_f32 v[26:27], v[10:11], v[132:133] op_sel:[0,0] op_sel_hi:[0,1]
	v_pk_fma_f32 v[26:27], v[10:11], v[134:135], v[26:27] op_sel:[1,0,0] op_sel_hi:[1,1,1]
	v_pk_fma_f32 v[26:27], v[8:9], v[136:137], v[26:27] op_sel:[0,0,0] op_sel_hi:[0,1,1]
	v_pk_fma_f32 v[26:27], v[8:9], v[138:139], v[26:27] op_sel:[1,0,0] op_sel_hi:[1,1,1]
	v_pk_fma_f32 v[16:17], v[76:77], v[160:161], v[10:11] op_sel_hi:[1,0,1]
	v_pk_fma_f32 v[18:19], v[78:79], v[160:161], v[8:9] op_sel_hi:[1,0,1]
	v_add_f32_dpp v15, v26, v26 row_ror:8 row_mask:0xf bank_mask:0xf bound_ctrl:1
	ds_read_b128 v[108:111], v34 offset:30720
	s_nop 0
	v_add_f32_dpp v15, v15, v15 row_ror:4 row_mask:0xf bank_mask:0xf bound_ctrl:1
	ds_read_b128 v[112:115], v34 offset:30976
	ds_read_b128 v[116:119], v34 offset:31232
	v_add_f32_dpp v15, v15, v15 row_ror:2 row_mask:0xf bank_mask:0xf bound_ctrl:1
	ds_read_b128 v[120:123], v34 offset:31488
	ds_read_b128 v[140:143], v34 offset:34560
	ds_write2st64_b32 v37, v25, v27 offset0:104 offset1:108
	v_add_f32_dpp v30, v15, v15 row_ror:1 row_mask:0xf bank_mask:0xf bound_ctrl:1
	s_waitcnt lgkmcnt(5)
	v_pk_fma_f32 v[10:11], v[80:81], v[30:31], v[16:17] op_sel_hi:[1,0,1] neg_lo:[0,1,0] neg_hi:[0,1,0]
	v_pk_fma_f32 v[8:9], v[82:83], v[30:31], v[18:19] op_sel_hi:[1,0,1] neg_lo:[0,1,0] neg_hi:[0,1,0]
	v_pk_mul_f32 v[24:25], v[10:11], v[84:85] op_sel:[0,0] op_sel_hi:[0,1]
	v_pk_fma_f32 v[24:25], v[10:11], v[86:87], v[24:25] op_sel:[1,0,0] op_sel_hi:[1,1,1]
	v_pk_fma_f32 v[24:25], v[8:9], v[88:89], v[24:25] op_sel:[0,0,0] op_sel_hi:[0,1,1]
	v_pk_fma_f32 v[24:25], v[8:9], v[90:91], v[24:25] op_sel:[1,0,0] op_sel_hi:[1,1,1]
	v_pk_fma_f32 v[16:17], v[92:93], v[160:161], v[10:11] op_sel:[0,1,0] op_sel_hi:[1,1,1]
	v_pk_fma_f32 v[18:19], v[94:95], v[160:161], v[8:9] op_sel:[0,1,0] op_sel_hi:[1,1,1]
	v_add_f32_dpp v15, v24, v24 row_ror:8 row_mask:0xf bank_mask:0xf bound_ctrl:1
	ds_read_b128 v[124:127], v34 offset:31744
	s_nop 0
	v_add_f32_dpp v15, v15, v15 row_ror:4 row_mask:0xf bank_mask:0xf bound_ctrl:1
	ds_read_b128 v[128:131], v34 offset:32000
	ds_read_b128 v[132:135], v34 offset:32256
	v_add_f32_dpp v15, v15, v15 row_ror:2 row_mask:0xf bank_mask:0xf bound_ctrl:1
	ds_read_b128 v[136:139], v34 offset:32512
	s_nop 0
	v_add_f32_dpp v30, v15, v15 row_ror:1 row_mask:0xf bank_mask:0xf bound_ctrl:1
	v_readfirstlane_b32 s54, v56
	s_add_u32 s64, s6, 2
	s_cmp_lt_u32 s54, s64
	s_cbranch_scc1 .Lss_spin_0
.Lss_ok_0:
	v_pk_fma_f32 v[10:11], v[96:97], v[30:31], v[16:17] op_sel_hi:[1,0,1] neg_lo:[0,1,0] neg_hi:[0,1,0]
	v_pk_fma_f32 v[8:9], v[98:99], v[30:31], v[18:19] op_sel_hi:[1,0,1] neg_lo:[0,1,0] neg_hi:[0,1,0]
	v_pk_mul_f32 v[26:27], v[10:11], v[100:101] op_sel:[0,0] op_sel_hi:[0,1]
	v_pk_fma_f32 v[26:27], v[10:11], v[102:103], v[26:27] op_sel:[1,0,0] op_sel_hi:[1,1,1]
	v_pk_fma_f32 v[26:27], v[8:9], v[104:105], v[26:27] op_sel:[0,0,0] op_sel_hi:[0,1,1]
	v_pk_fma_f32 v[26:27], v[8:9], v[106:107], v[26:27] op_sel:[1,0,0] op_sel_hi:[1,1,1]
	v_pk_fma_f32 v[16:17], v[108:109], v[162:163], v[10:11] op_sel_hi:[1,0,1]
	v_pk_fma_f32 v[18:19], v[110:111], v[162:163], v[8:9] op_sel_hi:[1,0,1]
	v_add_f32_dpp v15, v26, v26 row_ror:8 row_mask:0xf bank_mask:0xf bound_ctrl:1
	ds_read_b128 v[76:79], v48 offset:0
	s_nop 0
	v_add_f32_dpp v15, v15, v15 row_ror:4 row_mask:0xf bank_mask:0xf bound_ctrl:1
	ds_read_b128 v[80:83], v48 offset:256
	ds_read_b128 v[84:87], v48 offset:512
	v_add_f32_dpp v15, v15, v15 row_ror:2 row_mask:0xf bank_mask:0xf bound_ctrl:1
	ds_read_b128 v[88:91], v48 offset:768
	ds_read_b128 v[144:147], v48 offset:32768
	ds_write2st64_b32 v37, v25, v27 offset0:112 offset1:116
	v_add_f32_dpp v30, v15, v15 row_ror:1 row_mask:0xf bank_mask:0xf bound_ctrl:1
	ds_read_b128 v[156:159], v49 offset:0
	s_waitcnt lgkmcnt(6)
	v_pk_fma_f32 v[10:11], v[112:113], v[30:31], v[16:17] op_sel_hi:[1,0,1] neg_lo:[0,1,0] neg_hi:[0,1,0]
	v_pk_fma_f32 v[8:9], v[114:115], v[30:31], v[18:19] op_sel_hi:[1,0,1] neg_lo:[0,1,0] neg_hi:[0,1,0]
	v_pk_mul_f32 v[24:25], v[10:11], v[116:117] op_sel:[0,0] op_sel_hi:[0,1]
	v_pk_fma_f32 v[24:25], v[10:11], v[118:119], v[24:25] op_sel:[1,0,0] op_sel_hi:[1,1,1]
	v_pk_fma_f32 v[24:25], v[8:9], v[120:121], v[24:25] op_sel:[0,0,0] op_sel_hi:[0,1,1]
	v_pk_fma_f32 v[24:25], v[8:9], v[122:123], v[24:25] op_sel:[1,0,0] op_sel_hi:[1,1,1]
	v_pk_fma_f32 v[16:17], v[124:125], v[162:163], v[10:11] op_sel:[0,1,0] op_sel_hi:[1,1,1]
	v_pk_fma_f32 v[18:19], v[126:127], v[162:163], v[8:9] op_sel:[0,1,0] op_sel_hi:[1,1,1]
	v_add_f32_dpp v15, v24, v24 row_ror:8 row_mask:0xf bank_mask:0xf bound_ctrl:1
	ds_read_b128 v[92:95], v48 offset:1024
	s_nop 0
	v_add_f32_dpp v15, v15, v15 row_ror:4 row_mask:0xf bank_mask:0xf bound_ctrl:1
	ds_read_b128 v[96:99], v48 offset:1280
	ds_read_b128 v[100:103], v48 offset:1536
	v_add_f32_dpp v15, v15, v15 row_ror:2 row_mask:0xf bank_mask:0xf bound_ctrl:1
	ds_read_b128 v[104:107], v48 offset:1792
	s_nop 0
	v_add_f32_dpp v30, v15, v15 row_ror:1 row_mask:0xf bank_mask:0xf bound_ctrl:1
	v_pk_fma_f32 v[10:11], v[128:129], v[30:31], v[16:17] op_sel_hi:[1,0,1] neg_lo:[0,1,0] neg_hi:[0,1,0]
	v_pk_fma_f32 v[8:9], v[130:131], v[30:31], v[18:19] op_sel_hi:[1,0,1] neg_lo:[0,1,0] neg_hi:[0,1,0]
	v_pk_mul_f32 v[26:27], v[10:11], v[132:133] op_sel:[0,0] op_sel_hi:[0,1]
	v_pk_fma_f32 v[26:27], v[10:11], v[134:135], v[26:27] op_sel:[1,0,0] op_sel_hi:[1,1,1]
	v_pk_fma_f32 v[26:27], v[8:9], v[136:137], v[26:27] op_sel:[0,0,0] op_sel_hi:[0,1,1]
	v_pk_fma_f32 v[26:27], v[8:9], v[138:139], v[26:27] op_sel:[1,0,0] op_sel_hi:[1,1,1]
	ds_write2st64_b32 v37, v25, v27 offset0:120 offset1:124
	v_pk_mul_f32 v[10:11], v[10:11], v[140:141]
	v_pk_mul_f32 v[8:9], v[8:9], v[142:143]
	s_waitcnt lgkmcnt(7)
	v_pk_mul_f32 v[24:25], v[10:11], v[144:145]
	v_pk_fma_f32 v[24:25], v[8:9], v[146:147], v[24:25]
	v_add_f32_e32 v24, v24, v25
	s_waitcnt lgkmcnt(5)
	v_pk_fma_f32 v[16:17], v[76:77], v[156:157], v[10:11] op_sel_hi:[1,0,1]
	v_pk_fma_f32 v[18:19], v[78:79], v[156:157], v[8:9] op_sel_hi:[1,0,1]
	v_add_f32_dpp v15, v24, v24 row_ror:8 row_mask:0xf bank_mask:0xf bound_ctrl:1
	v_add_u32_e32 v51, 1, v51
	s_add_u32 s6, s6, 1
	v_add_f32_dpp v15, v15, v15 row_ror:4 row_mask:0xf bank_mask:0xf bound_ctrl:1
	ds_write_b32 v53, v51
	ds_read_b128 v[108:111], v48 offset:2048
	v_add_f32_dpp v15, v15, v15 row_ror:2 row_mask:0xf bank_mask:0xf bound_ctrl:1
	ds_read_b128 v[112:115], v48 offset:2304
	ds_read_b128 v[116:119], v48 offset:2560
	v_add_f32_dpp v30, v15, v15 row_ror:1 row_mask:0xf bank_mask:0xf bound_ctrl:1
	ds_read_b128 v[120:123], v48 offset:2816
	s_waitcnt lgkmcnt(3)
	v_pk_fma_f32 v[10:11], v[80:81], v[30:31], v[16:17] op_sel_hi:[1,0,1] neg_lo:[0,1,0] neg_hi:[0,1,0]
	v_pk_fma_f32 v[8:9], v[82:83], v[30:31], v[18:19] op_sel_hi:[1,0,1] neg_lo:[0,1,0] neg_hi:[0,1,0]
	v_pk_mul_f32 v[24:25], v[10:11], v[84:85] op_sel:[0,0] op_sel_hi:[0,1]
	v_pk_fma_f32 v[24:25], v[10:11], v[86:87], v[24:25] op_sel:[1,0,0] op_sel_hi:[1,1,1]
	v_pk_fma_f32 v[24:25], v[8:9], v[88:89], v[24:25] op_sel:[0,0,0] op_sel_hi:[0,1,1]
	v_pk_fma_f32 v[24:25], v[8:9], v[90:91], v[24:25] op_sel:[1,0,0] op_sel_hi:[1,1,1]
	v_pk_fma_f32 v[16:17], v[92:93], v[156:157], v[10:11] op_sel:[0,1,0] op_sel_hi:[1,1,1]
	v_pk_fma_f32 v[18:19], v[94:95], v[156:157], v[8:9] op_sel:[0,1,0] op_sel_hi:[1,1,1]
	v_add_f32_dpp v15, v24, v24 row_ror:8 row_mask:0xf bank_mask:0xf bound_ctrl:1
	ds_read_b128 v[124:127], v48 offset:3072
	s_nop 0
	v_add_f32_dpp v15, v15, v15 row_ror:4 row_mask:0xf bank_mask:0xf bound_ctrl:1
	ds_read_b128 v[128:131], v48 offset:3328
	ds_read_b128 v[132:135], v48 offset:3584
	v_add_f32_dpp v15, v15, v15 row_ror:2 row_mask:0xf bank_mask:0xf bound_ctrl:1
	ds_read_b128 v[136:139], v48 offset:3840
	ds_read_b128 v[160:163], v49 offset:16
	v_add_f32_dpp v30, v15, v15 row_ror:1 row_mask:0xf bank_mask:0xf bound_ctrl:1
	v_pk_fma_f32 v[10:11], v[96:97], v[30:31], v[16:17] op_sel_hi:[1,0,1] neg_lo:[0,1,0] neg_hi:[0,1,0]
	v_pk_fma_f32 v[8:9], v[98:99], v[30:31], v[18:19] op_sel_hi:[1,0,1] neg_lo:[0,1,0] neg_hi:[0,1,0]
	v_pk_mul_f32 v[26:27], v[10:11], v[100:101] op_sel:[0,0] op_sel_hi:[0,1]
	v_pk_fma_f32 v[26:27], v[10:11], v[102:103], v[26:27] op_sel:[1,0,0] op_sel_hi:[1,1,1]
	v_pk_fma_f32 v[26:27], v[8:9], v[104:105], v[26:27] op_sel:[0,0,0] op_sel_hi:[0,1,1]
	v_pk_fma_f32 v[26:27], v[8:9], v[106:107], v[26:27] op_sel:[1,0,0] op_sel_hi:[1,1,1]
	v_pk_fma_f32 v[16:17], v[108:109], v[158:159], v[10:11] op_sel_hi:[1,0,1]
	v_pk_fma_f32 v[18:19], v[110:111], v[158:159], v[8:9] op_sel_hi:[1,0,1]
	v_add_f32_dpp v15, v26, v26 row_ror:8 row_mask:0xf bank_mask:0xf bound_ctrl:1
	ds_read_b128 v[76:79], v48 offset:4096
	s_nop 0
	v_add_f32_dpp v15, v15, v15 row_ror:4 row_mask:0xf bank_mask:0xf bound_ctrl:1
	ds_read_b128 v[80:83], v48 offset:4352
	ds_read_b128 v[84:87], v48 offset:4608
	v_add_f32_dpp v15, v15, v15 row_ror:2 row_mask:0xf bank_mask:0xf bound_ctrl:1
	ds_read_b128 v[88:91], v48 offset:4864
	ds_write2st64_b32 v50, v25, v27 offset0:0 offset1:4
	v_add_f32_dpp v30, v15, v15 row_ror:1 row_mask:0xf bank_mask:0xf bound_ctrl:1
	s_waitcnt lgkmcnt(4)
	v_pk_fma_f32 v[10:11], v[112:113], v[30:31], v[16:17] op_sel_hi:[1,0,1] neg_lo:[0,1,0] neg_hi:[0,1,0]
	v_pk_fma_f32 v[8:9], v[114:115], v[30:31], v[18:19] op_sel_hi:[1,0,1] neg_lo:[0,1,0] neg_hi:[0,1,0]
	v_pk_mul_f32 v[24:25], v[10:11], v[116:117] op_sel:[0,0] op_sel_hi:[0,1]
	v_pk_fma_f32 v[24:25], v[10:11], v[118:119], v[24:25] op_sel:[1,0,0] op_sel_hi:[1,1,1]
	v_pk_fma_f32 v[24:25], v[8:9], v[120:121], v[24:25] op_sel:[0,0,0] op_sel_hi:[0,1,1]
	v_pk_fma_f32 v[24:25], v[8:9], v[122:123], v[24:25] op_sel:[1,0,0] op_sel_hi:[1,1,1]
	v_pk_fma_f32 v[16:17], v[124:125], v[158:159], v[10:11] op_sel:[0,1,0] op_sel_hi:[1,1,1]
	v_pk_fma_f32 v[18:19], v[126:127], v[158:159], v[8:9] op_sel:[0,1,0] op_sel_hi:[1,1,1]
	v_add_f32_dpp v15, v24, v24 row_ror:8 row_mask:0xf bank_mask:0xf bound_ctrl:1
	ds_read_b128 v[92:95], v48 offset:5120
	s_nop 0
	v_add_f32_dpp v15, v15, v15 row_ror:4 row_mask:0xf bank_mask:0xf bound_ctrl:1
	ds_read_b128 v[96:99], v48 offset:5376
	ds_read_b128 v[100:103], v48 offset:5632
	v_add_f32_dpp v15, v15, v15 row_ror:2 row_mask:0xf bank_mask:0xf bound_ctrl:1
	ds_read_b128 v[104:107], v48 offset:5888
	s_nop 0
	v_add_f32_dpp v30, v15, v15 row_ror:1 row_mask:0xf bank_mask:0xf bound_ctrl:1
	v_pk_fma_f32 v[10:11], v[128:129], v[30:31], v[16:17] op_sel_hi:[1,0,1] neg_lo:[0,1,0] neg_hi:[0,1,0]
	v_pk_fma_f32 v[8:9], v[130:131], v[30:31], v[18:19] op_sel_hi:[1,0,1] neg_lo:[0,1,0] neg_hi:[0,1,0]
	v_pk_mul_f32 v[26:27], v[10:11], v[132:133] op_sel:[0,0] op_sel_hi:[0,1]
	v_pk_fma_f32 v[26:27], v[10:11], v[134:135], v[26:27] op_sel:[1,0,0] op_sel_hi:[1,1,1]
	v_pk_fma_f32 v[26:27], v[8:9], v[136:137], v[26:27] op_sel:[0,0,0] op_sel_hi:[0,1,1]
	v_pk_fma_f32 v[26:27], v[8:9], v[138:139], v[26:27] op_sel:[1,0,0] op_sel_hi:[1,1,1]
	v_pk_fma_f32 v[16:17], v[76:77], v[160:161], v[10:11] op_sel_hi:[1,0,1]
	v_pk_fma_f32 v[18:19], v[78:79], v[160:161], v[8:9] op_sel_hi:[1,0,1]
	v_add_f32_dpp v15, v26, v26 row_ror:8 row_mask:0xf bank_mask:0xf bound_ctrl:1
	ds_read_b128 v[108:111], v48 offset:6144
	s_nop 0
	v_add_f32_dpp v15, v15, v15 row_ror:4 row_mask:0xf bank_mask:0xf bound_ctrl:1
	ds_read_b128 v[112:115], v48 offset:6400
	ds_read_b128 v[116:119], v48 offset:6656
	v_add_f32_dpp v15, v15, v15 row_ror:2 row_mask:0xf bank_mask:0xf bound_ctrl:1
	ds_read_b128 v[120:123], v48 offset:6912
	ds_read_b128 v[140:143], v48 offset:33792
	ds_write2st64_b32 v50, v25, v27 offset0:8 offset1:12
	v_add_f32_dpp v30, v15, v15 row_ror:1 row_mask:0xf bank_mask:0xf bound_ctrl:1
	s_waitcnt lgkmcnt(5)
	v_pk_fma_f32 v[10:11], v[80:81], v[30:31], v[16:17] op_sel_hi:[1,0,1] neg_lo:[0,1,0] neg_hi:[0,1,0]
	v_pk_fma_f32 v[8:9], v[82:83], v[30:31], v[18:19] op_sel_hi:[1,0,1] neg_lo:[0,1,0] neg_hi:[0,1,0]
	v_pk_mul_f32 v[24:25], v[10:11], v[84:85] op_sel:[0,0] op_sel_hi:[0,1]
	v_pk_fma_f32 v[24:25], v[10:11], v[86:87], v[24:25] op_sel:[1,0,0] op_sel_hi:[1,1,1]
	v_pk_fma_f32 v[24:25], v[8:9], v[88:89], v[24:25] op_sel:[0,0,0] op_sel_hi:[0,1,1]
	v_pk_fma_f32 v[24:25], v[8:9], v[90:91], v[24:25] op_sel:[1,0,0] op_sel_hi:[1,1,1]
	v_pk_fma_f32 v[16:17], v[92:93], v[160:161], v[10:11] op_sel:[0,1,0] op_sel_hi:[1,1,1]
	v_pk_fma_f32 v[18:19], v[94:95], v[160:161], v[8:9] op_sel:[0,1,0] op_sel_hi:[1,1,1]
	v_add_f32_dpp v15, v24, v24 row_ror:8 row_mask:0xf bank_mask:0xf bound_ctrl:1
	ds_read_b128 v[124:127], v48 offset:7168
	s_nop 0
	v_add_f32_dpp v15, v15, v15 row_ror:4 row_mask:0xf bank_mask:0xf bound_ctrl:1
	ds_read_b128 v[128:131], v48 offset:7424
	ds_read_b128 v[132:135], v48 offset:7680
	v_add_f32_dpp v15, v15, v15 row_ror:2 row_mask:0xf bank_mask:0xf bound_ctrl:1
	ds_read_b128 v[136:139], v48 offset:7936
	ds_read_b128 v[156:159], v49 offset:32
	v_add_f32_dpp v30, v15, v15 row_ror:1 row_mask:0xf bank_mask:0xf bound_ctrl:1
	v_pk_fma_f32 v[10:11], v[96:97], v[30:31], v[16:17] op_sel_hi:[1,0,1] neg_lo:[0,1,0] neg_hi:[0,1,0]
	v_pk_fma_f32 v[8:9], v[98:99], v[30:31], v[18:19] op_sel_hi:[1,0,1] neg_lo:[0,1,0] neg_hi:[0,1,0]
	v_pk_mul_f32 v[26:27], v[10:11], v[100:101] op_sel:[0,0] op_sel_hi:[0,1]
	v_pk_fma_f32 v[26:27], v[10:11], v[102:103], v[26:27] op_sel:[1,0,0] op_sel_hi:[1,1,1]
	v_pk_fma_f32 v[26:27], v[8:9], v[104:105], v[26:27] op_sel:[0,0,0] op_sel_hi:[0,1,1]
	v_pk_fma_f32 v[26:27], v[8:9], v[106:107], v[26:27] op_sel:[1,0,0] op_sel_hi:[1,1,1]
	v_pk_fma_f32 v[16:17], v[108:109], v[162:163], v[10:11] op_sel_hi:[1,0,1]
	v_pk_fma_f32 v[18:19], v[110:111], v[162:163], v[8:9] op_sel_hi:[1,0,1]
	v_add_f32_dpp v15, v26, v26 row_ror:8 row_mask:0xf bank_mask:0xf bound_ctrl:1
	ds_read_b128 v[76:79], v48 offset:8192
	s_nop 0
	v_add_f32_dpp v15, v15, v15 row_ror:4 row_mask:0xf bank_mask:0xf bound_ctrl:1
	ds_read_b128 v[80:83], v48 offset:8448
	ds_read_b128 v[84:87], v48 offset:8704
	v_add_f32_dpp v15, v15, v15 row_ror:2 row_mask:0xf bank_mask:0xf bound_ctrl:1
	ds_read_b128 v[88:91], v48 offset:8960
	ds_read_b128 v[144:147], v48 offset:33024
	ds_write2st64_b32 v50, v25, v27 offset0:16 offset1:20
	v_add_f32_dpp v30, v15, v15 row_ror:1 row_mask:0xf bank_mask:0xf bound_ctrl:1
	s_waitcnt lgkmcnt(5)
	v_pk_fma_f32 v[10:11], v[112:113], v[30:31], v[16:17] op_sel_hi:[1,0,1] neg_lo:[0,1,0] neg_hi:[0,1,0]
	v_pk_fma_f32 v[8:9], v[114:115], v[30:31], v[18:19] op_sel_hi:[1,0,1] neg_lo:[0,1,0] neg_hi:[0,1,0]
	v_pk_mul_f32 v[24:25], v[10:11], v[116:117] op_sel:[0,0] op_sel_hi:[0,1]
	v_pk_fma_f32 v[24:25], v[10:11], v[118:119], v[24:25] op_sel:[1,0,0] op_sel_hi:[1,1,1]
	v_pk_fma_f32 v[24:25], v[8:9], v[120:121], v[24:25] op_sel:[0,0,0] op_sel_hi:[0,1,1]
	v_pk_fma_f32 v[24:25], v[8:9], v[122:123], v[24:25] op_sel:[1,0,0] op_sel_hi:[1,1,1]
	v_pk_fma_f32 v[16:17], v[124:125], v[162:163], v[10:11] op_sel:[0,1,0] op_sel_hi:[1,1,1]
	v_pk_fma_f32 v[18:19], v[126:127], v[162:163], v[8:9] op_sel:[0,1,0] op_sel_hi:[1,1,1]
	v_add_f32_dpp v15, v24, v24 row_ror:8 row_mask:0xf bank_mask:0xf bound_ctrl:1
	ds_read_b128 v[92:95], v48 offset:9216
	s_nop 0
	v_add_f32_dpp v15, v15, v15 row_ror:4 row_mask:0xf bank_mask:0xf bound_ctrl:1
	ds_read_b128 v[96:99], v48 offset:9472
	ds_read_b128 v[100:103], v48 offset:9728
	v_add_f32_dpp v15, v15, v15 row_ror:2 row_mask:0xf bank_mask:0xf bound_ctrl:1
	ds_read_b128 v[104:107], v48 offset:9984
	s_nop 0
	v_add_f32_dpp v30, v15, v15 row_ror:1 row_mask:0xf bank_mask:0xf bound_ctrl:1
	v_pk_fma_f32 v[10:11], v[128:129], v[30:31], v[16:17] op_sel_hi:[1,0,1] neg_lo:[0,1,0] neg_hi:[0,1,0]
	v_pk_fma_f32 v[8:9], v[130:131], v[30:31], v[18:19] op_sel_hi:[1,0,1] neg_lo:[0,1,0] neg_hi:[0,1,0]
	v_pk_mul_f32 v[26:27], v[10:11], v[132:133] op_sel:[0,0] op_sel_hi:[0,1]
	v_pk_fma_f32 v[26:27], v[10:11], v[134:135], v[26:27] op_sel:[1,0,0] op_sel_hi:[1,1,1]
	v_pk_fma_f32 v[26:27], v[8:9], v[136:137], v[26:27] op_sel:[0,0,0] op_sel_hi:[0,1,1]
	v_pk_fma_f32 v[26:27], v[8:9], v[138:139], v[26:27] op_sel:[1,0,0] op_sel_hi:[1,1,1]
	ds_write2st64_b32 v50, v25, v27 offset0:24 offset1:28
	v_pk_mul_f32 v[10:11], v[10:11], v[140:141]
	v_pk_mul_f32 v[8:9], v[8:9], v[142:143]
	s_waitcnt lgkmcnt(6)
	v_pk_mul_f32 v[24:25], v[10:11], v[144:145]
	v_pk_fma_f32 v[24:25], v[8:9], v[146:147], v[24:25]
	v_add_f32_e32 v24, v24, v25
	v_pk_fma_f32 v[16:17], v[76:77], v[156:157], v[10:11] op_sel_hi:[1,0,1]
	v_pk_fma_f32 v[18:19], v[78:79], v[156:157], v[8:9] op_sel_hi:[1,0,1]
	v_add_f32_dpp v15, v24, v24 row_ror:8 row_mask:0xf bank_mask:0xf bound_ctrl:1
	ds_read_b128 v[108:111], v48 offset:10240
	ds_read_b128 v[112:115], v48 offset:10496
	v_add_f32_dpp v15, v15, v15 row_ror:4 row_mask:0xf bank_mask:0xf bound_ctrl:1
	ds_read_b128 v[116:119], v48 offset:10752
	ds_read_b128 v[120:123], v48 offset:11008
	v_add_f32_dpp v15, v15, v15 row_ror:2 row_mask:0xf bank_mask:0xf bound_ctrl:1
	s_nop 1
	v_add_f32_dpp v30, v15, v15 row_ror:1 row_mask:0xf bank_mask:0xf bound_ctrl:1
	s_waitcnt lgkmcnt(3)
	v_pk_fma_f32 v[10:11], v[80:81], v[30:31], v[16:17] op_sel_hi:[1,0,1] neg_lo:[0,1,0] neg_hi:[0,1,0]
	v_pk_fma_f32 v[8:9], v[82:83], v[30:31], v[18:19] op_sel_hi:[1,0,1] neg_lo:[0,1,0] neg_hi:[0,1,0]
	v_pk_mul_f32 v[24:25], v[10:11], v[84:85] op_sel:[0,0] op_sel_hi:[0,1]
	v_pk_fma_f32 v[24:25], v[10:11], v[86:87], v[24:25] op_sel:[1,0,0] op_sel_hi:[1,1,1]
	v_pk_fma_f32 v[24:25], v[8:9], v[88:89], v[24:25] op_sel:[0,0,0] op_sel_hi:[0,1,1]
	v_pk_fma_f32 v[24:25], v[8:9], v[90:91], v[24:25] op_sel:[1,0,0] op_sel_hi:[1,1,1]
	v_pk_fma_f32 v[16:17], v[92:93], v[156:157], v[10:11] op_sel:[0,1,0] op_sel_hi:[1,1,1]
	v_pk_fma_f32 v[18:19], v[94:95], v[156:157], v[8:9] op_sel:[0,1,0] op_sel_hi:[1,1,1]
	v_add_f32_dpp v15, v24, v24 row_ror:8 row_mask:0xf bank_mask:0xf bound_ctrl:1
	ds_read_b128 v[124:127], v48 offset:11264
	s_nop 0
	v_add_f32_dpp v15, v15, v15 row_ror:4 row_mask:0xf bank_mask:0xf bound_ctrl:1
	ds_read_b128 v[128:131], v48 offset:11520
	ds_read_b128 v[132:135], v48 offset:11776
	v_add_f32_dpp v15, v15, v15 row_ror:2 row_mask:0xf bank_mask:0xf bound_ctrl:1
	ds_read_b128 v[136:139], v48 offset:12032
	ds_read_b128 v[160:163], v49 offset:48
	v_add_f32_dpp v30, v15, v15 row_ror:1 row_mask:0xf bank_mask:0xf bound_ctrl:1
	v_pk_fma_f32 v[10:11], v[96:97], v[30:31], v[16:17] op_sel_hi:[1,0,1] neg_lo:[0,1,0] neg_hi:[0,1,0]
	v_pk_fma_f32 v[8:9], v[98:99], v[30:31], v[18:19] op_sel_hi:[1,0,1] neg_lo:[0,1,0] neg_hi:[0,1,0]
	v_pk_mul_f32 v[26:27], v[10:11], v[100:101] op_sel:[0,0] op_sel_hi:[0,1]
	v_pk_fma_f32 v[26:27], v[10:11], v[102:103], v[26:27] op_sel:[1,0,0] op_sel_hi:[1,1,1]
	v_pk_fma_f32 v[26:27], v[8:9], v[104:105], v[26:27] op_sel:[0,0,0] op_sel_hi:[0,1,1]
	v_pk_fma_f32 v[26:27], v[8:9], v[106:107], v[26:27] op_sel:[1,0,0] op_sel_hi:[1,1,1]
	v_pk_fma_f32 v[16:17], v[108:109], v[158:159], v[10:11] op_sel_hi:[1,0,1]
	v_pk_fma_f32 v[18:19], v[110:111], v[158:159], v[8:9] op_sel_hi:[1,0,1]
	v_add_f32_dpp v15, v26, v26 row_ror:8 row_mask:0xf bank_mask:0xf bound_ctrl:1
	ds_read_b128 v[76:79], v48 offset:12288
	s_nop 0
	v_add_f32_dpp v15, v15, v15 row_ror:4 row_mask:0xf bank_mask:0xf bound_ctrl:1
	ds_read_b128 v[80:83], v48 offset:12544
	ds_read_b128 v[84:87], v48 offset:12800
	v_add_f32_dpp v15, v15, v15 row_ror:2 row_mask:0xf bank_mask:0xf bound_ctrl:1
	ds_read_b128 v[88:91], v48 offset:13056
	ds_write2st64_b32 v50, v25, v27 offset0:32 offset1:36
	v_add_f32_dpp v30, v15, v15 row_ror:1 row_mask:0xf bank_mask:0xf bound_ctrl:1
	s_waitcnt lgkmcnt(4)
	v_pk_fma_f32 v[10:11], v[112:113], v[30:31], v[16:17] op_sel_hi:[1,0,1] neg_lo:[0,1,0] neg_hi:[0,1,0]
	v_pk_fma_f32 v[8:9], v[114:115], v[30:31], v[18:19] op_sel_hi:[1,0,1] neg_lo:[0,1,0] neg_hi:[0,1,0]
	v_pk_mul_f32 v[24:25], v[10:11], v[116:117] op_sel:[0,0] op_sel_hi:[0,1]
	v_pk_fma_f32 v[24:25], v[10:11], v[118:119], v[24:25] op_sel:[1,0,0] op_sel_hi:[1,1,1]
	v_pk_fma_f32 v[24:25], v[8:9], v[120:121], v[24:25] op_sel:[0,0,0] op_sel_hi:[0,1,1]
	v_pk_fma_f32 v[24:25], v[8:9], v[122:123], v[24:25] op_sel:[1,0,0] op_sel_hi:[1,1,1]
	v_pk_fma_f32 v[16:17], v[124:125], v[158:159], v[10:11] op_sel:[0,1,0] op_sel_hi:[1,1,1]
	v_pk_fma_f32 v[18:19], v[126:127], v[158:159], v[8:9] op_sel:[0,1,0] op_sel_hi:[1,1,1]
	v_add_f32_dpp v15, v24, v24 row_ror:8 row_mask:0xf bank_mask:0xf bound_ctrl:1
	ds_read_b128 v[92:95], v48 offset:13312
	s_nop 0
	v_add_f32_dpp v15, v15, v15 row_ror:4 row_mask:0xf bank_mask:0xf bound_ctrl:1
	ds_read_b128 v[96:99], v48 offset:13568
	ds_read_b128 v[100:103], v48 offset:13824
	v_add_f32_dpp v15, v15, v15 row_ror:2 row_mask:0xf bank_mask:0xf bound_ctrl:1
	ds_read_b128 v[104:107], v48 offset:14080
	s_nop 0
	v_add_f32_dpp v30, v15, v15 row_ror:1 row_mask:0xf bank_mask:0xf bound_ctrl:1
	v_pk_fma_f32 v[10:11], v[128:129], v[30:31], v[16:17] op_sel_hi:[1,0,1] neg_lo:[0,1,0] neg_hi:[0,1,0]
	v_pk_fma_f32 v[8:9], v[130:131], v[30:31], v[18:19] op_sel_hi:[1,0,1] neg_lo:[0,1,0] neg_hi:[0,1,0]
	v_pk_mul_f32 v[26:27], v[10:11], v[132:133] op_sel:[0,0] op_sel_hi:[0,1]
	v_pk_fma_f32 v[26:27], v[10:11], v[134:135], v[26:27] op_sel:[1,0,0] op_sel_hi:[1,1,1]
	v_pk_fma_f32 v[26:27], v[8:9], v[136:137], v[26:27] op_sel:[0,0,0] op_sel_hi:[0,1,1]
	v_pk_fma_f32 v[26:27], v[8:9], v[138:139], v[26:27] op_sel:[1,0,0] op_sel_hi:[1,1,1]
	v_pk_fma_f32 v[16:17], v[76:77], v[160:161], v[10:11] op_sel_hi:[1,0,1]
	v_pk_fma_f32 v[18:19], v[78:79], v[160:161], v[8:9] op_sel_hi:[1,0,1]
	v_add_f32_dpp v15, v26, v26 row_ror:8 row_mask:0xf bank_mask:0xf bound_ctrl:1
	ds_read_b128 v[108:111], v48 offset:14336
	s_nop 0
	v_add_f32_dpp v15, v15, v15 row_ror:4 row_mask:0xf bank_mask:0xf bound_ctrl:1
	ds_read_b128 v[112:115], v48 offset:14592
	ds_read_b128 v[116:119], v48 offset:14848
	v_add_f32_dpp v15, v15, v15 row_ror:2 row_mask:0xf bank_mask:0xf bound_ctrl:1
	ds_read_b128 v[120:123], v48 offset:15104
	ds_read_b128 v[140:143], v48 offset:34048
	ds_write2st64_b32 v50, v25, v27 offset0:40 offset1:44
	v_add_f32_dpp v30, v15, v15 row_ror:1 row_mask:0xf bank_mask:0xf bound_ctrl:1
	s_waitcnt lgkmcnt(5)
	v_pk_fma_f32 v[10:11], v[80:81], v[30:31], v[16:17] op_sel_hi:[1,0,1] neg_lo:[0,1,0] neg_hi:[0,1,0]
	v_pk_fma_f32 v[8:9], v[82:83], v[30:31], v[18:19] op_sel_hi:[1,0,1] neg_lo:[0,1,0] neg_hi:[0,1,0]
	v_pk_mul_f32 v[24:25], v[10:11], v[84:85] op_sel:[0,0] op_sel_hi:[0,1]
	v_pk_fma_f32 v[24:25], v[10:11], v[86:87], v[24:25] op_sel:[1,0,0] op_sel_hi:[1,1,1]
	v_pk_fma_f32 v[24:25], v[8:9], v[88:89], v[24:25] op_sel:[0,0,0] op_sel_hi:[0,1,1]
	v_pk_fma_f32 v[24:25], v[8:9], v[90:91], v[24:25] op_sel:[1,0,0] op_sel_hi:[1,1,1]
	v_pk_fma_f32 v[16:17], v[92:93], v[160:161], v[10:11] op_sel:[0,1,0] op_sel_hi:[1,1,1]
	v_pk_fma_f32 v[18:19], v[94:95], v[160:161], v[8:9] op_sel:[0,1,0] op_sel_hi:[1,1,1]
	v_add_f32_dpp v15, v24, v24 row_ror:8 row_mask:0xf bank_mask:0xf bound_ctrl:1
	ds_read_b128 v[124:127], v48 offset:15360
	s_nop 0
	v_add_f32_dpp v15, v15, v15 row_ror:4 row_mask:0xf bank_mask:0xf bound_ctrl:1
	ds_read_b128 v[128:131], v48 offset:15616
	ds_read_b128 v[132:135], v48 offset:15872
	v_add_f32_dpp v15, v15, v15 row_ror:2 row_mask:0xf bank_mask:0xf bound_ctrl:1
	ds_read_b128 v[136:139], v48 offset:16128
	ds_read_b128 v[156:159], v49 offset:64
	v_add_f32_dpp v30, v15, v15 row_ror:1 row_mask:0xf bank_mask:0xf bound_ctrl:1
	v_pk_fma_f32 v[10:11], v[96:97], v[30:31], v[16:17] op_sel_hi:[1,0,1] neg_lo:[0,1,0] neg_hi:[0,1,0]
	v_pk_fma_f32 v[8:9], v[98:99], v[30:31], v[18:19] op_sel_hi:[1,0,1] neg_lo:[0,1,0] neg_hi:[0,1,0]
	v_pk_mul_f32 v[26:27], v[10:11], v[100:101] op_sel:[0,0] op_sel_hi:[0,1]
	v_pk_fma_f32 v[26:27], v[10:11], v[102:103], v[26:27] op_sel:[1,0,0] op_sel_hi:[1,1,1]
	v_pk_fma_f32 v[26:27], v[8:9], v[104:105], v[26:27] op_sel:[0,0,0] op_sel_hi:[0,1,1]
	v_pk_fma_f32 v[26:27], v[8:9], v[106:107], v[26:27] op_sel:[1,0,0] op_sel_hi:[1,1,1]
	v_pk_fma_f32 v[16:17], v[108:109], v[162:163], v[10:11] op_sel_hi:[1,0,1]
	v_pk_fma_f32 v[18:19], v[110:111], v[162:163], v[8:9] op_sel_hi:[1,0,1]
	v_add_f32_dpp v15, v26, v26 row_ror:8 row_mask:0xf bank_mask:0xf bound_ctrl:1
	ds_read_b128 v[76:79], v48 offset:16384
	s_nop 0
	v_add_f32_dpp v15, v15, v15 row_ror:4 row_mask:0xf bank_mask:0xf bound_ctrl:1
	ds_read_b128 v[80:83], v48 offset:16640
	ds_read_b128 v[84:87], v48 offset:16896
	v_add_f32_dpp v15, v15, v15 row_ror:2 row_mask:0xf bank_mask:0xf bound_ctrl:1
	ds_read_b128 v[88:91], v48 offset:17152
	ds_read_b128 v[144:147], v48 offset:33280
	ds_write2st64_b32 v50, v25, v27 offset0:48 offset1:52
	v_add_f32_dpp v30, v15, v15 row_ror:1 row_mask:0xf bank_mask:0xf bound_ctrl:1
	s_waitcnt lgkmcnt(5)
	v_pk_fma_f32 v[10:11], v[112:113], v[30:31], v[16:17] op_sel_hi:[1,0,1] neg_lo:[0,1,0] neg_hi:[0,1,0]
	v_pk_fma_f32 v[8:9], v[114:115], v[30:31], v[18:19] op_sel_hi:[1,0,1] neg_lo:[0,1,0] neg_hi:[0,1,0]
	v_pk_mul_f32 v[24:25], v[10:11], v[116:117] op_sel:[0,0] op_sel_hi:[0,1]
	v_pk_fma_f32 v[24:25], v[10:11], v[118:119], v[24:25] op_sel:[1,0,0] op_sel_hi:[1,1,1]
	v_pk_fma_f32 v[24:25], v[8:9], v[120:121], v[24:25] op_sel:[0,0,0] op_sel_hi:[0,1,1]
	v_pk_fma_f32 v[24:25], v[8:9], v[122:123], v[24:25] op_sel:[1,0,0] op_sel_hi:[1,1,1]
	v_pk_fma_f32 v[16:17], v[124:125], v[162:163], v[10:11] op_sel:[0,1,0] op_sel_hi:[1,1,1]
	v_pk_fma_f32 v[18:19], v[126:127], v[162:163], v[8:9] op_sel:[0,1,0] op_sel_hi:[1,1,1]
	v_add_f32_dpp v15, v24, v24 row_ror:8 row_mask:0xf bank_mask:0xf bound_ctrl:1
	ds_read_b128 v[92:95], v48 offset:17408
	s_nop 0
	v_add_f32_dpp v15, v15, v15 row_ror:4 row_mask:0xf bank_mask:0xf bound_ctrl:1
	ds_read_b128 v[96:99], v48 offset:17664
	ds_read_b128 v[100:103], v48 offset:17920
	v_add_f32_dpp v15, v15, v15 row_ror:2 row_mask:0xf bank_mask:0xf bound_ctrl:1
	ds_read_b128 v[104:107], v48 offset:18176
	s_nop 0
	v_add_f32_dpp v30, v15, v15 row_ror:1 row_mask:0xf bank_mask:0xf bound_ctrl:1
	v_pk_fma_f32 v[10:11], v[128:129], v[30:31], v[16:17] op_sel_hi:[1,0,1] neg_lo:[0,1,0] neg_hi:[0,1,0]
	v_pk_fma_f32 v[8:9], v[130:131], v[30:31], v[18:19] op_sel_hi:[1,0,1] neg_lo:[0,1,0] neg_hi:[0,1,0]
	v_pk_mul_f32 v[26:27], v[10:11], v[132:133] op_sel:[0,0] op_sel_hi:[0,1]
	v_pk_fma_f32 v[26:27], v[10:11], v[134:135], v[26:27] op_sel:[1,0,0] op_sel_hi:[1,1,1]
	v_pk_fma_f32 v[26:27], v[8:9], v[136:137], v[26:27] op_sel:[0,0,0] op_sel_hi:[0,1,1]
	v_pk_fma_f32 v[26:27], v[8:9], v[138:139], v[26:27] op_sel:[1,0,0] op_sel_hi:[1,1,1]
	ds_write2st64_b32 v50, v25, v27 offset0:56 offset1:60
	v_pk_mul_f32 v[10:11], v[10:11], v[140:141]
	v_pk_mul_f32 v[8:9], v[8:9], v[142:143]
	s_waitcnt lgkmcnt(6)
	v_pk_mul_f32 v[24:25], v[10:11], v[144:145]
	v_pk_fma_f32 v[24:25], v[8:9], v[146:147], v[24:25]
	v_add_f32_e32 v24, v24, v25
	v_pk_fma_f32 v[16:17], v[76:77], v[156:157], v[10:11] op_sel_hi:[1,0,1]
	v_pk_fma_f32 v[18:19], v[78:79], v[156:157], v[8:9] op_sel_hi:[1,0,1]
	v_add_f32_dpp v15, v24, v24 row_ror:8 row_mask:0xf bank_mask:0xf bound_ctrl:1
	ds_read_b128 v[108:111], v48 offset:18432
	ds_read_b128 v[112:115], v48 offset:18688
	v_add_f32_dpp v15, v15, v15 row_ror:4 row_mask:0xf bank_mask:0xf bound_ctrl:1
	ds_read_b128 v[116:119], v48 offset:18944
	ds_read_b128 v[120:123], v48 offset:19200
	v_add_f32_dpp v15, v15, v15 row_ror:2 row_mask:0xf bank_mask:0xf bound_ctrl:1
	s_nop 1
	v_add_f32_dpp v30, v15, v15 row_ror:1 row_mask:0xf bank_mask:0xf bound_ctrl:1
	s_waitcnt lgkmcnt(3)
	v_pk_fma_f32 v[10:11], v[80:81], v[30:31], v[16:17] op_sel_hi:[1,0,1] neg_lo:[0,1,0] neg_hi:[0,1,0]
	v_pk_fma_f32 v[8:9], v[82:83], v[30:31], v[18:19] op_sel_hi:[1,0,1] neg_lo:[0,1,0] neg_hi:[0,1,0]
	v_pk_mul_f32 v[24:25], v[10:11], v[84:85] op_sel:[0,0] op_sel_hi:[0,1]
	v_pk_fma_f32 v[24:25], v[10:11], v[86:87], v[24:25] op_sel:[1,0,0] op_sel_hi:[1,1,1]
	v_pk_fma_f32 v[24:25], v[8:9], v[88:89], v[24:25] op_sel:[0,0,0] op_sel_hi:[0,1,1]
	v_pk_fma_f32 v[24:25], v[8:9], v[90:91], v[24:25] op_sel:[1,0,0] op_sel_hi:[1,1,1]
	v_pk_fma_f32 v[16:17], v[92:93], v[156:157], v[10:11] op_sel:[0,1,0] op_sel_hi:[1,1,1]
	v_pk_fma_f32 v[18:19], v[94:95], v[156:157], v[8:9] op_sel:[0,1,0] op_sel_hi:[1,1,1]
	v_add_f32_dpp v15, v24, v24 row_ror:8 row_mask:0xf bank_mask:0xf bound_ctrl:1
	ds_read_b128 v[124:127], v48 offset:19456
	s_nop 0
	v_add_f32_dpp v15, v15, v15 row_ror:4 row_mask:0xf bank_mask:0xf bound_ctrl:1
	ds_read_b128 v[128:131], v48 offset:19712
	ds_read_b128 v[132:135], v48 offset:19968
	v_add_f32_dpp v15, v15, v15 row_ror:2 row_mask:0xf bank_mask:0xf bound_ctrl:1
	ds_read_b128 v[136:139], v48 offset:20224
	ds_read_b128 v[160:163], v49 offset:80
	v_add_f32_dpp v30, v15, v15 row_ror:1 row_mask:0xf bank_mask:0xf bound_ctrl:1
	v_pk_fma_f32 v[10:11], v[96:97], v[30:31], v[16:17] op_sel_hi:[1,0,1] neg_lo:[0,1,0] neg_hi:[0,1,0]
	v_pk_fma_f32 v[8:9], v[98:99], v[30:31], v[18:19] op_sel_hi:[1,0,1] neg_lo:[0,1,0] neg_hi:[0,1,0]
	v_pk_mul_f32 v[26:27], v[10:11], v[100:101] op_sel:[0,0] op_sel_hi:[0,1]
	v_pk_fma_f32 v[26:27], v[10:11], v[102:103], v[26:27] op_sel:[1,0,0] op_sel_hi:[1,1,1]
	v_pk_fma_f32 v[26:27], v[8:9], v[104:105], v[26:27] op_sel:[0,0,0] op_sel_hi:[0,1,1]
	v_pk_fma_f32 v[26:27], v[8:9], v[106:107], v[26:27] op_sel:[1,0,0] op_sel_hi:[1,1,1]
	v_pk_fma_f32 v[16:17], v[108:109], v[158:159], v[10:11] op_sel_hi:[1,0,1]
	v_pk_fma_f32 v[18:19], v[110:111], v[158:159], v[8:9] op_sel_hi:[1,0,1]
	v_add_f32_dpp v15, v26, v26 row_ror:8 row_mask:0xf bank_mask:0xf bound_ctrl:1
	ds_read_b128 v[76:79], v48 offset:20480
	s_nop 0
	v_add_f32_dpp v15, v15, v15 row_ror:4 row_mask:0xf bank_mask:0xf bound_ctrl:1
	ds_read_b128 v[80:83], v48 offset:20736
	ds_read_b128 v[84:87], v48 offset:20992
	v_add_f32_dpp v15, v15, v15 row_ror:2 row_mask:0xf bank_mask:0xf bound_ctrl:1
	ds_read_b128 v[88:91], v48 offset:21248
	ds_write2st64_b32 v50, v25, v27 offset0:64 offset1:68
	v_add_f32_dpp v30, v15, v15 row_ror:1 row_mask:0xf bank_mask:0xf bound_ctrl:1
	s_waitcnt lgkmcnt(4)
	v_pk_fma_f32 v[10:11], v[112:113], v[30:31], v[16:17] op_sel_hi:[1,0,1] neg_lo:[0,1,0] neg_hi:[0,1,0]
	v_pk_fma_f32 v[8:9], v[114:115], v[30:31], v[18:19] op_sel_hi:[1,0,1] neg_lo:[0,1,0] neg_hi:[0,1,0]
	v_pk_mul_f32 v[24:25], v[10:11], v[116:117] op_sel:[0,0] op_sel_hi:[0,1]
	v_pk_fma_f32 v[24:25], v[10:11], v[118:119], v[24:25] op_sel:[1,0,0] op_sel_hi:[1,1,1]
	v_pk_fma_f32 v[24:25], v[8:9], v[120:121], v[24:25] op_sel:[0,0,0] op_sel_hi:[0,1,1]
	v_pk_fma_f32 v[24:25], v[8:9], v[122:123], v[24:25] op_sel:[1,0,0] op_sel_hi:[1,1,1]
	v_pk_fma_f32 v[16:17], v[124:125], v[158:159], v[10:11] op_sel:[0,1,0] op_sel_hi:[1,1,1]
	v_pk_fma_f32 v[18:19], v[126:127], v[158:159], v[8:9] op_sel:[0,1,0] op_sel_hi:[1,1,1]
	v_add_f32_dpp v15, v24, v24 row_ror:8 row_mask:0xf bank_mask:0xf bound_ctrl:1
	ds_read_b128 v[92:95], v48 offset:21504
	s_nop 0
	v_add_f32_dpp v15, v15, v15 row_ror:4 row_mask:0xf bank_mask:0xf bound_ctrl:1
	ds_read_b128 v[96:99], v48 offset:21760
	ds_read_b128 v[100:103], v48 offset:22016
	v_add_f32_dpp v15, v15, v15 row_ror:2 row_mask:0xf bank_mask:0xf bound_ctrl:1
	ds_read_b128 v[104:107], v48 offset:22272
	s_nop 0
	v_add_f32_dpp v30, v15, v15 row_ror:1 row_mask:0xf bank_mask:0xf bound_ctrl:1
	v_pk_fma_f32 v[10:11], v[128:129], v[30:31], v[16:17] op_sel_hi:[1,0,1] neg_lo:[0,1,0] neg_hi:[0,1,0]
	v_pk_fma_f32 v[8:9], v[130:131], v[30:31], v[18:19] op_sel_hi:[1,0,1] neg_lo:[0,1,0] neg_hi:[0,1,0]
	v_pk_mul_f32 v[26:27], v[10:11], v[132:133] op_sel:[0,0] op_sel_hi:[0,1]
	v_pk_fma_f32 v[26:27], v[10:11], v[134:135], v[26:27] op_sel:[1,0,0] op_sel_hi:[1,1,1]
	v_pk_fma_f32 v[26:27], v[8:9], v[136:137], v[26:27] op_sel:[0,0,0] op_sel_hi:[0,1,1]
	v_pk_fma_f32 v[26:27], v[8:9], v[138:139], v[26:27] op_sel:[1,0,0] op_sel_hi:[1,1,1]
	v_pk_fma_f32 v[16:17], v[76:77], v[160:161], v[10:11] op_sel_hi:[1,0,1]
	v_pk_fma_f32 v[18:19], v[78:79], v[160:161], v[8:9] op_sel_hi:[1,0,1]
	v_add_f32_dpp v15, v26, v26 row_ror:8 row_mask:0xf bank_mask:0xf bound_ctrl:1
	ds_read_b128 v[108:111], v48 offset:22528
	s_nop 0
	v_add_f32_dpp v15, v15, v15 row_ror:4 row_mask:0xf bank_mask:0xf bound_ctrl:1
	ds_read_b128 v[112:115], v48 offset:22784
	ds_read_b128 v[116:119], v48 offset:23040
	v_add_f32_dpp v15, v15, v15 row_ror:2 row_mask:0xf bank_mask:0xf bound_ctrl:1
	ds_read_b128 v[120:123], v48 offset:23296
	ds_read_b128 v[140:143], v48 offset:34304
	ds_write2st64_b32 v50, v25, v27 offset0:72 offset1:76
	v_add_f32_dpp v30, v15, v15 row_ror:1 row_mask:0xf bank_mask:0xf bound_ctrl:1
	s_waitcnt lgkmcnt(5)
	v_pk_fma_f32 v[10:11], v[80:81], v[30:31], v[16:17] op_sel_hi:[1,0,1] neg_lo:[0,1,0] neg_hi:[0,1,0]
	v_pk_fma_f32 v[8:9], v[82:83], v[30:31], v[18:19] op_sel_hi:[1,0,1] neg_lo:[0,1,0] neg_hi:[0,1,0]
	v_pk_mul_f32 v[24:25], v[10:11], v[84:85] op_sel:[0,0] op_sel_hi:[0,1]
	v_pk_fma_f32 v[24:25], v[10:11], v[86:87], v[24:25] op_sel:[1,0,0] op_sel_hi:[1,1,1]
	v_pk_fma_f32 v[24:25], v[8:9], v[88:89], v[24:25] op_sel:[0,0,0] op_sel_hi:[0,1,1]
	v_pk_fma_f32 v[24:25], v[8:9], v[90:91], v[24:25] op_sel:[1,0,0] op_sel_hi:[1,1,1]
	v_pk_fma_f32 v[16:17], v[92:93], v[160:161], v[10:11] op_sel:[0,1,0] op_sel_hi:[1,1,1]
	v_pk_fma_f32 v[18:19], v[94:95], v[160:161], v[8:9] op_sel:[0,1,0] op_sel_hi:[1,1,1]
	v_add_f32_dpp v15, v24, v24 row_ror:8 row_mask:0xf bank_mask:0xf bound_ctrl:1
	ds_read_b128 v[124:127], v48 offset:23552
	s_nop 0
	v_add_f32_dpp v15, v15, v15 row_ror:4 row_mask:0xf bank_mask:0xf bound_ctrl:1
	ds_read_b128 v[128:131], v48 offset:23808
	ds_read_b128 v[132:135], v48 offset:24064
	v_add_f32_dpp v15, v15, v15 row_ror:2 row_mask:0xf bank_mask:0xf bound_ctrl:1
	ds_read_b128 v[136:139], v48 offset:24320
	ds_read_b128 v[156:159], v49 offset:96
	v_add_f32_dpp v30, v15, v15 row_ror:1 row_mask:0xf bank_mask:0xf bound_ctrl:1
	v_pk_fma_f32 v[10:11], v[96:97], v[30:31], v[16:17] op_sel_hi:[1,0,1] neg_lo:[0,1,0] neg_hi:[0,1,0]
	v_pk_fma_f32 v[8:9], v[98:99], v[30:31], v[18:19] op_sel_hi:[1,0,1] neg_lo:[0,1,0] neg_hi:[0,1,0]
	v_pk_mul_f32 v[26:27], v[10:11], v[100:101] op_sel:[0,0] op_sel_hi:[0,1]
	v_pk_fma_f32 v[26:27], v[10:11], v[102:103], v[26:27] op_sel:[1,0,0] op_sel_hi:[1,1,1]
	v_pk_fma_f32 v[26:27], v[8:9], v[104:105], v[26:27] op_sel:[0,0,0] op_sel_hi:[0,1,1]
	v_pk_fma_f32 v[26:27], v[8:9], v[106:107], v[26:27] op_sel:[1,0,0] op_sel_hi:[1,1,1]
	v_pk_fma_f32 v[16:17], v[108:109], v[162:163], v[10:11] op_sel_hi:[1,0,1]
	v_pk_fma_f32 v[18:19], v[110:111], v[162:163], v[8:9] op_sel_hi:[1,0,1]
	v_add_f32_dpp v15, v26, v26 row_ror:8 row_mask:0xf bank_mask:0xf bound_ctrl:1
	ds_read_b128 v[76:79], v48 offset:24576
	s_nop 0
	v_add_f32_dpp v15, v15, v15 row_ror:4 row_mask:0xf bank_mask:0xf bound_ctrl:1
	ds_read_b128 v[80:83], v48 offset:24832
	ds_read_b128 v[84:87], v48 offset:25088
	v_add_f32_dpp v15, v15, v15 row_ror:2 row_mask:0xf bank_mask:0xf bound_ctrl:1
	ds_read_b128 v[88:91], v48 offset:25344
	ds_read_b128 v[144:147], v48 offset:33536
	ds_write2st64_b32 v50, v25, v27 offset0:80 offset1:84
	v_add_f32_dpp v30, v15, v15 row_ror:1 row_mask:0xf bank_mask:0xf bound_ctrl:1
	s_waitcnt lgkmcnt(5)
	v_pk_fma_f32 v[10:11], v[112:113], v[30:31], v[16:17] op_sel_hi:[1,0,1] neg_lo:[0,1,0] neg_hi:[0,1,0]
	v_pk_fma_f32 v[8:9], v[114:115], v[30:31], v[18:19] op_sel_hi:[1,0,1] neg_lo:[0,1,0] neg_hi:[0,1,0]
	v_pk_mul_f32 v[24:25], v[10:11], v[116:117] op_sel:[0,0] op_sel_hi:[0,1]
	v_pk_fma_f32 v[24:25], v[10:11], v[118:119], v[24:25] op_sel:[1,0,0] op_sel_hi:[1,1,1]
	v_pk_fma_f32 v[24:25], v[8:9], v[120:121], v[24:25] op_sel:[0,0,0] op_sel_hi:[0,1,1]
	v_pk_fma_f32 v[24:25], v[8:9], v[122:123], v[24:25] op_sel:[1,0,0] op_sel_hi:[1,1,1]
	v_pk_fma_f32 v[16:17], v[124:125], v[162:163], v[10:11] op_sel:[0,1,0] op_sel_hi:[1,1,1]
	v_pk_fma_f32 v[18:19], v[126:127], v[162:163], v[8:9] op_sel:[0,1,0] op_sel_hi:[1,1,1]
	v_add_f32_dpp v15, v24, v24 row_ror:8 row_mask:0xf bank_mask:0xf bound_ctrl:1
	ds_read_b128 v[92:95], v48 offset:25600
	s_nop 0
	v_add_f32_dpp v15, v15, v15 row_ror:4 row_mask:0xf bank_mask:0xf bound_ctrl:1
	ds_read_b128 v[96:99], v48 offset:25856
	ds_read_b128 v[100:103], v48 offset:26112
	v_add_f32_dpp v15, v15, v15 row_ror:2 row_mask:0xf bank_mask:0xf bound_ctrl:1
	ds_read_b128 v[104:107], v48 offset:26368
	s_nop 0
	v_add_f32_dpp v30, v15, v15 row_ror:1 row_mask:0xf bank_mask:0xf bound_ctrl:1
	v_pk_fma_f32 v[10:11], v[128:129], v[30:31], v[16:17] op_sel_hi:[1,0,1] neg_lo:[0,1,0] neg_hi:[0,1,0]
	v_pk_fma_f32 v[8:9], v[130:131], v[30:31], v[18:19] op_sel_hi:[1,0,1] neg_lo:[0,1,0] neg_hi:[0,1,0]
	v_pk_mul_f32 v[26:27], v[10:11], v[132:133] op_sel:[0,0] op_sel_hi:[0,1]
	v_pk_fma_f32 v[26:27], v[10:11], v[134:135], v[26:27] op_sel:[1,0,0] op_sel_hi:[1,1,1]
	v_pk_fma_f32 v[26:27], v[8:9], v[136:137], v[26:27] op_sel:[0,0,0] op_sel_hi:[0,1,1]
	v_pk_fma_f32 v[26:27], v[8:9], v[138:139], v[26:27] op_sel:[1,0,0] op_sel_hi:[1,1,1]
	ds_write2st64_b32 v50, v25, v27 offset0:88 offset1:92
	v_pk_mul_f32 v[10:11], v[10:11], v[140:141]
	v_pk_mul_f32 v[8:9], v[8:9], v[142:143]
	s_waitcnt lgkmcnt(6)
	v_pk_mul_f32 v[24:25], v[10:11], v[144:145]
	v_pk_fma_f32 v[24:25], v[8:9], v[146:147], v[24:25]
	v_add_f32_e32 v24, v24, v25
	v_pk_fma_f32 v[16:17], v[76:77], v[156:157], v[10:11] op_sel_hi:[1,0,1]
	v_pk_fma_f32 v[18:19], v[78:79], v[156:157], v[8:9] op_sel_hi:[1,0,1]
	v_add_f32_dpp v15, v24, v24 row_ror:8 row_mask:0xf bank_mask:0xf bound_ctrl:1
	ds_read_b128 v[108:111], v48 offset:26624
	ds_read_b128 v[112:115], v48 offset:26880
	v_add_f32_dpp v15, v15, v15 row_ror:4 row_mask:0xf bank_mask:0xf bound_ctrl:1
	ds_read_b128 v[116:119], v48 offset:27136
	ds_read_b128 v[120:123], v48 offset:27392
	v_add_f32_dpp v15, v15, v15 row_ror:2 row_mask:0xf bank_mask:0xf bound_ctrl:1
	s_nop 1
	v_add_f32_dpp v30, v15, v15 row_ror:1 row_mask:0xf bank_mask:0xf bound_ctrl:1
	s_waitcnt lgkmcnt(3)
	v_pk_fma_f32 v[10:11], v[80:81], v[30:31], v[16:17] op_sel_hi:[1,0,1] neg_lo:[0,1,0] neg_hi:[0,1,0]
	v_pk_fma_f32 v[8:9], v[82:83], v[30:31], v[18:19] op_sel_hi:[1,0,1] neg_lo:[0,1,0] neg_hi:[0,1,0]
	v_pk_mul_f32 v[24:25], v[10:11], v[84:85] op_sel:[0,0] op_sel_hi:[0,1]
	v_pk_fma_f32 v[24:25], v[10:11], v[86:87], v[24:25] op_sel:[1,0,0] op_sel_hi:[1,1,1]
	v_pk_fma_f32 v[24:25], v[8:9], v[88:89], v[24:25] op_sel:[0,0,0] op_sel_hi:[0,1,1]
	v_pk_fma_f32 v[24:25], v[8:9], v[90:91], v[24:25] op_sel:[1,0,0] op_sel_hi:[1,1,1]
	v_pk_fma_f32 v[16:17], v[92:93], v[156:157], v[10:11] op_sel:[0,1,0] op_sel_hi:[1,1,1]
	v_pk_fma_f32 v[18:19], v[94:95], v[156:157], v[8:9] op_sel:[0,1,0] op_sel_hi:[1,1,1]
	v_add_f32_dpp v15, v24, v24 row_ror:8 row_mask:0xf bank_mask:0xf bound_ctrl:1
	ds_read_b128 v[124:127], v48 offset:27648
	s_nop 0
	v_add_f32_dpp v15, v15, v15 row_ror:4 row_mask:0xf bank_mask:0xf bound_ctrl:1
	ds_read_b128 v[128:131], v48 offset:27904
	ds_read_b128 v[132:135], v48 offset:28160
	v_add_f32_dpp v15, v15, v15 row_ror:2 row_mask:0xf bank_mask:0xf bound_ctrl:1
	ds_read_b128 v[136:139], v48 offset:28416
	ds_read_b128 v[160:163], v49 offset:112
	v_add_f32_dpp v30, v15, v15 row_ror:1 row_mask:0xf bank_mask:0xf bound_ctrl:1
	v_pk_fma_f32 v[10:11], v[96:97], v[30:31], v[16:17] op_sel_hi:[1,0,1] neg_lo:[0,1,0] neg_hi:[0,1,0]
	v_pk_fma_f32 v[8:9], v[98:99], v[30:31], v[18:19] op_sel_hi:[1,0,1] neg_lo:[0,1,0] neg_hi:[0,1,0]
	v_pk_mul_f32 v[26:27], v[10:11], v[100:101] op_sel:[0,0] op_sel_hi:[0,1]
	v_pk_fma_f32 v[26:27], v[10:11], v[102:103], v[26:27] op_sel:[1,0,0] op_sel_hi:[1,1,1]
	v_pk_fma_f32 v[26:27], v[8:9], v[104:105], v[26:27] op_sel:[0,0,0] op_sel_hi:[0,1,1]
	v_pk_fma_f32 v[26:27], v[8:9], v[106:107], v[26:27] op_sel:[1,0,0] op_sel_hi:[1,1,1]
	v_pk_fma_f32 v[16:17], v[108:109], v[158:159], v[10:11] op_sel_hi:[1,0,1]
	v_pk_fma_f32 v[18:19], v[110:111], v[158:159], v[8:9] op_sel_hi:[1,0,1]
	v_add_f32_dpp v15, v26, v26 row_ror:8 row_mask:0xf bank_mask:0xf bound_ctrl:1
	ds_read_b128 v[76:79], v48 offset:28672
	s_nop 0
	v_add_f32_dpp v15, v15, v15 row_ror:4 row_mask:0xf bank_mask:0xf bound_ctrl:1
	ds_read_b128 v[80:83], v48 offset:28928
	ds_read_b128 v[84:87], v48 offset:29184
	v_add_f32_dpp v15, v15, v15 row_ror:2 row_mask:0xf bank_mask:0xf bound_ctrl:1
	ds_read_b128 v[88:91], v48 offset:29440
	ds_write2st64_b32 v50, v25, v27 offset0:96 offset1:100
	v_add_f32_dpp v30, v15, v15 row_ror:1 row_mask:0xf bank_mask:0xf bound_ctrl:1
	ds_read_b128 v[56:59], v52
	s_waitcnt lgkmcnt(5)
	v_pk_fma_f32 v[10:11], v[112:113], v[30:31], v[16:17] op_sel_hi:[1,0,1] neg_lo:[0,1,0] neg_hi:[0,1,0]
	v_pk_fma_f32 v[8:9], v[114:115], v[30:31], v[18:19] op_sel_hi:[1,0,1] neg_lo:[0,1,0] neg_hi:[0,1,0]
	v_pk_mul_f32 v[24:25], v[10:11], v[116:117] op_sel:[0,0] op_sel_hi:[0,1]
	v_pk_fma_f32 v[24:25], v[10:11], v[118:119], v[24:25] op_sel:[1,0,0] op_sel_hi:[1,1,1]
	v_pk_fma_f32 v[24:25], v[8:9], v[120:121], v[24:25] op_sel:[0,0,0] op_sel_hi:[0,1,1]
	v_pk_fma_f32 v[24:25], v[8:9], v[122:123], v[24:25] op_sel:[1,0,0] op_sel_hi:[1,1,1]
	v_pk_fma_f32 v[16:17], v[124:125], v[158:159], v[10:11] op_sel:[0,1,0] op_sel_hi:[1,1,1]
	v_pk_fma_f32 v[18:19], v[126:127], v[158:159], v[8:9] op_sel:[0,1,0] op_sel_hi:[1,1,1]
	v_add_f32_dpp v15, v24, v24 row_ror:8 row_mask:0xf bank_mask:0xf bound_ctrl:1
	ds_read_b128 v[92:95], v48 offset:29696
	s_nop 0
	v_add_f32_dpp v15, v15, v15 row_ror:4 row_mask:0xf bank_mask:0xf bound_ctrl:1
	ds_read_b128 v[96:99], v48 offset:29952
	ds_read_b128 v[100:103], v48 offset:30208
	v_add_f32_dpp v15, v15, v15 row_ror:2 row_mask:0xf bank_mask:0xf bound_ctrl:1
	ds_read_b128 v[104:107], v48 offset:30464
	s_nop 0
	v_add_f32_dpp v30, v15, v15 row_ror:1 row_mask:0xf bank_mask:0xf bound_ctrl:1
	s_waitcnt lgkmcnt(4)
	v_min_u32_e32 v56, v56, v57
	v_min3_u32 v56, v56, v58, v59
	v_pk_fma_f32 v[10:11], v[128:129], v[30:31], v[16:17] op_sel_hi:[1,0,1] neg_lo:[0,1,0] neg_hi:[0,1,0]
	v_pk_fma_f32 v[8:9], v[130:131], v[30:31], v[18:19] op_sel_hi:[1,0,1] neg_lo:[0,1,0] neg_hi:[0,1,0]
	v_pk_mul_f32 v[26:27], v[10:11], v[132:133] op_sel:[0,0] op_sel_hi:[0,1]
	v_pk_fma_f32 v[26:27], v[10:11], v[134:135], v[26:27] op_sel:[1,0,0] op_sel_hi:[1,1,1]
	v_pk_fma_f32 v[26:27], v[8:9], v[136:137], v[26:27] op_sel:[0,0,0] op_sel_hi:[0,1,1]
	v_pk_fma_f32 v[26:27], v[8:9], v[138:139], v[26:27] op_sel:[1,0,0] op_sel_hi:[1,1,1]
	v_pk_fma_f32 v[16:17], v[76:77], v[160:161], v[10:11] op_sel_hi:[1,0,1]
	v_pk_fma_f32 v[18:19], v[78:79], v[160:161], v[8:9] op_sel_hi:[1,0,1]
	v_add_f32_dpp v15, v26, v26 row_ror:8 row_mask:0xf bank_mask:0xf bound_ctrl:1
	ds_read_b128 v[108:111], v48 offset:30720
	s_nop 0
	v_add_f32_dpp v15, v15, v15 row_ror:4 row_mask:0xf bank_mask:0xf bound_ctrl:1
	ds_read_b128 v[112:115], v48 offset:30976
	ds_read_b128 v[116:119], v48 offset:31232
	v_add_f32_dpp v15, v15, v15 row_ror:2 row_mask:0xf bank_mask:0xf bound_ctrl:1
	ds_read_b128 v[120:123], v48 offset:31488
	ds_read_b128 v[140:143], v48 offset:34560
	ds_write2st64_b32 v50, v25, v27 offset0:104 offset1:108
	v_add_f32_dpp v30, v15, v15 row_ror:1 row_mask:0xf bank_mask:0xf bound_ctrl:1
	s_waitcnt lgkmcnt(5)
	v_pk_fma_f32 v[10:11], v[80:81], v[30:31], v[16:17] op_sel_hi:[1,0,1] neg_lo:[0,1,0] neg_hi:[0,1,0]
	v_pk_fma_f32 v[8:9], v[82:83], v[30:31], v[18:19] op_sel_hi:[1,0,1] neg_lo:[0,1,0] neg_hi:[0,1,0]
	v_pk_mul_f32 v[24:25], v[10:11], v[84:85] op_sel:[0,0] op_sel_hi:[0,1]
	v_pk_fma_f32 v[24:25], v[10:11], v[86:87], v[24:25] op_sel:[1,0,0] op_sel_hi:[1,1,1]
	v_pk_fma_f32 v[24:25], v[8:9], v[88:89], v[24:25] op_sel:[0,0,0] op_sel_hi:[0,1,1]
	v_pk_fma_f32 v[24:25], v[8:9], v[90:91], v[24:25] op_sel:[1,0,0] op_sel_hi:[1,1,1]
	v_pk_fma_f32 v[16:17], v[92:93], v[160:161], v[10:11] op_sel:[0,1,0] op_sel_hi:[1,1,1]
	v_pk_fma_f32 v[18:19], v[94:95], v[160:161], v[8:9] op_sel:[0,1,0] op_sel_hi:[1,1,1]
	v_add_f32_dpp v15, v24, v24 row_ror:8 row_mask:0xf bank_mask:0xf bound_ctrl:1
	ds_read_b128 v[124:127], v48 offset:31744
	s_nop 0
	v_add_f32_dpp v15, v15, v15 row_ror:4 row_mask:0xf bank_mask:0xf bound_ctrl:1
	ds_read_b128 v[128:131], v48 offset:32000
	ds_read_b128 v[132:135], v48 offset:32256
	v_add_f32_dpp v15, v15, v15 row_ror:2 row_mask:0xf bank_mask:0xf bound_ctrl:1
	ds_read_b128 v[136:139], v48 offset:32512
	s_nop 0
	v_add_f32_dpp v30, v15, v15 row_ror:1 row_mask:0xf bank_mask:0xf bound_ctrl:1
	v_readfirstlane_b32 s54, v56
	s_add_u32 s64, s6, 2
	s_cmp_lt_u32 s54, s64
	s_cbranch_scc1 .Lss_spin_1
.Lss_ok_1:
	v_pk_fma_f32 v[10:11], v[96:97], v[30:31], v[16:17] op_sel_hi:[1,0,1] neg_lo:[0,1,0] neg_hi:[0,1,0]
	v_pk_fma_f32 v[8:9], v[98:99], v[30:31], v[18:19] op_sel_hi:[1,0,1] neg_lo:[0,1,0] neg_hi:[0,1,0]
	v_pk_mul_f32 v[26:27], v[10:11], v[100:101] op_sel:[0,0] op_sel_hi:[0,1]
	v_pk_fma_f32 v[26:27], v[10:11], v[102:103], v[26:27] op_sel:[1,0,0] op_sel_hi:[1,1,1]
	v_pk_fma_f32 v[26:27], v[8:9], v[104:105], v[26:27] op_sel:[0,0,0] op_sel_hi:[0,1,1]
	v_pk_fma_f32 v[26:27], v[8:9], v[106:107], v[26:27] op_sel:[1,0,0] op_sel_hi:[1,1,1]
	v_pk_fma_f32 v[16:17], v[108:109], v[162:163], v[10:11] op_sel_hi:[1,0,1]
	v_pk_fma_f32 v[18:19], v[110:111], v[162:163], v[8:9] op_sel_hi:[1,0,1]
	v_add_f32_dpp v15, v26, v26 row_ror:8 row_mask:0xf bank_mask:0xf bound_ctrl:1
	ds_read_b128 v[76:79], v34 offset:0
	s_nop 0
	v_add_f32_dpp v15, v15, v15 row_ror:4 row_mask:0xf bank_mask:0xf bound_ctrl:1
	ds_read_b128 v[80:83], v34 offset:256
	ds_read_b128 v[84:87], v34 offset:512
	v_add_f32_dpp v15, v15, v15 row_ror:2 row_mask:0xf bank_mask:0xf bound_ctrl:1
	ds_read_b128 v[88:91], v34 offset:768
	ds_read_b128 v[144:147], v34 offset:32768
	ds_write2st64_b32 v50, v25, v27 offset0:112 offset1:116
	v_add_f32_dpp v30, v15, v15 row_ror:1 row_mask:0xf bank_mask:0xf bound_ctrl:1
	ds_read_b128 v[156:159], v35 offset:0
	s_waitcnt lgkmcnt(6)
	v_pk_fma_f32 v[10:11], v[112:113], v[30:31], v[16:17] op_sel_hi:[1,0,1] neg_lo:[0,1,0] neg_hi:[0,1,0]
	v_pk_fma_f32 v[8:9], v[114:115], v[30:31], v[18:19] op_sel_hi:[1,0,1] neg_lo:[0,1,0] neg_hi:[0,1,0]
	v_pk_mul_f32 v[24:25], v[10:11], v[116:117] op_sel:[0,0] op_sel_hi:[0,1]
	v_pk_fma_f32 v[24:25], v[10:11], v[118:119], v[24:25] op_sel:[1,0,0] op_sel_hi:[1,1,1]
	v_pk_fma_f32 v[24:25], v[8:9], v[120:121], v[24:25] op_sel:[0,0,0] op_sel_hi:[0,1,1]
	v_pk_fma_f32 v[24:25], v[8:9], v[122:123], v[24:25] op_sel:[1,0,0] op_sel_hi:[1,1,1]
	v_pk_fma_f32 v[16:17], v[124:125], v[162:163], v[10:11] op_sel:[0,1,0] op_sel_hi:[1,1,1]
	v_pk_fma_f32 v[18:19], v[126:127], v[162:163], v[8:9] op_sel:[0,1,0] op_sel_hi:[1,1,1]
	v_add_f32_dpp v15, v24, v24 row_ror:8 row_mask:0xf bank_mask:0xf bound_ctrl:1
	ds_read_b128 v[92:95], v34 offset:1024
	s_nop 0
	v_add_f32_dpp v15, v15, v15 row_ror:4 row_mask:0xf bank_mask:0xf bound_ctrl:1
	ds_read_b128 v[96:99], v34 offset:1280
	ds_read_b128 v[100:103], v34 offset:1536
	v_add_f32_dpp v15, v15, v15 row_ror:2 row_mask:0xf bank_mask:0xf bound_ctrl:1
	ds_read_b128 v[104:107], v34 offset:1792
	s_nop 0
	v_add_f32_dpp v30, v15, v15 row_ror:1 row_mask:0xf bank_mask:0xf bound_ctrl:1
	v_pk_fma_f32 v[10:11], v[128:129], v[30:31], v[16:17] op_sel_hi:[1,0,1] neg_lo:[0,1,0] neg_hi:[0,1,0]
	v_pk_fma_f32 v[8:9], v[130:131], v[30:31], v[18:19] op_sel_hi:[1,0,1] neg_lo:[0,1,0] neg_hi:[0,1,0]
	v_pk_mul_f32 v[26:27], v[10:11], v[132:133] op_sel:[0,0] op_sel_hi:[0,1]
	v_pk_fma_f32 v[26:27], v[10:11], v[134:135], v[26:27] op_sel:[1,0,0] op_sel_hi:[1,1,1]
	v_pk_fma_f32 v[26:27], v[8:9], v[136:137], v[26:27] op_sel:[0,0,0] op_sel_hi:[0,1,1]
	v_pk_fma_f32 v[26:27], v[8:9], v[138:139], v[26:27] op_sel:[1,0,0] op_sel_hi:[1,1,1]
	ds_write2st64_b32 v50, v25, v27 offset0:120 offset1:124
	v_pk_mul_f32 v[10:11], v[10:11], v[140:141]
	v_pk_mul_f32 v[8:9], v[8:9], v[142:143]
	s_waitcnt lgkmcnt(7)
	v_pk_mul_f32 v[24:25], v[10:11], v[144:145]
	v_pk_fma_f32 v[24:25], v[8:9], v[146:147], v[24:25]
	v_add_f32_e32 v24, v24, v25
	s_waitcnt lgkmcnt(5)
	v_pk_fma_f32 v[16:17], v[76:77], v[156:157], v[10:11] op_sel_hi:[1,0,1]
	v_pk_fma_f32 v[18:19], v[78:79], v[156:157], v[8:9] op_sel_hi:[1,0,1]
	v_add_f32_dpp v15, v24, v24 row_ror:8 row_mask:0xf bank_mask:0xf bound_ctrl:1
	v_add_u32_e32 v51, 1, v51
	s_add_u32 s6, s6, 1
	v_add_f32_dpp v15, v15, v15 row_ror:4 row_mask:0xf bank_mask:0xf bound_ctrl:1
	ds_write_b32 v53, v51
	ds_read_b128 v[108:111], v34 offset:2048
	v_add_f32_dpp v15, v15, v15 row_ror:2 row_mask:0xf bank_mask:0xf bound_ctrl:1
	ds_read_b128 v[112:115], v34 offset:2304
	ds_read_b128 v[116:119], v34 offset:2560
	v_add_f32_dpp v30, v15, v15 row_ror:1 row_mask:0xf bank_mask:0xf bound_ctrl:1
	ds_read_b128 v[120:123], v34 offset:2816
	s_cmp_lt_u32 s6, 0x100
	s_cbranch_scc1 .Lsc_S_loop
	s_waitcnt lgkmcnt(0)
	s_branch .Lsc_item_end
	s_nop 0
	s_nop 0
	s_nop 0
	s_nop 0
	s_nop 0
	s_nop 0
	s_nop 0
	s_nop 0
	s_nop 0
	s_nop 0
	s_nop 0
	s_nop 0
	s_nop 0
	s_nop 0
	s_nop 0
	s_nop 0
	s_nop 0

.Lsc_G:
	v_add_u32_e32 v1, 0xffffff00, v173
	v_lshrrev_b32_e32 v2, 3, v1
	v_and_b32_e32 v3, 7, v1
	s_and_b32 s8, s4, 7
	s_bfe_u32 s10, s4, 0x20003
	s_lshr_b32 s11, s4, 7
	s_bfe_u32 s9, s4, 0x20005
	s_lshl_b32 s9, s9, 13
	v_readlane_b32 s50, v242, 0
	v_readlane_b32 s51, v242, 1
	v_readlane_b32 s16, v242, 62
	s_load_dwordx4 s[12:15], s[50:51], 0x68
	s_add_u32 s36, s90, 0x5e00000
	s_addc_u32 s37, s91, 0
	s_add_u32 s38, s90, 0x7e00000
	s_addc_u32 s39, s91, 0
	s_add_u32 s44, s90, 0x9e00000
	s_addc_u32 s45, s91, 0
	s_add_u32 s46, s90, 0x1c00000
	s_addc_u32 s47, s91, 0
	s_lshl_b32 s68, s11, 25
	s_add_u32 s69, s68, 0x13e00000
	s_add_u32 s40, s90, s69
	s_addc_u32 s41, s91, 0
	s_add_u32 s69, s68, 0x17e00000
	s_add_u32 s42, s90, s69
	s_addc_u32 s43, s91, 0
	s_lshl_b32 s68, s11, 26
	s_add_u32 s68, s68, 0xbe00000
	s_add_u32 s48, s90, s68
	s_addc_u32 s49, s91, 0
	s_cmp_eq_u32 s11, 0
	s_mov_b32 s54, 0x8000
	s_movk_i32 s55, 0x400
	s_mov_b32 s64, 0x10000
	s_cselect_b32 s54, s54, 0xffff8000
	s_cselect_b32 s55, s55, 0xfffffc00
	s_cselect_b32 s64, s64, 0xffff0000
	s_cselect_b64 vcc, -1, 0
	v_sub_u32_e32 v4, 0x1fff, v2
	s_nop 3
	v_cndmask_b32_e32 v4, v4, v2, vcc
	v_add_u32_e32 v4, s9, v4
	s_lshl_b32 s68, s8, 7
	v_lshlrev_b32_e32 v5, 10, v4
	v_lshl_add_u32 v5, v3, 3, v5
	v_add_u32_e32 v5, s68, v5
	s_lshl_b32 s69, s8, 2
	v_lshlrev_b32_e32 v6, 5, v4
	v_add_u32_e32 v6, s69, v6
	s_lshl_b32 s69, s10, 5
	s_add_i32 s69, s69, s68
	v_lshlrev_b32_e32 v9, 10, v4
	v_lshl_add_u32 v9, v3, 2, v9
	v_add_u32_e32 v9, s69, v9
	s_lshl_b32 s65, s69, 1
	v_mul_u32_u24_e32 v8, 1024, v2
	v_lshl_add_u32 v8, v3, 4, v8
	v_add_u32_e32 v138, 512, v8
	v_add_u32_e32 v140, 35328, v8
	v_add_u32_e32 v152, -4, v0
	v_mul_u32_u24_e32 v152, 4608, v152
	v_add_u32_e32 v152, 139840, v152
	v_and_b32_e32 v156, 7, v2
	v_lshlrev_b32_e32 v153, 8, v156
	v_lshl_add_u32 v153, v3, 4, v153
	v_add_u32_e32 v153, v152, v153
	v_and_b32_e32 v154, 63, v1
	v_lshl_add_u32 v154, v154, 2, v152
	v_add_u32_e32 v155, 2048, v154
	v_add_u32_e32 v139, -1, v2
	v_mul_u32_u24_e32 v139, 1024, v139
	v_lshl_add_u32 v139, v3, 4, v139
	v_add_u32_e32 v141, 35328, v139
	v_add_u32_e32 v139, 512, v139
	v_cmp_eq_u32_e32 vcc, 0, v2
	s_nop 1
	v_cndmask_b32_e32 v139, v139, v152, vcc
	v_cndmask_b32_e32 v141, v141, v152, vcc
	v_lshrrev_b32_e32 v158, 3, v2
	v_lshlrev_b32_e32 v158, 8, v158
	v_lshl_add_u32 v158, v3, 4, v158
	v_and_b32_e32 v159, 63, v1
	v_lshlrev_b32_e32 v159, 2, v159
	v_add_u32_e32 v106, -4, v0
	v_lshl_add_u32 v159, v106, 8, v159
	v_add_u32_e32 v159, 33792, v159
	v_mov_b32_e32 v106, 1.0
	ds_write_b32 v155, v106
	v_add_u32_e32 v158, 32768, v158
	v_mul_u32_u24_e32 v142, 288, v3
	v_lshl_add_u32 v142, v2, 2, v142
	v_add_u32_e32 v143, 71936, v142
	v_add_u32_e32 v142, 69632, v142
	s_lshl_b32 s69, s8, 6
	s_add_i32 s69, s69, s16
	v_lshl_add_u32 v106, v3, 2, s69
	v_lshlrev_b32_e32 v106, 2, v106
	s_waitcnt lgkmcnt(0)
	global_load_dwordx4 v[12:15], v106, s[12:13]
	global_load_dwordx4 v[16:19], v106, s[12:13] offset:128
	global_load_dwordx4 v[20:23], v106, s[14:15]
	global_load_dwordx4 v[24:27], v106, s[14:15] offset:128
	global_load_dwordx2 v[28:29], v5, s[36:37]
	global_load_dwordx2 v[30:31], v5, s[36:37] offset:64
	global_load_dwordx2 v[32:33], v5, s[38:39]
	global_load_dwordx2 v[34:35], v5, s[38:39] offset:64
	global_load_dwordx2 v[36:37], v5, s[40:41]
	global_load_dwordx2 v[38:39], v5, s[40:41] offset:64
	global_load_dwordx2 v[40:41], v5, s[42:43]
	global_load_dwordx2 v[42:43], v5, s[42:43] offset:64
	global_load_dword v44, v6, s[46:47]
	global_load_dword v45, v9, s[44:45]
	v_add_u32_e32 v5, s54, v5
	v_add_u32_e32 v6, s55, v6
	v_add_u32_e32 v9, s54, v9
	global_load_dwordx2 v[46:47], v5, s[36:37]
	global_load_dwordx2 v[48:49], v5, s[36:37] offset:64
	global_load_dwordx2 v[50:51], v5, s[38:39]
	global_load_dwordx2 v[52:53], v5, s[38:39] offset:64
	global_load_dwordx2 v[54:55], v5, s[40:41]
	global_load_dwordx2 v[56:57], v5, s[40:41] offset:64
	global_load_dwordx2 v[58:59], v5, s[42:43]
	global_load_dwordx2 v[60:61], v5, s[42:43] offset:64
	global_load_dword v62, v6, s[46:47]
	global_load_dword v63, v9, s[44:45]
	v_add_u32_e32 v5, s54, v5
	v_add_u32_e32 v6, s55, v6
	v_add_u32_e32 v9, s54, v9
	v_and_b32_e32 v166, 15, v1
	v_lshrrev_b32_e32 v167, 4, v1
	v_sub_u32_e32 v4, 0x1fff, v167
	s_cmp_eq_u32 s11, 0
	s_cselect_b64 vcc, -1, 0
	s_nop 3
	v_cndmask_b32_e32 v4, v4, v167, vcc
	v_add_u32_e32 v4, s9, v4
	v_lshlrev_b32_e32 v7, 11, v4
	v_lshl_add_u32 v7, v166, 2, v7
	v_add_u32_e32 v7, s65, v7
	s_ashr_i32 s65, s64, 1
	v_add_u32_e32 v165, s65, v7
	v_lshlrev_b32_e32 v11, 10, v167
	v_lshl_add_u32 v11, v166, 6, v11
	v_add_u32_e32 v11, 74240, v11
	v_lshrrev_b32_e32 v166, 2, v166
	v_add_u32_e32 v2, 0, v166
	v_and_b32_e32 v2, 3, v2
	v_lshl_add_u32 v2, v2, 4, v11
	v_add_u32_e32 v3, 1, v166
	v_and_b32_e32 v3, 3, v3
	v_lshl_add_u32 v3, v3, 4, v11
	v_add_u32_e32 v4, 2, v166
	v_and_b32_e32 v4, 3, v4
	v_lshl_add_u32 v4, v4, 4, v11
	v_add_u32_e32 v10, 3, v166
	v_and_b32_e32 v10, 3, v10
	v_lshl_add_u32 v10, v10, 4, v11
	v_cmp_eq_u32_e64 s[12:13], 0, v156
	v_cmp_eq_u32_e64 s[14:15], 7, v156
	s_mov_b32 s6, 0
	v_mov_b32_e32 v144, 139792
	v_mov_b32_e32 v145, v164
	v_mov_b32_e32 v146, 0
	s_waitcnt vmcnt(10)
	v_lshlrev_b32_e32 v64, 16, v36
	v_and_b32_e32 v65, 0xffff0000, v36
	v_mul_f32_e32 v64, 0x3fb8aa3b, v64
	v_mul_f32_e32 v65, 0x3fb8aa3b, v65
	v_lshlrev_b32_e32 v66, 16, v37
	v_and_b32_e32 v67, 0xffff0000, v37
	v_mul_f32_e32 v66, 0x3fb8aa3b, v66
	v_mul_f32_e32 v67, 0x3fb8aa3b, v67
	v_lshlrev_b32_e32 v68, 16, v38
	v_and_b32_e32 v69, 0xffff0000, v38
	v_mul_f32_e32 v68, 0x3fb8aa3b, v68
	v_mul_f32_e32 v69, 0x3fb8aa3b, v69
	v_lshlrev_b32_e32 v70, 16, v39
	v_and_b32_e32 v71, 0xffff0000, v39
	v_mul_f32_e32 v70, 0x3fb8aa3b, v70
	v_mul_f32_e32 v71, 0x3fb8aa3b, v71
	ds_write_b128 v153, v[64:67]
	ds_write_b128 v153, v[68:71] offset:128
	s_waitcnt lgkmcnt(0)
	ds_read_b32 v124, v154 offset:0
	ds_read_b32 v125, v154 offset:256
	ds_read_b32 v126, v154 offset:512
	ds_read_b32 v127, v154 offset:768
	ds_read_b32 v128, v154 offset:1024
	ds_read_b32 v129, v154 offset:1280
	ds_read_b32 v130, v154 offset:1536
	ds_read_b32 v131, v154 offset:1792
	v_lshlrev_b32_e32 v108, 16, v32
	v_and_b32_e32 v109, 0xffff0000, v32
	v_lshlrev_b32_e32 v110, 16, v40
	v_and_b32_e32 v111, 0xffff0000, v40
	v_lshlrev_b32_e32 v96, 16, v28
	v_and_b32_e32 v97, 0xffff0000, v28
	v_pk_add_f32 v[112:113], v[110:111], -1.0 op_sel_hi:[1,0]
	v_pk_mul_f32 v[114:115], v[12:13], v[108:109]
	v_pk_fma_f32 v[112:113], v[20:21], v[112:113], 1.0 op_sel_hi:[1,1,0]
	v_pk_mul_f32 v[88:89], v[44:45], v[114:115] op_sel_hi:[0,1]
	v_pk_mul_f32 v[72:73], v[112:113], v[108:109]
	v_pk_mul_f32 v[80:81], v[88:89], v[110:111]
	v_lshlrev_b32_e32 v108, 16, v33
	v_and_b32_e32 v109, 0xffff0000, v33
	v_lshlrev_b32_e32 v110, 16, v41
	v_and_b32_e32 v111, 0xffff0000, v41
	v_lshlrev_b32_e32 v98, 16, v29
	v_and_b32_e32 v99, 0xffff0000, v29
	v_pk_add_f32 v[112:113], v[110:111], -1.0 op_sel_hi:[1,0]
	v_pk_mul_f32 v[114:115], v[14:15], v[108:109]
	v_pk_fma_f32 v[112:113], v[22:23], v[112:113], 1.0 op_sel_hi:[1,1,0]
	v_pk_mul_f32 v[90:91], v[44:45], v[114:115] op_sel_hi:[0,1]
	v_pk_mul_f32 v[74:75], v[112:113], v[108:109]
	v_pk_mul_f32 v[82:83], v[90:91], v[110:111]
	v_lshlrev_b32_e32 v108, 16, v34
	v_and_b32_e32 v109, 0xffff0000, v34
	v_lshlrev_b32_e32 v110, 16, v42
	v_and_b32_e32 v111, 0xffff0000, v42
	v_lshlrev_b32_e32 v100, 16, v30
	v_and_b32_e32 v101, 0xffff0000, v30
	v_pk_add_f32 v[112:113], v[110:111], -1.0 op_sel_hi:[1,0]
	v_pk_mul_f32 v[114:115], v[16:17], v[108:109]
	v_pk_fma_f32 v[112:113], v[24:25], v[112:113], 1.0 op_sel_hi:[1,1,0]
	v_pk_mul_f32 v[92:93], v[44:45], v[114:115] op_sel_hi:[0,1]
	v_pk_mul_f32 v[76:77], v[112:113], v[108:109]
	v_pk_mul_f32 v[84:85], v[92:93], v[110:111]
	v_lshlrev_b32_e32 v108, 16, v35
	v_and_b32_e32 v109, 0xffff0000, v35
	v_lshlrev_b32_e32 v110, 16, v43
	v_and_b32_e32 v111, 0xffff0000, v43
	v_lshlrev_b32_e32 v102, 16, v31
	v_and_b32_e32 v103, 0xffff0000, v31
	v_pk_add_f32 v[112:113], v[110:111], -1.0 op_sel_hi:[1,0]
	v_pk_mul_f32 v[114:115], v[18:19], v[108:109]
	v_pk_fma_f32 v[112:113], v[26:27], v[112:113], 1.0 op_sel_hi:[1,1,0]
	v_pk_mul_f32 v[94:95], v[44:45], v[114:115] op_sel_hi:[0,1]
	v_pk_mul_f32 v[78:79], v[112:113], v[108:109]
	v_pk_mul_f32 v[86:87], v[94:95], v[110:111]
	v_lshlrev_b32_e32 v104, 16, v45
	v_and_b32_e32 v105, 0xffff0000, v45
	s_waitcnt lgkmcnt(0)
	v_add_f32_e32 v125, v124, v125
	v_add_f32_e32 v126, v125, v126
	v_add_f32_e32 v127, v126, v127
	v_add_f32_e32 v128, v127, v128
	v_add_f32_e32 v129, v128, v129
	v_add_f32_e32 v130, v129, v130
	v_add_f32_e32 v131, v130, v131
	v_exp_f32_e64 v124, -v124
	v_exp_f32_e64 v125, -v125
	v_exp_f32_e64 v126, -v126
	v_exp_f32_e64 v127, -v127
	v_exp_f32_e64 v128, -v128
	v_exp_f32_e64 v129, -v129
	v_exp_f32_e64 v130, -v130
	v_exp_f32_e64 v131, -v131
	s_nop 0
	ds_write_b32 v155, v124 offset:256
	ds_write_b32 v155, v125 offset:512
	ds_write_b32 v155, v126 offset:768
	ds_write_b32 v155, v127 offset:1024
	ds_write_b32 v155, v128 offset:1280
	ds_write_b32 v155, v129 offset:1536
	ds_write_b32 v155, v130 offset:1792
	ds_write_b32 v155, v131 offset:2048
	v_mov_b32_e32 v161, v131
	s_waitcnt lgkmcnt(0)
	ds_read_b128 v[64:67], v153 offset:2048
	ds_read_b128 v[68:71], v153 offset:2176
	ds_read_b128 v[116:119], v153 offset:2304
	ds_read_b128 v[120:123], v153 offset:2432
	s_waitcnt lgkmcnt(0)
	v_rcp_f32_e32 v124, v116
	v_rcp_f32_e32 v125, v117
	v_rcp_f32_e32 v126, v118
	v_rcp_f32_e32 v127, v119
	v_rcp_f32_e32 v128, v120
	v_rcp_f32_e32 v129, v121
	v_rcp_f32_e32 v130, v122
	v_rcp_f32_e32 v131, v123
	s_nop 1
	v_pk_mul_f32 v[72:73], v[72:73], v[124:125]
	v_pk_mul_f32 v[80:81], v[80:81], v[124:125]
	v_pk_mul_f32 v[88:89], v[88:89], v[64:65]
	v_pk_mul_f32 v[96:97], v[96:97], v[116:117]
	v_pk_mul_f32 v[74:75], v[74:75], v[126:127]
	v_pk_mul_f32 v[82:83], v[82:83], v[126:127]
	v_pk_mul_f32 v[90:91], v[90:91], v[66:67]
	v_pk_mul_f32 v[98:99], v[98:99], v[118:119]
	v_pk_mul_f32 v[76:77], v[76:77], v[128:129]
	v_pk_mul_f32 v[84:85], v[84:85], v[128:129]
	v_pk_mul_f32 v[92:93], v[92:93], v[68:69]
	v_pk_mul_f32 v[100:101], v[100:101], v[120:121]
	v_pk_mul_f32 v[78:79], v[78:79], v[130:131]
	v_pk_mul_f32 v[86:87], v[86:87], v[130:131]
	v_pk_mul_f32 v[94:95], v[94:95], v[70:71]
	v_pk_mul_f32 v[102:103], v[102:103], v[122:123]
	global_load_dwordx2 v[28:29], v5, s[36:37]
	global_load_dwordx2 v[30:31], v5, s[36:37] offset:64
	global_load_dwordx2 v[32:33], v5, s[38:39]
	global_load_dwordx2 v[34:35], v5, s[38:39] offset:64
	global_load_dwordx2 v[36:37], v5, s[40:41]
	global_load_dwordx2 v[38:39], v5, s[40:41] offset:64
	global_load_dwordx2 v[40:41], v5, s[42:43]
	global_load_dwordx2 v[42:43], v5, s[42:43] offset:64
	global_load_dword v44, v6, s[46:47]
	global_load_dword v45, v9, s[44:45]
	v_add_u32_e32 v5, s54, v5
	v_add_u32_e32 v6, s55, v6
	v_add_u32_e32 v9, s54, v9
	ds_write_b32 v159, v161 offset:0
	ds_write_b128 v8, v[72:75] offset:0
	ds_write_b128 v8, v[76:79] offset:128
	ds_write_b128 v8, v[80:83] offset:256
	ds_write_b128 v8, v[84:87] offset:384
	ds_write2_b32 v138, v96, v97 offset0:1 offset1:3
	ds_write2_b32 v139, v88, v89 offset0:0 offset1:2
	ds_write2_b32 v138, v98, v99 offset0:65 offset1:67
	ds_write2_b32 v139, v90, v91 offset0:64 offset1:66
	ds_write2_b32 v138, v100, v101 offset0:33 offset1:35
	ds_write2_b32 v139, v92, v93 offset0:32 offset1:34
	ds_write2_b32 v138, v102, v103 offset0:97 offset1:99
	ds_write2_b32 v139, v94, v95 offset0:96 offset1:98
	ds_write2_b32 v142, v104, v105 offset1:36
	s_and_saveexec_b64 s[68:69], s[12:13]
	ds_write_b128 v158, v[88:91] offset:0
	ds_write_b128 v158, v[92:95] offset:128
	s_mov_b64 exec, s[68:69]
	s_add_i32 s6, s6, 1
	v_add_u32_e32 v146, 1, v146
	s_waitcnt lgkmcnt(0)
	ds_write_b32 v145, v146
	s_waitcnt vmcnt(10)
	v_lshlrev_b32_e32 v64, 16, v54
	v_and_b32_e32 v65, 0xffff0000, v54
	v_mul_f32_e32 v64, 0x3fb8aa3b, v64
	v_mul_f32_e32 v65, 0x3fb8aa3b, v65
	v_lshlrev_b32_e32 v66, 16, v55
	v_and_b32_e32 v67, 0xffff0000, v55
	v_mul_f32_e32 v66, 0x3fb8aa3b, v66
	v_mul_f32_e32 v67, 0x3fb8aa3b, v67
	v_lshlrev_b32_e32 v68, 16, v56
	v_and_b32_e32 v69, 0xffff0000, v56
	v_mul_f32_e32 v68, 0x3fb8aa3b, v68
	v_mul_f32_e32 v69, 0x3fb8aa3b, v69
	v_lshlrev_b32_e32 v70, 16, v57
	v_and_b32_e32 v71, 0xffff0000, v57
	v_mul_f32_e32 v70, 0x3fb8aa3b, v70
	v_mul_f32_e32 v71, 0x3fb8aa3b, v71
	ds_write_b128 v153, v[64:67]
	ds_write_b128 v153, v[68:71] offset:128
	s_waitcnt lgkmcnt(0)
	ds_read_b32 v124, v154 offset:0
	ds_read_b32 v125, v154 offset:256
	ds_read_b32 v126, v154 offset:512
	ds_read_b32 v127, v154 offset:768
	ds_read_b32 v128, v154 offset:1024
	ds_read_b32 v129, v154 offset:1280
	ds_read_b32 v130, v154 offset:1536
	ds_read_b32 v131, v154 offset:1792
	v_lshlrev_b32_e32 v108, 16, v50
	v_and_b32_e32 v109, 0xffff0000, v50
	v_lshlrev_b32_e32 v110, 16, v58
	v_and_b32_e32 v111, 0xffff0000, v58
	v_lshlrev_b32_e32 v96, 16, v46
	v_and_b32_e32 v97, 0xffff0000, v46
	v_pk_add_f32 v[112:113], v[110:111], -1.0 op_sel_hi:[1,0]
	v_pk_mul_f32 v[114:115], v[12:13], v[108:109]
	v_pk_fma_f32 v[112:113], v[20:21], v[112:113], 1.0 op_sel_hi:[1,1,0]
	v_pk_mul_f32 v[88:89], v[62:63], v[114:115] op_sel_hi:[0,1]
	v_pk_mul_f32 v[72:73], v[112:113], v[108:109]
	v_pk_mul_f32 v[80:81], v[88:89], v[110:111]
	v_lshlrev_b32_e32 v108, 16, v51
	v_and_b32_e32 v109, 0xffff0000, v51
	v_lshlrev_b32_e32 v110, 16, v59
	v_and_b32_e32 v111, 0xffff0000, v59
	v_lshlrev_b32_e32 v98, 16, v47
	v_and_b32_e32 v99, 0xffff0000, v47
	v_pk_add_f32 v[112:113], v[110:111], -1.0 op_sel_hi:[1,0]
	v_pk_mul_f32 v[114:115], v[14:15], v[108:109]
	v_pk_fma_f32 v[112:113], v[22:23], v[112:113], 1.0 op_sel_hi:[1,1,0]
	v_pk_mul_f32 v[90:91], v[62:63], v[114:115] op_sel_hi:[0,1]
	v_pk_mul_f32 v[74:75], v[112:113], v[108:109]
	v_pk_mul_f32 v[82:83], v[90:91], v[110:111]
	v_lshlrev_b32_e32 v108, 16, v52
	v_and_b32_e32 v109, 0xffff0000, v52
	v_lshlrev_b32_e32 v110, 16, v60
	v_and_b32_e32 v111, 0xffff0000, v60
	v_lshlrev_b32_e32 v100, 16, v48
	v_and_b32_e32 v101, 0xffff0000, v48
	v_pk_add_f32 v[112:113], v[110:111], -1.0 op_sel_hi:[1,0]
	v_pk_mul_f32 v[114:115], v[16:17], v[108:109]
	v_pk_fma_f32 v[112:113], v[24:25], v[112:113], 1.0 op_sel_hi:[1,1,0]
	v_pk_mul_f32 v[92:93], v[62:63], v[114:115] op_sel_hi:[0,1]
	v_pk_mul_f32 v[76:77], v[112:113], v[108:109]
	v_pk_mul_f32 v[84:85], v[92:93], v[110:111]
	v_lshlrev_b32_e32 v108, 16, v53
	v_and_b32_e32 v109, 0xffff0000, v53
	v_lshlrev_b32_e32 v110, 16, v61
	v_and_b32_e32 v111, 0xffff0000, v61
	v_lshlrev_b32_e32 v102, 16, v49
	v_and_b32_e32 v103, 0xffff0000, v49
	v_pk_add_f32 v[112:113], v[110:111], -1.0 op_sel_hi:[1,0]
	v_pk_mul_f32 v[114:115], v[18:19], v[108:109]
	v_pk_fma_f32 v[112:113], v[26:27], v[112:113], 1.0 op_sel_hi:[1,1,0]
	v_pk_mul_f32 v[94:95], v[62:63], v[114:115] op_sel_hi:[0,1]
	v_pk_mul_f32 v[78:79], v[112:113], v[108:109]
	v_pk_mul_f32 v[86:87], v[94:95], v[110:111]
	v_lshlrev_b32_e32 v104, 16, v63
	v_and_b32_e32 v105, 0xffff0000, v63
	s_waitcnt lgkmcnt(0)
	v_add_f32_e32 v125, v124, v125
	v_add_f32_e32 v126, v125, v126
	v_add_f32_e32 v127, v126, v127
	v_add_f32_e32 v128, v127, v128
	v_add_f32_e32 v129, v128, v129
	v_add_f32_e32 v130, v129, v130
	v_add_f32_e32 v131, v130, v131
	v_exp_f32_e64 v124, -v124
	v_exp_f32_e64 v125, -v125
	v_exp_f32_e64 v126, -v126
	v_exp_f32_e64 v127, -v127
	v_exp_f32_e64 v128, -v128
	v_exp_f32_e64 v129, -v129
	v_exp_f32_e64 v130, -v130
	v_exp_f32_e64 v131, -v131
	s_nop 0
	ds_write_b32 v155, v124 offset:256
	ds_write_b32 v155, v125 offset:512
	ds_write_b32 v155, v126 offset:768
	ds_write_b32 v155, v127 offset:1024
	ds_write_b32 v155, v128 offset:1280
	ds_write_b32 v155, v129 offset:1536
	ds_write_b32 v155, v130 offset:1792
	ds_write_b32 v155, v131 offset:2048
	v_mov_b32_e32 v161, v131
	s_waitcnt lgkmcnt(0)
	ds_read_b128 v[64:67], v153 offset:2048
	ds_read_b128 v[68:71], v153 offset:2176
	ds_read_b128 v[116:119], v153 offset:2304
	ds_read_b128 v[120:123], v153 offset:2432
	s_waitcnt lgkmcnt(0)
	v_rcp_f32_e32 v124, v116
	v_rcp_f32_e32 v125, v117
	v_rcp_f32_e32 v126, v118
	v_rcp_f32_e32 v127, v119
	v_rcp_f32_e32 v128, v120
	v_rcp_f32_e32 v129, v121
	v_rcp_f32_e32 v130, v122
	v_rcp_f32_e32 v131, v123
	s_nop 1
	v_pk_mul_f32 v[72:73], v[72:73], v[124:125]
	v_pk_mul_f32 v[80:81], v[80:81], v[124:125]
	v_pk_mul_f32 v[88:89], v[88:89], v[64:65]
	v_pk_mul_f32 v[96:97], v[96:97], v[116:117]
	v_pk_mul_f32 v[74:75], v[74:75], v[126:127]
	v_pk_mul_f32 v[82:83], v[82:83], v[126:127]
	v_pk_mul_f32 v[90:91], v[90:91], v[66:67]
	v_pk_mul_f32 v[98:99], v[98:99], v[118:119]
	v_pk_mul_f32 v[76:77], v[76:77], v[128:129]
	v_pk_mul_f32 v[84:85], v[84:85], v[128:129]
	v_pk_mul_f32 v[92:93], v[92:93], v[68:69]
	v_pk_mul_f32 v[100:101], v[100:101], v[120:121]
	v_pk_mul_f32 v[78:79], v[78:79], v[130:131]
	v_pk_mul_f32 v[86:87], v[86:87], v[130:131]
	v_pk_mul_f32 v[94:95], v[94:95], v[70:71]
	v_pk_mul_f32 v[102:103], v[102:103], v[122:123]
	global_load_dwordx2 v[46:47], v5, s[36:37]
	global_load_dwordx2 v[48:49], v5, s[36:37] offset:64
	global_load_dwordx2 v[50:51], v5, s[38:39]
	global_load_dwordx2 v[52:53], v5, s[38:39] offset:64
	global_load_dwordx2 v[54:55], v5, s[40:41]
	global_load_dwordx2 v[56:57], v5, s[40:41] offset:64
	global_load_dwordx2 v[58:59], v5, s[42:43]
	global_load_dwordx2 v[60:61], v5, s[42:43] offset:64
	global_load_dword v62, v6, s[46:47]
	global_load_dword v63, v9, s[44:45]
	v_add_u32_e32 v5, s54, v5
	v_add_u32_e32 v6, s55, v6
	v_add_u32_e32 v9, s54, v9
	ds_write_b32 v159, v161 offset:34816
	ds_write_b128 v8, v[72:75] offset:34816
	ds_write_b128 v8, v[76:79] offset:34944
	ds_write_b128 v8, v[80:83] offset:35072
	ds_write_b128 v8, v[84:87] offset:35200
	ds_write2_b32 v140, v96, v97 offset0:1 offset1:3
	ds_write2_b32 v141, v88, v89 offset0:0 offset1:2
	ds_write2_b32 v140, v98, v99 offset0:65 offset1:67
	ds_write2_b32 v141, v90, v91 offset0:64 offset1:66
	ds_write2_b32 v140, v100, v101 offset0:33 offset1:35
	ds_write2_b32 v141, v92, v93 offset0:32 offset1:34
	ds_write2_b32 v140, v102, v103 offset0:97 offset1:99
	ds_write2_b32 v141, v94, v95 offset0:96 offset1:98
	ds_write2_b32 v143, v104, v105 offset1:36
	s_and_saveexec_b64 s[68:69], s[12:13]
	ds_write_b128 v158, v[88:91] offset:34816
	ds_write_b128 v158, v[92:95] offset:34944
	s_mov_b64 exec, s[68:69]
	s_add_i32 s6, s6, 1
	v_add_u32_e32 v146, 1, v146
	s_waitcnt lgkmcnt(0)
	ds_write_b32 v145, v146

.Lsc_G_gom0:
	ds_write_b32 v159, v161 offset:0
	ds_write_b128 v8, v[72:75] offset:0
	ds_write_b128 v8, v[76:79] offset:128
	ds_write_b128 v8, v[80:83] offset:256
	ds_write_b128 v8, v[84:87] offset:384
	ds_write2_b32 v138, v96, v97 offset0:1 offset1:3
	ds_write2_b32 v139, v88, v89 offset0:0 offset1:2
	ds_write2_b32 v138, v98, v99 offset0:65 offset1:67
	ds_write2_b32 v139, v90, v91 offset0:64 offset1:66
	ds_write2_b32 v138, v100, v101 offset0:33 offset1:35
	ds_write2_b32 v139, v92, v93 offset0:32 offset1:34
	ds_write2_b32 v138, v102, v103 offset0:97 offset1:99
	ds_write2_b32 v139, v94, v95 offset0:96 offset1:98
	ds_write2_b32 v142, v104, v105 offset1:36
	s_and_saveexec_b64 s[68:69], s[12:13]
	ds_write_b128 v158, v[88:91] offset:0
	ds_write_b128 v158, v[92:95] offset:128
	s_mov_b64 exec, s[68:69]
	ds_read_b128 v[106:109], v2 offset:0
	ds_read_b128 v[122:125], v2 offset:16384
	ds_read_b128 v[110:113], v3 offset:0
	ds_read_b128 v[126:129], v3 offset:16384
	ds_read_b128 v[114:117], v4 offset:0
	ds_read_b128 v[130:133], v4 offset:16384
	ds_read_b128 v[118:121], v10 offset:0
	ds_read_b128 v[134:137], v10 offset:16384
	s_waitcnt lgkmcnt(0)
	v_pk_add_f32 v[106:107], v[106:107], v[108:109]
	v_pk_add_f32 v[110:111], v[110:111], v[112:113]
	v_pk_add_f32 v[114:115], v[114:115], v[116:117]
	v_pk_add_f32 v[118:119], v[118:119], v[120:121]
	v_pk_add_f32 v[106:107], v[106:107], v[110:111]
	v_pk_add_f32 v[114:115], v[114:115], v[118:119]
	v_pk_add_f32 v[106:107], v[106:107], v[114:115]
	v_add_f32_e32 v64, v106, v107
	v_pk_add_f32 v[122:123], v[122:123], v[124:125]
	v_pk_add_f32 v[126:127], v[126:127], v[128:129]
	v_pk_add_f32 v[130:131], v[130:131], v[132:133]
	v_pk_add_f32 v[134:135], v[134:135], v[136:137]
	v_pk_add_f32 v[122:123], v[122:123], v[126:127]
	v_pk_add_f32 v[130:131], v[130:131], v[134:135]
	v_pk_add_f32 v[122:123], v[122:123], v[130:131]
	v_add_f32_e32 v65, v122, v123
	global_store_dword v7, v64, s[48:49]
	global_store_dword v165, v65, s[48:49]
	v_add_u32_e32 v7, s64, v7
	v_add_u32_e32 v165, s64, v165
	s_add_i32 s6, s6, 1
	v_add_u32_e32 v146, 1, v146
	s_waitcnt lgkmcnt(0)
	ds_write_b32 v145, v146
	s_waitcnt vmcnt(10)
	v_lshlrev_b32_e32 v64, 16, v54
	v_and_b32_e32 v65, 0xffff0000, v54
	v_mul_f32_e32 v64, 0x3fb8aa3b, v64
	v_mul_f32_e32 v65, 0x3fb8aa3b, v65
	v_lshlrev_b32_e32 v66, 16, v55
	v_and_b32_e32 v67, 0xffff0000, v55
	v_mul_f32_e32 v66, 0x3fb8aa3b, v66
	v_mul_f32_e32 v67, 0x3fb8aa3b, v67
	v_lshlrev_b32_e32 v68, 16, v56
	v_and_b32_e32 v69, 0xffff0000, v56
	v_mul_f32_e32 v68, 0x3fb8aa3b, v68
	v_mul_f32_e32 v69, 0x3fb8aa3b, v69
	v_lshlrev_b32_e32 v70, 16, v57
	v_and_b32_e32 v71, 0xffff0000, v57
	v_mul_f32_e32 v70, 0x3fb8aa3b, v70
	v_mul_f32_e32 v71, 0x3fb8aa3b, v71
	ds_write_b128 v153, v[64:67]
	ds_write_b128 v153, v[68:71] offset:128
	s_waitcnt lgkmcnt(0)
	ds_read_b32 v124, v154 offset:0
	ds_read_b32 v125, v154 offset:256
	ds_read_b32 v126, v154 offset:512
	ds_read_b32 v127, v154 offset:768
	ds_read_b32 v128, v154 offset:1024
	ds_read_b32 v129, v154 offset:1280
	ds_read_b32 v130, v154 offset:1536
	ds_read_b32 v131, v154 offset:1792
	v_lshlrev_b32_e32 v108, 16, v50
	v_and_b32_e32 v109, 0xffff0000, v50
	v_lshlrev_b32_e32 v110, 16, v58
	v_and_b32_e32 v111, 0xffff0000, v58
	v_lshlrev_b32_e32 v96, 16, v46
	v_and_b32_e32 v97, 0xffff0000, v46
	v_pk_add_f32 v[112:113], v[110:111], -1.0 op_sel_hi:[1,0]
	v_pk_mul_f32 v[114:115], v[12:13], v[108:109]
	v_pk_fma_f32 v[112:113], v[20:21], v[112:113], 1.0 op_sel_hi:[1,1,0]
	v_pk_mul_f32 v[88:89], v[62:63], v[114:115] op_sel_hi:[0,1]
	v_pk_mul_f32 v[72:73], v[112:113], v[108:109]
	v_pk_mul_f32 v[80:81], v[88:89], v[110:111]
	v_lshlrev_b32_e32 v108, 16, v51
	v_and_b32_e32 v109, 0xffff0000, v51
	v_lshlrev_b32_e32 v110, 16, v59
	v_and_b32_e32 v111, 0xffff0000, v59
	v_lshlrev_b32_e32 v98, 16, v47
	v_and_b32_e32 v99, 0xffff0000, v47
	v_pk_add_f32 v[112:113], v[110:111], -1.0 op_sel_hi:[1,0]
	v_pk_mul_f32 v[114:115], v[14:15], v[108:109]
	v_pk_fma_f32 v[112:113], v[22:23], v[112:113], 1.0 op_sel_hi:[1,1,0]
	v_pk_mul_f32 v[90:91], v[62:63], v[114:115] op_sel_hi:[0,1]
	v_pk_mul_f32 v[74:75], v[112:113], v[108:109]
	v_pk_mul_f32 v[82:83], v[90:91], v[110:111]
	v_lshlrev_b32_e32 v108, 16, v52
	v_and_b32_e32 v109, 0xffff0000, v52
	v_lshlrev_b32_e32 v110, 16, v60
	v_and_b32_e32 v111, 0xffff0000, v60
	v_lshlrev_b32_e32 v100, 16, v48
	v_and_b32_e32 v101, 0xffff0000, v48
	v_pk_add_f32 v[112:113], v[110:111], -1.0 op_sel_hi:[1,0]
	v_pk_mul_f32 v[114:115], v[16:17], v[108:109]
	v_pk_fma_f32 v[112:113], v[24:25], v[112:113], 1.0 op_sel_hi:[1,1,0]
	v_pk_mul_f32 v[92:93], v[62:63], v[114:115] op_sel_hi:[0,1]
	v_pk_mul_f32 v[76:77], v[112:113], v[108:109]
	v_pk_mul_f32 v[84:85], v[92:93], v[110:111]
	v_lshlrev_b32_e32 v108, 16, v53
	v_and_b32_e32 v109, 0xffff0000, v53
	v_lshlrev_b32_e32 v110, 16, v61
	v_and_b32_e32 v111, 0xffff0000, v61
	v_lshlrev_b32_e32 v102, 16, v49
	v_and_b32_e32 v103, 0xffff0000, v49
	v_pk_add_f32 v[112:113], v[110:111], -1.0 op_sel_hi:[1,0]
	v_pk_mul_f32 v[114:115], v[18:19], v[108:109]
	v_pk_fma_f32 v[112:113], v[26:27], v[112:113], 1.0 op_sel_hi:[1,1,0]
	v_pk_mul_f32 v[94:95], v[62:63], v[114:115] op_sel_hi:[0,1]
	v_pk_mul_f32 v[78:79], v[112:113], v[108:109]
	v_pk_mul_f32 v[86:87], v[94:95], v[110:111]
	v_lshlrev_b32_e32 v104, 16, v63
	v_and_b32_e32 v105, 0xffff0000, v63
	s_waitcnt lgkmcnt(0)
	v_add_f32_e32 v125, v124, v125
	v_add_f32_e32 v126, v125, v126
	v_add_f32_e32 v127, v126, v127
	v_add_f32_e32 v128, v127, v128
	v_add_f32_e32 v129, v128, v129
	v_add_f32_e32 v130, v129, v130
	v_add_f32_e32 v131, v130, v131
	v_exp_f32_e64 v124, -v124
	v_exp_f32_e64 v125, -v125
	v_exp_f32_e64 v126, -v126
	v_exp_f32_e64 v127, -v127
	v_exp_f32_e64 v128, -v128
	v_exp_f32_e64 v129, -v129
	v_exp_f32_e64 v130, -v130
	v_exp_f32_e64 v131, -v131
	s_nop 0
	ds_write_b32 v155, v124 offset:256
	ds_write_b32 v155, v125 offset:512
	ds_write_b32 v155, v126 offset:768
	ds_write_b32 v155, v127 offset:1024
	ds_write_b32 v155, v128 offset:1280
	ds_write_b32 v155, v129 offset:1536
	ds_write_b32 v155, v130 offset:1792
	ds_write_b32 v155, v131 offset:2048
	v_mov_b32_e32 v161, v131
	s_waitcnt lgkmcnt(0)
	ds_read_b128 v[64:67], v153 offset:2048
	ds_read_b128 v[68:71], v153 offset:2176
	ds_read_b128 v[116:119], v153 offset:2304
	ds_read_b128 v[120:123], v153 offset:2432
	s_waitcnt lgkmcnt(0)
	v_rcp_f32_e32 v124, v116
	v_rcp_f32_e32 v125, v117
	v_rcp_f32_e32 v126, v118
	v_rcp_f32_e32 v127, v119
	v_rcp_f32_e32 v128, v120
	v_rcp_f32_e32 v129, v121
	v_rcp_f32_e32 v130, v122
	v_rcp_f32_e32 v131, v123
	s_nop 1
	v_pk_mul_f32 v[72:73], v[72:73], v[124:125]
	v_pk_mul_f32 v[80:81], v[80:81], v[124:125]
	v_pk_mul_f32 v[88:89], v[88:89], v[64:65]
	v_pk_mul_f32 v[96:97], v[96:97], v[116:117]
	v_pk_mul_f32 v[74:75], v[74:75], v[126:127]
	v_pk_mul_f32 v[82:83], v[82:83], v[126:127]
	v_pk_mul_f32 v[90:91], v[90:91], v[66:67]
	v_pk_mul_f32 v[98:99], v[98:99], v[118:119]
	v_pk_mul_f32 v[76:77], v[76:77], v[128:129]
	v_pk_mul_f32 v[84:85], v[84:85], v[128:129]
	v_pk_mul_f32 v[92:93], v[92:93], v[68:69]
	v_pk_mul_f32 v[100:101], v[100:101], v[120:121]
	v_pk_mul_f32 v[78:79], v[78:79], v[130:131]
	v_pk_mul_f32 v[86:87], v[86:87], v[130:131]
	v_pk_mul_f32 v[94:95], v[94:95], v[70:71]
	v_pk_mul_f32 v[102:103], v[102:103], v[122:123]
	global_load_dwordx2 v[46:47], v5, s[36:37]
	global_load_dwordx2 v[48:49], v5, s[36:37] offset:64
	global_load_dwordx2 v[50:51], v5, s[38:39]
	global_load_dwordx2 v[52:53], v5, s[38:39] offset:64
	global_load_dwordx2 v[54:55], v5, s[40:41]
	global_load_dwordx2 v[56:57], v5, s[40:41] offset:64
	global_load_dwordx2 v[58:59], v5, s[42:43]
	global_load_dwordx2 v[60:61], v5, s[42:43] offset:64
	global_load_dword v62, v6, s[46:47]
	global_load_dword v63, v9, s[44:45]
	v_add_u32_e32 v5, s54, v5
	v_add_u32_e32 v6, s55, v6
	v_add_u32_e32 v9, s54, v9
	s_sub_u32 s65, s6, 1
	ds_read_b128 v[148:151], v144
	s_waitcnt lgkmcnt(0)
	v_min_u32_e32 v148, v148, v149
	v_min3_u32 v148, v148, v150, v151
	s_nop 1
	v_readfirstlane_b32 s68, v148
	s_cmp_ge_u32 s68, s65
	s_cbranch_scc1 .Lsc_G_gom1
	s_mov_b32 s69, 0x100000

.Lsc_G_gom1:
	ds_write_b32 v159, v161 offset:34816
	ds_write_b128 v8, v[72:75] offset:34816
	ds_write_b128 v8, v[76:79] offset:34944
	ds_write_b128 v8, v[80:83] offset:35072
	ds_write_b128 v8, v[84:87] offset:35200
	ds_write2_b32 v140, v96, v97 offset0:1 offset1:3
	ds_write2_b32 v141, v88, v89 offset0:0 offset1:2
	ds_write2_b32 v140, v98, v99 offset0:65 offset1:67
	ds_write2_b32 v141, v90, v91 offset0:64 offset1:66
	ds_write2_b32 v140, v100, v101 offset0:33 offset1:35
	ds_write2_b32 v141, v92, v93 offset0:32 offset1:34
	ds_write2_b32 v140, v102, v103 offset0:97 offset1:99
	ds_write2_b32 v141, v94, v95 offset0:96 offset1:98
	ds_write2_b32 v143, v104, v105 offset1:36
	s_and_saveexec_b64 s[68:69], s[12:13]
	ds_write_b128 v158, v[88:91] offset:34816
	ds_write_b128 v158, v[92:95] offset:34944
	s_mov_b64 exec, s[68:69]
	ds_read_b128 v[106:109], v2 offset:32768
	ds_read_b128 v[122:125], v2 offset:49152
	ds_read_b128 v[110:113], v3 offset:32768
	ds_read_b128 v[126:129], v3 offset:49152
	ds_read_b128 v[114:117], v4 offset:32768
	ds_read_b128 v[130:133], v4 offset:49152
	ds_read_b128 v[118:121], v10 offset:32768
	ds_read_b128 v[134:137], v10 offset:49152
	s_waitcnt lgkmcnt(0)
	v_pk_add_f32 v[106:107], v[106:107], v[108:109]
	v_pk_add_f32 v[110:111], v[110:111], v[112:113]
	v_pk_add_f32 v[114:115], v[114:115], v[116:117]
	v_pk_add_f32 v[118:119], v[118:119], v[120:121]
	v_pk_add_f32 v[106:107], v[106:107], v[110:111]
	v_pk_add_f32 v[114:115], v[114:115], v[118:119]
	v_pk_add_f32 v[106:107], v[106:107], v[114:115]
	v_add_f32_e32 v64, v106, v107
	v_pk_add_f32 v[122:123], v[122:123], v[124:125]
	v_pk_add_f32 v[126:127], v[126:127], v[128:129]
	v_pk_add_f32 v[130:131], v[130:131], v[132:133]
	v_pk_add_f32 v[134:135], v[134:135], v[136:137]
	v_pk_add_f32 v[122:123], v[122:123], v[126:127]
	v_pk_add_f32 v[130:131], v[130:131], v[134:135]
	v_pk_add_f32 v[122:123], v[122:123], v[130:131]
	v_add_f32_e32 v65, v122, v123
	global_store_dword v7, v64, s[48:49]
	global_store_dword v165, v65, s[48:49]
	v_add_u32_e32 v7, s64, v7
	v_add_u32_e32 v165, s64, v165
	s_add_i32 s6, s6, 1
	v_add_u32_e32 v146, 1, v146
	s_waitcnt lgkmcnt(0)
	ds_write_b32 v145, v146
	s_cmp_lt_u32 s6, 0xfe
	s_cbranch_scc1 .Lsc_G_loop
	s_waitcnt vmcnt(10)
	v_lshlrev_b32_e32 v64, 16, v36
	v_and_b32_e32 v65, 0xffff0000, v36
	v_mul_f32_e32 v64, 0x3fb8aa3b, v64
	v_mul_f32_e32 v65, 0x3fb8aa3b, v65
	v_lshlrev_b32_e32 v66, 16, v37
	v_and_b32_e32 v67, 0xffff0000, v37
	v_mul_f32_e32 v66, 0x3fb8aa3b, v66
	v_mul_f32_e32 v67, 0x3fb8aa3b, v67
	v_lshlrev_b32_e32 v68, 16, v38
	v_and_b32_e32 v69, 0xffff0000, v38
	v_mul_f32_e32 v68, 0x3fb8aa3b, v68
	v_mul_f32_e32 v69, 0x3fb8aa3b, v69
	v_lshlrev_b32_e32 v70, 16, v39
	v_and_b32_e32 v71, 0xffff0000, v39
	v_mul_f32_e32 v70, 0x3fb8aa3b, v70
	v_mul_f32_e32 v71, 0x3fb8aa3b, v71
	ds_write_b128 v153, v[64:67]
	ds_write_b128 v153, v[68:71] offset:128
	s_waitcnt lgkmcnt(0)
	ds_read_b32 v124, v154 offset:0
	ds_read_b32 v125, v154 offset:256
	ds_read_b32 v126, v154 offset:512
	ds_read_b32 v127, v154 offset:768
	ds_read_b32 v128, v154 offset:1024
	ds_read_b32 v129, v154 offset:1280
	ds_read_b32 v130, v154 offset:1536
	ds_read_b32 v131, v154 offset:1792
	v_lshlrev_b32_e32 v108, 16, v32
	v_and_b32_e32 v109, 0xffff0000, v32
	v_lshlrev_b32_e32 v110, 16, v40
	v_and_b32_e32 v111, 0xffff0000, v40
	v_lshlrev_b32_e32 v96, 16, v28
	v_and_b32_e32 v97, 0xffff0000, v28
	v_pk_add_f32 v[112:113], v[110:111], -1.0 op_sel_hi:[1,0]
	v_pk_mul_f32 v[114:115], v[12:13], v[108:109]
	v_pk_fma_f32 v[112:113], v[20:21], v[112:113], 1.0 op_sel_hi:[1,1,0]
	v_pk_mul_f32 v[88:89], v[44:45], v[114:115] op_sel_hi:[0,1]
	v_pk_mul_f32 v[72:73], v[112:113], v[108:109]
	v_pk_mul_f32 v[80:81], v[88:89], v[110:111]
	v_lshlrev_b32_e32 v108, 16, v33
	v_and_b32_e32 v109, 0xffff0000, v33
	v_lshlrev_b32_e32 v110, 16, v41
	v_and_b32_e32 v111, 0xffff0000, v41
	v_lshlrev_b32_e32 v98, 16, v29
	v_and_b32_e32 v99, 0xffff0000, v29
	v_pk_add_f32 v[112:113], v[110:111], -1.0 op_sel_hi:[1,0]
	v_pk_mul_f32 v[114:115], v[14:15], v[108:109]
	v_pk_fma_f32 v[112:113], v[22:23], v[112:113], 1.0 op_sel_hi:[1,1,0]
	v_pk_mul_f32 v[90:91], v[44:45], v[114:115] op_sel_hi:[0,1]
	v_pk_mul_f32 v[74:75], v[112:113], v[108:109]
	v_pk_mul_f32 v[82:83], v[90:91], v[110:111]
	v_lshlrev_b32_e32 v108, 16, v34
	v_and_b32_e32 v109, 0xffff0000, v34
	v_lshlrev_b32_e32 v110, 16, v42
	v_and_b32_e32 v111, 0xffff0000, v42
	v_lshlrev_b32_e32 v100, 16, v30
	v_and_b32_e32 v101, 0xffff0000, v30
	v_pk_add_f32 v[112:113], v[110:111], -1.0 op_sel_hi:[1,0]
	v_pk_mul_f32 v[114:115], v[16:17], v[108:109]
	v_pk_fma_f32 v[112:113], v[24:25], v[112:113], 1.0 op_sel_hi:[1,1,0]
	v_pk_mul_f32 v[92:93], v[44:45], v[114:115] op_sel_hi:[0,1]
	v_pk_mul_f32 v[76:77], v[112:113], v[108:109]
	v_pk_mul_f32 v[84:85], v[92:93], v[110:111]
	v_lshlrev_b32_e32 v108, 16, v35
	v_and_b32_e32 v109, 0xffff0000, v35
	v_lshlrev_b32_e32 v110, 16, v43
	v_and_b32_e32 v111, 0xffff0000, v43
	v_lshlrev_b32_e32 v102, 16, v31
	v_and_b32_e32 v103, 0xffff0000, v31
	v_pk_add_f32 v[112:113], v[110:111], -1.0 op_sel_hi:[1,0]
	v_pk_mul_f32 v[114:115], v[18:19], v[108:109]
	v_pk_fma_f32 v[112:113], v[26:27], v[112:113], 1.0 op_sel_hi:[1,1,0]
	v_pk_mul_f32 v[94:95], v[44:45], v[114:115] op_sel_hi:[0,1]
	v_pk_mul_f32 v[78:79], v[112:113], v[108:109]
	v_pk_mul_f32 v[86:87], v[94:95], v[110:111]
	v_lshlrev_b32_e32 v104, 16, v45
	v_and_b32_e32 v105, 0xffff0000, v45
	s_waitcnt lgkmcnt(0)
	v_add_f32_e32 v125, v124, v125
	v_add_f32_e32 v126, v125, v126
	v_add_f32_e32 v127, v126, v127
	v_add_f32_e32 v128, v127, v128
	v_add_f32_e32 v129, v128, v129
	v_add_f32_e32 v130, v129, v130
	v_add_f32_e32 v131, v130, v131
	v_exp_f32_e64 v124, -v124
	v_exp_f32_e64 v125, -v125
	v_exp_f32_e64 v126, -v126
	v_exp_f32_e64 v127, -v127
	v_exp_f32_e64 v128, -v128
	v_exp_f32_e64 v129, -v129
	v_exp_f32_e64 v130, -v130
	v_exp_f32_e64 v131, -v131
	s_nop 0
	ds_write_b32 v155, v124 offset:256
	ds_write_b32 v155, v125 offset:512
	ds_write_b32 v155, v126 offset:768
	ds_write_b32 v155, v127 offset:1024
	ds_write_b32 v155, v128 offset:1280
	ds_write_b32 v155, v129 offset:1536
	ds_write_b32 v155, v130 offset:1792
	ds_write_b32 v155, v131 offset:2048
	v_mov_b32_e32 v161, v131
	s_waitcnt lgkmcnt(0)
	ds_read_b128 v[64:67], v153 offset:2048
	ds_read_b128 v[68:71], v153 offset:2176
	ds_read_b128 v[116:119], v153 offset:2304
	ds_read_b128 v[120:123], v153 offset:2432
	s_waitcnt lgkmcnt(0)
	v_rcp_f32_e32 v124, v116
	v_rcp_f32_e32 v125, v117
	v_rcp_f32_e32 v126, v118
	v_rcp_f32_e32 v127, v119
	v_rcp_f32_e32 v128, v120
	v_rcp_f32_e32 v129, v121
	v_rcp_f32_e32 v130, v122
	v_rcp_f32_e32 v131, v123
	s_nop 1
	v_pk_mul_f32 v[72:73], v[72:73], v[124:125]
	v_pk_mul_f32 v[80:81], v[80:81], v[124:125]
	v_pk_mul_f32 v[88:89], v[88:89], v[64:65]
	v_pk_mul_f32 v[96:97], v[96:97], v[116:117]
	v_pk_mul_f32 v[74:75], v[74:75], v[126:127]
	v_pk_mul_f32 v[82:83], v[82:83], v[126:127]
	v_pk_mul_f32 v[90:91], v[90:91], v[66:67]
	v_pk_mul_f32 v[98:99], v[98:99], v[118:119]
	v_pk_mul_f32 v[76:77], v[76:77], v[128:129]
	v_pk_mul_f32 v[84:85], v[84:85], v[128:129]
	v_pk_mul_f32 v[92:93], v[92:93], v[68:69]
	v_pk_mul_f32 v[100:101], v[100:101], v[120:121]
	v_pk_mul_f32 v[78:79], v[78:79], v[130:131]
	v_pk_mul_f32 v[86:87], v[86:87], v[130:131]
	v_pk_mul_f32 v[94:95], v[94:95], v[70:71]
	v_pk_mul_f32 v[102:103], v[102:103], v[122:123]
	s_sub_u32 s65, s6, 1
	ds_read_b128 v[148:151], v144
	s_waitcnt lgkmcnt(0)
	v_min_u32_e32 v148, v148, v149
	v_min3_u32 v148, v148, v150, v151
	s_nop 1
	v_readfirstlane_b32 s68, v148
	s_cmp_ge_u32 s68, s65
	s_cbranch_scc1 .Lsc_G_goz0
	s_mov_b32 s69, 0x100000

.Lsc_G_goz0:
	ds_write_b32 v159, v161 offset:0
	ds_write_b128 v8, v[72:75] offset:0
	ds_write_b128 v8, v[76:79] offset:128
	ds_write_b128 v8, v[80:83] offset:256
	ds_write_b128 v8, v[84:87] offset:384
	ds_write2_b32 v138, v96, v97 offset0:1 offset1:3
	ds_write2_b32 v139, v88, v89 offset0:0 offset1:2
	ds_write2_b32 v138, v98, v99 offset0:65 offset1:67
	ds_write2_b32 v139, v90, v91 offset0:64 offset1:66
	ds_write2_b32 v138, v100, v101 offset0:33 offset1:35
	ds_write2_b32 v139, v92, v93 offset0:32 offset1:34
	ds_write2_b32 v138, v102, v103 offset0:97 offset1:99
	ds_write2_b32 v139, v94, v95 offset0:96 offset1:98
	ds_write2_b32 v142, v104, v105 offset1:36
	s_and_saveexec_b64 s[68:69], s[12:13]
	ds_write_b128 v158, v[88:91] offset:0
	ds_write_b128 v158, v[92:95] offset:128
	s_mov_b64 exec, s[68:69]
	ds_read_b128 v[106:109], v2 offset:0
	ds_read_b128 v[122:125], v2 offset:16384
	ds_read_b128 v[110:113], v3 offset:0
	ds_read_b128 v[126:129], v3 offset:16384
	ds_read_b128 v[114:117], v4 offset:0
	ds_read_b128 v[130:133], v4 offset:16384
	ds_read_b128 v[118:121], v10 offset:0
	ds_read_b128 v[134:137], v10 offset:16384
	s_waitcnt lgkmcnt(0)
	v_pk_add_f32 v[106:107], v[106:107], v[108:109]
	v_pk_add_f32 v[110:111], v[110:111], v[112:113]
	v_pk_add_f32 v[114:115], v[114:115], v[116:117]
	v_pk_add_f32 v[118:119], v[118:119], v[120:121]
	v_pk_add_f32 v[106:107], v[106:107], v[110:111]
	v_pk_add_f32 v[114:115], v[114:115], v[118:119]
	v_pk_add_f32 v[106:107], v[106:107], v[114:115]
	v_add_f32_e32 v64, v106, v107
	v_pk_add_f32 v[122:123], v[122:123], v[124:125]
	v_pk_add_f32 v[126:127], v[126:127], v[128:129]
	v_pk_add_f32 v[130:131], v[130:131], v[132:133]
	v_pk_add_f32 v[134:135], v[134:135], v[136:137]
	v_pk_add_f32 v[122:123], v[122:123], v[126:127]
	v_pk_add_f32 v[130:131], v[130:131], v[134:135]
	v_pk_add_f32 v[122:123], v[122:123], v[130:131]
	v_add_f32_e32 v65, v122, v123
	global_store_dword v7, v64, s[48:49]
	global_store_dword v165, v65, s[48:49]
	v_add_u32_e32 v7, s64, v7
	v_add_u32_e32 v165, s64, v165
	s_add_i32 s6, s6, 1
	v_add_u32_e32 v146, 1, v146
	s_waitcnt lgkmcnt(0)
	ds_write_b32 v145, v146
	s_waitcnt vmcnt(0)
	v_lshlrev_b32_e32 v64, 16, v54
	v_and_b32_e32 v65, 0xffff0000, v54
	v_mul_f32_e32 v64, 0x3fb8aa3b, v64
	v_mul_f32_e32 v65, 0x3fb8aa3b, v65
	v_lshlrev_b32_e32 v66, 16, v55
	v_and_b32_e32 v67, 0xffff0000, v55
	v_mul_f32_e32 v66, 0x3fb8aa3b, v66
	v_mul_f32_e32 v67, 0x3fb8aa3b, v67
	v_lshlrev_b32_e32 v68, 16, v56
	v_and_b32_e32 v69, 0xffff0000, v56
	v_mul_f32_e32 v68, 0x3fb8aa3b, v68
	v_mul_f32_e32 v69, 0x3fb8aa3b, v69
	v_lshlrev_b32_e32 v70, 16, v57
	v_and_b32_e32 v71, 0xffff0000, v57
	v_mul_f32_e32 v70, 0x3fb8aa3b, v70
	v_mul_f32_e32 v71, 0x3fb8aa3b, v71
	ds_write_b128 v153, v[64:67]
	ds_write_b128 v153, v[68:71] offset:128
	s_waitcnt lgkmcnt(0)
	ds_read_b32 v124, v154 offset:0
	ds_read_b32 v125, v154 offset:256
	ds_read_b32 v126, v154 offset:512
	ds_read_b32 v127, v154 offset:768
	ds_read_b32 v128, v154 offset:1024
	ds_read_b32 v129, v154 offset:1280
	ds_read_b32 v130, v154 offset:1536
	ds_read_b32 v131, v154 offset:1792
	v_lshlrev_b32_e32 v108, 16, v50
	v_and_b32_e32 v109, 0xffff0000, v50
	v_lshlrev_b32_e32 v110, 16, v58
	v_and_b32_e32 v111, 0xffff0000, v58
	v_lshlrev_b32_e32 v96, 16, v46
	v_and_b32_e32 v97, 0xffff0000, v46
	v_pk_add_f32 v[112:113], v[110:111], -1.0 op_sel_hi:[1,0]
	v_pk_mul_f32 v[114:115], v[12:13], v[108:109]
	v_pk_fma_f32 v[112:113], v[20:21], v[112:113], 1.0 op_sel_hi:[1,1,0]
	v_pk_mul_f32 v[88:89], v[62:63], v[114:115] op_sel_hi:[0,1]
	v_pk_mul_f32 v[72:73], v[112:113], v[108:109]
	v_pk_mul_f32 v[80:81], v[88:89], v[110:111]
	v_lshlrev_b32_e32 v108, 16, v51
	v_and_b32_e32 v109, 0xffff0000, v51
	v_lshlrev_b32_e32 v110, 16, v59
	v_and_b32_e32 v111, 0xffff0000, v59
	v_lshlrev_b32_e32 v98, 16, v47
	v_and_b32_e32 v99, 0xffff0000, v47
	v_pk_add_f32 v[112:113], v[110:111], -1.0 op_sel_hi:[1,0]
	v_pk_mul_f32 v[114:115], v[14:15], v[108:109]
	v_pk_fma_f32 v[112:113], v[22:23], v[112:113], 1.0 op_sel_hi:[1,1,0]
	v_pk_mul_f32 v[90:91], v[62:63], v[114:115] op_sel_hi:[0,1]
	v_pk_mul_f32 v[74:75], v[112:113], v[108:109]
	v_pk_mul_f32 v[82:83], v[90:91], v[110:111]
	v_lshlrev_b32_e32 v108, 16, v52
	v_and_b32_e32 v109, 0xffff0000, v52
	v_lshlrev_b32_e32 v110, 16, v60
	v_and_b32_e32 v111, 0xffff0000, v60
	v_lshlrev_b32_e32 v100, 16, v48
	v_and_b32_e32 v101, 0xffff0000, v48
	v_pk_add_f32 v[112:113], v[110:111], -1.0 op_sel_hi:[1,0]
	v_pk_mul_f32 v[114:115], v[16:17], v[108:109]
	v_pk_fma_f32 v[112:113], v[24:25], v[112:113], 1.0 op_sel_hi:[1,1,0]
	v_pk_mul_f32 v[92:93], v[62:63], v[114:115] op_sel_hi:[0,1]
	v_pk_mul_f32 v[76:77], v[112:113], v[108:109]
	v_pk_mul_f32 v[84:85], v[92:93], v[110:111]
	v_lshlrev_b32_e32 v108, 16, v53
	v_and_b32_e32 v109, 0xffff0000, v53
	v_lshlrev_b32_e32 v110, 16, v61
	v_and_b32_e32 v111, 0xffff0000, v61
	v_lshlrev_b32_e32 v102, 16, v49
	v_and_b32_e32 v103, 0xffff0000, v49
	v_pk_add_f32 v[112:113], v[110:111], -1.0 op_sel_hi:[1,0]
	v_pk_mul_f32 v[114:115], v[18:19], v[108:109]
	v_pk_fma_f32 v[112:113], v[26:27], v[112:113], 1.0 op_sel_hi:[1,1,0]
	v_pk_mul_f32 v[94:95], v[62:63], v[114:115] op_sel_hi:[0,1]
	v_pk_mul_f32 v[78:79], v[112:113], v[108:109]
	v_pk_mul_f32 v[86:87], v[94:95], v[110:111]
	v_lshlrev_b32_e32 v104, 16, v63
	v_and_b32_e32 v105, 0xffff0000, v63
	s_waitcnt lgkmcnt(0)
	v_add_f32_e32 v125, v124, v125
	v_add_f32_e32 v126, v125, v126
	v_add_f32_e32 v127, v126, v127
	v_add_f32_e32 v128, v127, v128
	v_add_f32_e32 v129, v128, v129
	v_add_f32_e32 v130, v129, v130
	v_add_f32_e32 v131, v130, v131
	v_exp_f32_e64 v124, -v124
	v_exp_f32_e64 v125, -v125
	v_exp_f32_e64 v126, -v126
	v_exp_f32_e64 v127, -v127
	v_exp_f32_e64 v128, -v128
	v_exp_f32_e64 v129, -v129
	v_exp_f32_e64 v130, -v130
	v_exp_f32_e64 v131, -v131
	s_nop 0
	ds_write_b32 v155, v124 offset:256
	ds_write_b32 v155, v125 offset:512
	ds_write_b32 v155, v126 offset:768
	ds_write_b32 v155, v127 offset:1024
	ds_write_b32 v155, v128 offset:1280
	ds_write_b32 v155, v129 offset:1536
	ds_write_b32 v155, v130 offset:1792
	ds_write_b32 v155, v131 offset:2048
	v_mov_b32_e32 v161, v131
	s_waitcnt lgkmcnt(0)
	ds_read_b128 v[64:67], v153 offset:2048
	ds_read_b128 v[68:71], v153 offset:2176
	ds_read_b128 v[116:119], v153 offset:2304
	ds_read_b128 v[120:123], v153 offset:2432
	s_waitcnt lgkmcnt(0)
	v_rcp_f32_e32 v124, v116
	v_rcp_f32_e32 v125, v117
	v_rcp_f32_e32 v126, v118
	v_rcp_f32_e32 v127, v119
	v_rcp_f32_e32 v128, v120
	v_rcp_f32_e32 v129, v121
	v_rcp_f32_e32 v130, v122
	v_rcp_f32_e32 v131, v123
	s_nop 1
	v_pk_mul_f32 v[72:73], v[72:73], v[124:125]
	v_pk_mul_f32 v[80:81], v[80:81], v[124:125]
	v_pk_mul_f32 v[88:89], v[88:89], v[64:65]
	v_pk_mul_f32 v[96:97], v[96:97], v[116:117]
	v_pk_mul_f32 v[74:75], v[74:75], v[126:127]
	v_pk_mul_f32 v[82:83], v[82:83], v[126:127]
	v_pk_mul_f32 v[90:91], v[90:91], v[66:67]
	v_pk_mul_f32 v[98:99], v[98:99], v[118:119]
	v_pk_mul_f32 v[76:77], v[76:77], v[128:129]
	v_pk_mul_f32 v[84:85], v[84:85], v[128:129]
	v_pk_mul_f32 v[92:93], v[92:93], v[68:69]
	v_pk_mul_f32 v[100:101], v[100:101], v[120:121]
	v_pk_mul_f32 v[78:79], v[78:79], v[130:131]
	v_pk_mul_f32 v[86:87], v[86:87], v[130:131]
	v_pk_mul_f32 v[94:95], v[94:95], v[70:71]
	v_pk_mul_f32 v[102:103], v[102:103], v[122:123]
	s_sub_u32 s65, s6, 1
	ds_read_b128 v[148:151], v144
	s_waitcnt lgkmcnt(0)
	v_min_u32_e32 v148, v148, v149
	v_min3_u32 v148, v148, v150, v151
	s_nop 1
	v_readfirstlane_b32 s68, v148
	s_cmp_ge_u32 s68, s65
	s_cbranch_scc1 .Lsc_G_goz1
	s_mov_b32 s69, 0x100000

.Lsc_G_goz1:
	ds_write_b32 v159, v161 offset:34816
	ds_write_b128 v8, v[72:75] offset:34816
	ds_write_b128 v8, v[76:79] offset:34944
	ds_write_b128 v8, v[80:83] offset:35072
	ds_write_b128 v8, v[84:87] offset:35200
	ds_write2_b32 v140, v96, v97 offset0:1 offset1:3
	ds_write2_b32 v141, v88, v89 offset0:0 offset1:2
	ds_write2_b32 v140, v98, v99 offset0:65 offset1:67
	ds_write2_b32 v141, v90, v91 offset0:64 offset1:66
	ds_write2_b32 v140, v100, v101 offset0:33 offset1:35
	ds_write2_b32 v141, v92, v93 offset0:32 offset1:34
	ds_write2_b32 v140, v102, v103 offset0:97 offset1:99
	ds_write2_b32 v141, v94, v95 offset0:96 offset1:98
	ds_write2_b32 v143, v104, v105 offset1:36
	s_and_saveexec_b64 s[68:69], s[12:13]
	ds_write_b128 v158, v[88:91] offset:34816
	ds_write_b128 v158, v[92:95] offset:34944
	s_mov_b64 exec, s[68:69]
	ds_read_b128 v[106:109], v2 offset:32768
	ds_read_b128 v[122:125], v2 offset:49152
	ds_read_b128 v[110:113], v3 offset:32768
	ds_read_b128 v[126:129], v3 offset:49152
	ds_read_b128 v[114:117], v4 offset:32768
	ds_read_b128 v[130:133], v4 offset:49152
	ds_read_b128 v[118:121], v10 offset:32768
	ds_read_b128 v[134:137], v10 offset:49152
	s_waitcnt lgkmcnt(0)
	v_pk_add_f32 v[106:107], v[106:107], v[108:109]
	v_pk_add_f32 v[110:111], v[110:111], v[112:113]
	v_pk_add_f32 v[114:115], v[114:115], v[116:117]
	v_pk_add_f32 v[118:119], v[118:119], v[120:121]
	v_pk_add_f32 v[106:107], v[106:107], v[110:111]
	v_pk_add_f32 v[114:115], v[114:115], v[118:119]
	v_pk_add_f32 v[106:107], v[106:107], v[114:115]
	v_add_f32_e32 v64, v106, v107
	v_pk_add_f32 v[122:123], v[122:123], v[124:125]
	v_pk_add_f32 v[126:127], v[126:127], v[128:129]
	v_pk_add_f32 v[130:131], v[130:131], v[132:133]
	v_pk_add_f32 v[134:135], v[134:135], v[136:137]
	v_pk_add_f32 v[122:123], v[122:123], v[126:127]
	v_pk_add_f32 v[130:131], v[130:131], v[134:135]
	v_pk_add_f32 v[122:123], v[122:123], v[130:131]
	v_add_f32_e32 v65, v122, v123
	global_store_dword v7, v64, s[48:49]
	global_store_dword v165, v65, s[48:49]
	v_add_u32_e32 v7, s64, v7
	v_add_u32_e32 v165, s64, v165
	s_add_i32 s6, s6, 1
	v_add_u32_e32 v146, 1, v146
	s_waitcnt lgkmcnt(0)
	ds_write_b32 v145, v146
	s_sub_u32 s65, s6, 1
	ds_read_b128 v[148:151], v144
	s_waitcnt lgkmcnt(0)
	v_min_u32_e32 v148, v148, v149
	v_min3_u32 v148, v148, v150, v151
	s_nop 1
	v_readfirstlane_b32 s68, v148
	s_cmp_ge_u32 s68, s65
	s_cbranch_scc1 .Lsc_G_goz2
	s_mov_b32 s69, 0x100000

.Lsc_G_goz2:
	ds_read_b128 v[106:109], v2 offset:0
	ds_read_b128 v[122:125], v2 offset:16384
	ds_read_b128 v[110:113], v3 offset:0
	ds_read_b128 v[126:129], v3 offset:16384
	ds_read_b128 v[114:117], v4 offset:0
	ds_read_b128 v[130:133], v4 offset:16384
	ds_read_b128 v[118:121], v10 offset:0
	ds_read_b128 v[134:137], v10 offset:16384
	s_waitcnt lgkmcnt(0)
	v_pk_add_f32 v[106:107], v[106:107], v[108:109]
	v_pk_add_f32 v[110:111], v[110:111], v[112:113]
	v_pk_add_f32 v[114:115], v[114:115], v[116:117]
	v_pk_add_f32 v[118:119], v[118:119], v[120:121]
	v_pk_add_f32 v[106:107], v[106:107], v[110:111]
	v_pk_add_f32 v[114:115], v[114:115], v[118:119]
	v_pk_add_f32 v[106:107], v[106:107], v[114:115]
	v_add_f32_e32 v64, v106, v107
	v_pk_add_f32 v[122:123], v[122:123], v[124:125]
	v_pk_add_f32 v[126:127], v[126:127], v[128:129]
	v_pk_add_f32 v[130:131], v[130:131], v[132:133]
	v_pk_add_f32 v[134:135], v[134:135], v[136:137]
	v_pk_add_f32 v[122:123], v[122:123], v[126:127]
	v_pk_add_f32 v[130:131], v[130:131], v[134:135]
	v_pk_add_f32 v[122:123], v[122:123], v[130:131]
	v_add_f32_e32 v65, v122, v123
	global_store_dword v7, v64, s[48:49]
	global_store_dword v165, v65, s[48:49]
	v_add_u32_e32 v7, s64, v7
	v_add_u32_e32 v165, s64, v165
	s_add_i32 s6, s6, 1
	v_add_u32_e32 v146, 1, v146
	s_waitcnt lgkmcnt(0)
	ds_write_b32 v145, v146
	s_sub_u32 s65, s6, 1
	ds_read_b128 v[148:151], v144
	s_waitcnt lgkmcnt(0)
	v_min_u32_e32 v148, v148, v149
	v_min3_u32 v148, v148, v150, v151
	s_nop 1
	v_readfirstlane_b32 s68, v148
	s_cmp_ge_u32 s68, s65
	s_cbranch_scc1 .Lsc_G_goz3
	s_mov_b32 s69, 0x100000

.Lsc_G_goz3:
	ds_read_b128 v[106:109], v2 offset:32768
	ds_read_b128 v[122:125], v2 offset:49152
	ds_read_b128 v[110:113], v3 offset:32768
	ds_read_b128 v[126:129], v3 offset:49152
	ds_read_b128 v[114:117], v4 offset:32768
	ds_read_b128 v[130:133], v4 offset:49152
	ds_read_b128 v[118:121], v10 offset:32768
	ds_read_b128 v[134:137], v10 offset:49152
	s_waitcnt lgkmcnt(0)
	v_pk_add_f32 v[106:107], v[106:107], v[108:109]
	v_pk_add_f32 v[110:111], v[110:111], v[112:113]
	v_pk_add_f32 v[114:115], v[114:115], v[116:117]
	v_pk_add_f32 v[118:119], v[118:119], v[120:121]
	v_pk_add_f32 v[106:107], v[106:107], v[110:111]
	v_pk_add_f32 v[114:115], v[114:115], v[118:119]
	v_pk_add_f32 v[106:107], v[106:107], v[114:115]
	v_add_f32_e32 v64, v106, v107
	v_pk_add_f32 v[122:123], v[122:123], v[124:125]
	v_pk_add_f32 v[126:127], v[126:127], v[128:129]
	v_pk_add_f32 v[130:131], v[130:131], v[132:133]
	v_pk_add_f32 v[134:135], v[134:135], v[136:137]
	v_pk_add_f32 v[122:123], v[122:123], v[126:127]
	v_pk_add_f32 v[130:131], v[130:131], v[134:135]
	v_pk_add_f32 v[122:123], v[122:123], v[130:131]
	v_add_f32_e32 v65, v122, v123
	global_store_dword v7, v64, s[48:49]
	global_store_dword v165, v65, s[48:49]
	v_add_u32_e32 v7, s64, v7
	v_add_u32_e32 v165, s64, v165
	s_add_i32 s6, s6, 1
	v_add_u32_e32 v146, 1, v146
	s_waitcnt lgkmcnt(0)
	ds_write_b32 v145, v146

	.amdhsa_kernel _Z10hybrid_fwd6Params
		.amdhsa_group_segment_fixed_size 16384
		.amdhsa_private_segment_fixed_size 0
		.amdhsa_kernarg_size 472
		.amdhsa_user_sgpr_count 2
		.amdhsa_user_sgpr_dispatch_ptr 0
		.amdhsa_user_sgpr_queue_ptr 0
		.amdhsa_user_sgpr_kernarg_segment_ptr 1
		.amdhsa_user_sgpr_dispatch_id 0
		.amdhsa_user_sgpr_kernarg_preload_length 0
		.amdhsa_user_sgpr_kernarg_preload_offset 0
		.amdhsa_user_sgpr_private_segment_size 0
		.amdhsa_uses_dynamic_stack 0
		.amdhsa_enable_private_segment 0
		.amdhsa_system_sgpr_workgroup_id_x 1
		.amdhsa_system_sgpr_workgroup_id_y 0
		.amdhsa_system_sgpr_workgroup_id_z 0
		.amdhsa_system_sgpr_workgroup_info 0
		.amdhsa_system_vgpr_workitem_id 2
		.amdhsa_next_free_vgpr 243
		.amdhsa_next_free_sgpr 100
		.amdhsa_accum_offset 244
		.amdhsa_reserve_vcc 1
		.amdhsa_float_round_mode_32 0
		.amdhsa_float_round_mode_16_64 0
		.amdhsa_float_denorm_mode_32 3
		.amdhsa_float_denorm_mode_16_64 3
		.amdhsa_dx10_clamp 1
		.amdhsa_ieee_mode 1
		.amdhsa_fp16_overflow 0
		.amdhsa_tg_split 0
		.amdhsa_exception_fp_ieee_invalid_op 0
		.amdhsa_exception_fp_denorm_src 0
		.amdhsa_exception_fp_ieee_div_zero 0
		.amdhsa_exception_fp_ieee_overflow 0
		.amdhsa_exception_fp_ieee_underflow 0
		.amdhsa_exception_fp_ieee_inexact 0
		.amdhsa_exception_int_div_zero 0
	.end_amdhsa_kernel

amdhsa.kernels:
  - .agpr_count:     0
    .args:
      - .offset:         0
        .size:           216
        .value_kind:     by_value
      - .offset:         216
        .size:           4
        .value_kind:     hidden_block_count_x
      - .offset:         220
        .size:           4
        .value_kind:     hidden_block_count_y
      - .offset:         224
        .size:           4
        .value_kind:     hidden_block_count_z
      - .offset:         228
        .size:           2
        .value_kind:     hidden_group_size_x
      - .offset:         230
        .size:           2
        .value_kind:     hidden_group_size_y
      - .offset:         232
        .size:           2
        .value_kind:     hidden_group_size_z
      - .offset:         234
        .size:           2
        .value_kind:     hidden_remainder_x
      - .offset:         236
        .size:           2
        .value_kind:     hidden_remainder_y
      - .offset:         238
        .size:           2
        .value_kind:     hidden_remainder_z
      - .offset:         256
        .size:           8
        .value_kind:     hidden_global_offset_x
      - .offset:         264
        .size:           8
        .value_kind:     hidden_global_offset_y
      - .offset:         272
        .size:           8
        .value_kind:     hidden_global_offset_z
      - .offset:         280
        .size:           2
        .value_kind:     hidden_grid_dims
      - .offset:         304
        .size:           8
        .value_kind:     hidden_multigrid_sync_arg
      - .offset:         336
        .size:           4
        .value_kind:     hidden_dynamic_lds_size
    .group_segment_fixed_size: 16384
    .kernarg_segment_align: 8
    .kernarg_segment_size: 472
    .language:       OpenCL C
    .language_version:
      - 2
      - 0
    .max_flat_workgroup_size: 512
    .name:           _Z10hybrid_fwd6Params
    .private_segment_fixed_size: 0
    .sgpr_count:     106
    .sgpr_spill_count: 151
    .symbol:         _Z10hybrid_fwd6Params.kd
    .uniform_work_group_size: 1
    .uses_dynamic_stack: false
    .vgpr_count:     243
    .vgpr_spill_count: 0
    .wavefront_size: 64
